# attention tile loops: one static priority raise for waves 4-7, per-segment s_setprio flips removed
# baseline (speedup 1.0000x reference)
.LBB0_1211:
	v_readfirstlane_b32 s98, v176
	s_bitcmp1_b32 s98, 8
	s_cbranch_scc0 .Lsp0
	s_setprio 1
.Lsp0:
	s_bitcmp1_b32 s10, 0
	s_cselect_b32 s11, 0xb800, 0
	s_nop 0
	v_or_b32_e32 v80, s11, v94
	v_add_u32_e32 v109, v80, v187
	ds_read_b128 v[220:223], v109
	ds_read_b128 v[224:227], v109 offset:64
	ds_read_b128 v[228:231], v109 offset:3328
	ds_read_b128 v[232:235], v109 offset:6656
	ds_read_b128 v[236:239], v109 offset:9984
	ds_read_b128 v[240:243], v109 offset:3392
	ds_read_b128 v[244:247], v109 offset:6720
	ds_read_b128 v[248:251], v109 offset:10048
	s_waitcnt lgkmcnt(7)
	v_mfma_f32_16x16x32_bf16 v[112:115], v[220:223], v[4:7], v[0:3]
	v_mfma_f32_16x16x32_bf16 v[82:85], v[220:223], v[16:19], v[0:3]
	ds_read_b128 v[220:223], v109 offset:128
	s_waitcnt lgkmcnt(7)
	v_mfma_f32_16x16x32_bf16 v[112:115], v[224:227], v[8:11], v[112:115]
	v_mfma_f32_16x16x32_bf16 v[82:85], v[224:227], v[20:23], v[82:85]
	ds_read_b128 v[224:227], v109 offset:3456
	s_waitcnt lgkmcnt(7)
	v_mfma_f32_16x16x32_bf16 v[120:123], v[228:231], v[4:7], v[0:3]
	v_mfma_f32_16x16x32_bf16 v[116:119], v[228:231], v[16:19], v[0:3]
	ds_read_b128 v[228:231], v109 offset:6784
	s_waitcnt lgkmcnt(5)
	v_mfma_f32_16x16x32_bf16 v[120:123], v[240:243], v[8:11], v[120:123]
	v_mfma_f32_16x16x32_bf16 v[116:119], v[240:243], v[20:23], v[116:119]
	ds_read_b128 v[240:243], v109 offset:10112
	v_mfma_f32_16x16x32_bf16 v[128:131], v[232:235], v[4:7], v[0:3]
	v_mfma_f32_16x16x32_bf16 v[124:127], v[232:235], v[16:19], v[0:3]
	s_waitcnt lgkmcnt(5)
	v_mfma_f32_16x16x32_bf16 v[128:131], v[244:247], v[8:11], v[128:131]
	v_mfma_f32_16x16x32_bf16 v[124:127], v[244:247], v[20:23], v[124:127]
	v_mfma_f32_16x16x32_bf16 v[136:139], v[236:239], v[4:7], v[0:3]
	v_mfma_f32_16x16x32_bf16 v[132:135], v[236:239], v[16:19], v[0:3]
	s_waitcnt lgkmcnt(4)
	v_mfma_f32_16x16x32_bf16 v[136:139], v[248:251], v[8:11], v[136:139]
	v_mfma_f32_16x16x32_bf16 v[132:135], v[248:251], v[20:23], v[132:135]
	s_waitcnt lgkmcnt(3)
	v_mfma_f32_16x16x32_bf16 v[148:151], v[220:223], v[24:27], v[82:85]
	s_waitcnt lgkmcnt(2)
	v_mfma_f32_16x16x32_bf16 v[120:123], v[224:227], v[12:15], v[120:123]
	v_mfma_f32_16x16x32_bf16 v[84:87], v[224:227], v[24:27], v[116:119]
	s_waitcnt lgkmcnt(1)
	v_mfma_f32_16x16x32_bf16 v[152:155], v[228:231], v[12:15], v[128:131]
	v_mfma_f32_16x16x32_bf16 v[156:159], v[228:231], v[24:27], v[124:127]
	v_mfma_f32_16x16x32_bf16 v[112:115], v[220:223], v[12:15], v[112:115]
	s_waitcnt lgkmcnt(0)
	v_mfma_f32_16x16x32_bf16 v[160:163], v[240:243], v[12:15], v[136:139]
	v_mfma_f32_16x16x32_bf16 v[164:167], v[240:243], v[24:27], v[132:135]
	s_nop 2
	s_nop 0
	s_nop 3
	v_max3_f32 v80, v112, v113, v114
	v_max3_f32 v80, v80, v115, v120
	v_max3_f32 v80, v80, v121, v122
	v_max3_f32 v80, v80, v123, v152
	v_max3_f32 v80, v80, v153, v154
	v_max3_f32 v80, v80, v155, v160
	v_max3_f32 v80, v80, v161, v162
	v_max_f32_e32 v80, v80, v163
	v_mul_f32_e32 v80, 0x3e16c740, v80
	v_max_f32_e32 v80, s71, v80
	v_mov_b32_e32 v82, v80
	s_nop 1
	v_permlane16_swap_b32_e32 v80, v82
	v_max_f32_e32 v80, v80, v82
	v_mov_b32_e32 v82, v80
	s_nop 1
	v_permlane32_swap_b32_e32 v80, v82
	v_max3_f32 v144, v81, v80, v82
	v_sub_f32_e32 v80, v81, v144
	v_fma_f32 v81, v112, s70, -v144
	v_exp_f32_e32 v143, v81
	v_fma_f32 v81, v113, s70, -v144
	v_exp_f32_e32 v141, v81
	v_fma_f32 v81, v114, s70, -v144
	v_max3_f32 v112, v148, v149, v150
	v_max3_f32 v112, v112, v151, v84
	v_max3_f32 v112, v112, v85, v86
	v_max3_f32 v112, v112, v87, v156
	v_max3_f32 v112, v112, v157, v158
	v_max3_f32 v112, v112, v159, v164
	v_max3_f32 v112, v112, v165, v166
	v_max_f32_e32 v112, v112, v167
	v_mul_f32_e32 v112, 0x3e16c740, v112
	v_max_f32_e32 v112, s71, v112
	v_mov_b32_e32 v114, v112
	s_nop 1
	v_permlane16_swap_b32_e32 v112, v114
	v_max_f32_e32 v112, v112, v114
	v_mov_b32_e32 v114, v112
	v_exp_f32_e32 v139, v81
	v_fma_f32 v81, v115, s70, -v144
	v_permlane32_swap_b32_e32 v112, v114
	v_exp_f32_e32 v137, v81
	v_fma_f32 v81, v120, s70, -v144
	v_max3_f32 v146, v190, v112, v114
	v_exp_f32_e32 v135, v81
	v_fma_f32 v81, v121, s70, -v144
	v_fma_f32 v84, v84, s70, -v146
	v_exp_f32_e32 v133, v81
	v_fma_f32 v81, v122, s70, -v144
	v_exp_f32_e32 v134, v84
	v_fma_f32 v84, v85, s70, -v146
	v_exp_f32_e32 v131, v81
	v_fma_f32 v81, v123, s70, -v144
	v_exp_f32_e32 v132, v84
	v_fma_f32 v84, v86, s70, -v146
	v_exp_f32_e32 v129, v81
	v_fma_f32 v81, v152, s70, -v144
	v_exp_f32_e32 v130, v84
	v_fma_f32 v84, v87, s70, -v146
	v_exp_f32_e32 v127, v81
	v_fma_f32 v81, v153, s70, -v144
	v_exp_f32_e32 v128, v84
	v_fma_f32 v84, v156, s70, -v146
	v_exp_f32_e32 v125, v81
	v_fma_f32 v81, v154, s70, -v144
	v_exp_f32_e32 v126, v84
	v_fma_f32 v84, v157, s70, -v146
	v_exp_f32_e32 v123, v81
	v_fma_f32 v81, v155, s70, -v144
	v_fma_f32 v112, v148, s70, -v146
	v_exp_f32_e32 v124, v84
	v_fma_f32 v84, v158, s70, -v146
	v_exp_f32_e32 v119, v81
	v_fma_f32 v81, v160, s70, -v144
	v_exp_f32_e32 v142, v112
	v_fma_f32 v112, v149, s70, -v146
	v_exp_f32_e32 v122, v84
	v_fma_f32 v84, v159, s70, -v146
	v_exp_f32_e32 v115, v81
	v_fma_f32 v81, v161, s70, -v144
	v_exp_f32_e32 v140, v112
	v_fma_f32 v112, v150, s70, -v146
	v_exp_f32_e32 v118, v84
	v_fma_f32 v84, v164, s70, -v146
	v_fma_f32 v85, v166, s70, -v146
	v_exp_f32_e32 v113, v81
	v_fma_f32 v81, v162, s70, -v144
	v_exp_f32_e32 v110, v80
	v_fma_f32 v80, v163, s70, -v144
	v_sub_f32_e32 v116, v190, v146
	v_exp_f32_e32 v138, v112
	v_fma_f32 v112, v151, s70, -v146
	v_exp_f32_e32 v114, v84
	v_fma_f32 v84, v165, s70, -v146
	v_exp_f32_e32 v120, v85
	v_fma_f32 v85, v167, s70, -v146
	v_exp_f32_e32 v121, v81
	v_exp_f32_e32 v117, v80
	v_exp_f32_e32 v136, v112
	v_exp_f32_e32 v112, v84
	v_exp_f32_e32 v84, v116
	v_exp_f32_e32 v116, v85
	v_pk_mul_f32 v[70:71], v[70:71], v[110:111] op_sel_hi:[1,0]
	v_pk_mul_f32 v[68:69], v[68:69], v[110:111] op_sel_hi:[1,0]
	v_pk_mul_f32 v[66:67], v[66:67], v[110:111] op_sel_hi:[1,0]
	v_pk_mul_f32 v[64:65], v[64:65], v[110:111] op_sel_hi:[1,0]
	v_pk_mul_f32 v[74:75], v[74:75], v[110:111] op_sel_hi:[1,0]
	v_pk_mul_f32 v[72:73], v[72:73], v[110:111] op_sel_hi:[1,0]
	v_pk_mul_f32 v[82:83], v[78:79], v[110:111] op_sel_hi:[1,0]
	v_pk_mul_f32 v[80:81], v[76:77], v[110:111] op_sel_hi:[1,0]
	v_cvt_pk_bf16_f32 v152, v143, v141
	v_cvt_pk_bf16_f32 v153, v139, v137
	v_cvt_pk_bf16_f32 v154, v135, v133
	v_cvt_pk_bf16_f32 v155, v131, v129
	v_cvt_pk_bf16_f32 v76, v127, v125
	v_cvt_pk_bf16_f32 v77, v123, v119
	v_cvt_pk_bf16_f32 v78, v115, v113
	v_cvt_pk_bf16_f32 v79, v121, v117
	v_pk_mul_f32 v[54:55], v[54:55], v[84:85] op_sel_hi:[1,0]
	v_pk_mul_f32 v[52:53], v[52:53], v[84:85] op_sel_hi:[1,0]
	v_pk_mul_f32 v[50:51], v[50:51], v[84:85] op_sel_hi:[1,0]
	v_pk_mul_f32 v[48:49], v[48:49], v[84:85] op_sel_hi:[1,0]
	v_pk_mul_f32 v[58:59], v[58:59], v[84:85] op_sel_hi:[1,0]
	v_pk_mul_f32 v[56:57], v[56:57], v[84:85] op_sel_hi:[1,0]
	v_pk_mul_f32 v[62:63], v[62:63], v[84:85] op_sel_hi:[1,0]
	v_pk_mul_f32 v[60:61], v[60:61], v[84:85] op_sel_hi:[1,0]
	v_cvt_pk_bf16_f32 v148, v142, v140
	v_cvt_pk_bf16_f32 v149, v138, v136
	v_cvt_pk_bf16_f32 v150, v134, v132
	v_cvt_pk_bf16_f32 v151, v130, v128
	v_cvt_pk_bf16_f32 v156, v126, v124
	v_cvt_pk_bf16_f32 v157, v122, v118
	v_cvt_pk_bf16_f32 v158, v114, v112
	v_cvt_pk_bf16_f32 v159, v120, v116
	s_nop 0
	v_add3_u32 v85, s11, v188, v189
	ds_read_b64_tr_b16 v[222:223], v85 offset:29184
	ds_read_b64_tr_b16 v[220:221], v85 offset:26624
	ds_read_b64_tr_b16 v[224:225], v85 offset:26656
	ds_read_b64_tr_b16 v[226:227], v85 offset:29216
	ds_read_b64_tr_b16 v[228:229], v85 offset:31744
	ds_read_b64_tr_b16 v[230:231], v85 offset:34304
	ds_read_b64_tr_b16 v[232:233], v85 offset:31776
	ds_read_b64_tr_b16 v[234:235], v85 offset:34336
	ds_read_b64_tr_b16 v[236:237], v85 offset:26688
	ds_read_b64_tr_b16 v[238:239], v85 offset:29248
	ds_read_b64_tr_b16 v[240:241], v85 offset:31808
	ds_read_b64_tr_b16 v[242:243], v85 offset:34368
	ds_read_b64_tr_b16 v[244:245], v85 offset:26720
	ds_read_b64_tr_b16 v[246:247], v85 offset:29280
	ds_read_b64_tr_b16 v[248:249], v85 offset:31840
	ds_read_b64_tr_b16 v[250:251], v85 offset:34400
	s_waitcnt lgkmcnt(14)
	v_mfma_f32_16x16x32_bf16 v[68:71], v[220:223], v[152:155], v[68:71]
	v_mfma_f32_16x16x32_bf16 v[52:55], v[220:223], v[148:151], v[52:55]
	s_waitcnt lgkmcnt(10)
	v_mfma_f32_16x16x32_bf16 v[68:71], v[228:231], v[76:79], v[68:71]
	v_mfma_f32_16x16x32_bf16 v[52:55], v[228:231], v[156:159], v[52:55]
	v_mfma_f32_16x16x32_bf16 v[64:67], v[224:227], v[152:155], v[64:67]
	v_mfma_f32_16x16x32_bf16 v[48:51], v[224:227], v[148:151], v[48:51]
	s_waitcnt lgkmcnt(8)
	v_mfma_f32_16x16x32_bf16 v[64:67], v[232:235], v[76:79], v[64:67]
	v_mfma_f32_16x16x32_bf16 v[48:51], v[232:235], v[156:159], v[48:51]
	s_waitcnt lgkmcnt(6)
	v_mfma_f32_16x16x32_bf16 v[72:75], v[236:239], v[152:155], v[72:75]
	v_mfma_f32_16x16x32_bf16 v[56:59], v[236:239], v[148:151], v[56:59]
	s_waitcnt lgkmcnt(4)
	v_mfma_f32_16x16x32_bf16 v[72:75], v[240:243], v[76:79], v[72:75]
	v_mfma_f32_16x16x32_bf16 v[56:59], v[240:243], v[156:159], v[56:59]
	s_waitcnt lgkmcnt(2)
	v_mfma_f32_16x16x32_bf16 v[60:63], v[244:247], v[148:151], v[60:63]
	v_mfma_f32_16x16x32_bf16 v[80:83], v[244:247], v[152:155], v[80:83]
	s_waitcnt lgkmcnt(0)
	v_mfma_f32_16x16x32_bf16 v[76:79], v[248:251], v[76:79], v[80:83]
	v_mfma_f32_16x16x32_bf16 v[60:63], v[248:251], v[156:159], v[60:63]
	s_nop 3
	s_nop 0
	s_nop 0
	ds_read_b128 v[220:223], v109 offset:13312
	ds_read_b128 v[224:227], v109 offset:13376
	ds_read_b128 v[228:231], v109 offset:16640
	ds_read_b128 v[232:235], v109 offset:19968
	ds_read_b128 v[236:239], v109 offset:23296
	ds_read_b128 v[240:243], v109 offset:16704
	ds_read_b128 v[244:247], v109 offset:20032
	ds_read_b128 v[248:251], v109 offset:23360
	s_waitcnt lgkmcnt(7)
	v_mfma_f32_16x16x32_bf16 v[148:151], v[220:223], v[4:7], v[0:3]
	v_mfma_f32_16x16x32_bf16 v[80:83], v[220:223], v[16:19], v[0:3]
	ds_read_b128 v[220:223], v109 offset:13440
	s_waitcnt lgkmcnt(7)
	v_mfma_f32_16x16x32_bf16 v[148:151], v[224:227], v[8:11], v[148:151]
	v_mfma_f32_16x16x32_bf16 v[80:83], v[224:227], v[20:23], v[80:83]
	ds_read_b128 v[224:227], v109 offset:16768
	s_waitcnt lgkmcnt(7)
	v_mfma_f32_16x16x32_bf16 v[156:159], v[228:231], v[4:7], v[0:3]
	v_mfma_f32_16x16x32_bf16 v[152:155], v[228:231], v[16:19], v[0:3]
	ds_read_b128 v[228:231], v109 offset:20096
	s_waitcnt lgkmcnt(5)
	v_mfma_f32_16x16x32_bf16 v[156:159], v[240:243], v[8:11], v[156:159]
	v_mfma_f32_16x16x32_bf16 v[152:155], v[240:243], v[20:23], v[152:155]
	ds_read_b128 v[240:243], v109 offset:23424
	v_mfma_f32_16x16x32_bf16 v[164:167], v[232:235], v[4:7], v[0:3]
	v_mfma_f32_16x16x32_bf16 v[160:163], v[232:235], v[16:19], v[0:3]
	s_waitcnt lgkmcnt(5)
	v_mfma_f32_16x16x32_bf16 v[164:167], v[244:247], v[8:11], v[164:167]
	v_mfma_f32_16x16x32_bf16 v[160:163], v[244:247], v[20:23], v[160:163]
	v_mfma_f32_16x16x32_bf16 v[190:193], v[236:239], v[4:7], v[0:3]
	v_mfma_f32_16x16x32_bf16 v[168:171], v[236:239], v[16:19], v[0:3]
	s_waitcnt lgkmcnt(4)
	v_mfma_f32_16x16x32_bf16 v[190:193], v[248:251], v[8:11], v[190:193]
	v_mfma_f32_16x16x32_bf16 v[168:171], v[248:251], v[20:23], v[168:171]
	s_waitcnt lgkmcnt(3)
	v_mfma_f32_16x16x32_bf16 v[148:151], v[220:223], v[12:15], v[148:151]
	v_mfma_f32_16x16x32_bf16 v[194:197], v[220:223], v[24:27], v[80:83]
	s_waitcnt lgkmcnt(2)
	v_mfma_f32_16x16x32_bf16 v[198:201], v[224:227], v[12:15], v[156:159]
	v_mfma_f32_16x16x32_bf16 v[202:205], v[224:227], v[24:27], v[152:155]
	s_waitcnt lgkmcnt(1)
	v_mfma_f32_16x16x32_bf16 v[206:209], v[228:231], v[12:15], v[164:167]
	v_mfma_f32_16x16x32_bf16 v[210:213], v[228:231], v[24:27], v[160:163]
	s_waitcnt lgkmcnt(0)
	v_mfma_f32_16x16x32_bf16 v[190:193], v[240:243], v[12:15], v[190:193]
	v_mfma_f32_16x16x32_bf16 v[214:217], v[240:243], v[24:27], v[168:171]
	s_nop 1
	s_nop 0
	v_max3_f32 v80, v148, v149, v150
	v_max3_f32 v80, v80, v151, v198
	v_max3_f32 v80, v80, v199, v200
	v_max3_f32 v80, v80, v201, v206
	v_max3_f32 v80, v80, v207, v208
	v_max3_f32 v80, v80, v209, v190
	v_max3_f32 v80, v80, v191, v192
	v_max_f32_e32 v80, v80, v193
	v_mul_f32_e32 v80, 0x3e16c740, v80
	v_max_f32_e32 v80, s71, v80
	v_mov_b32_e32 v81, v80
	s_nop 1
	v_permlane16_swap_b32_e32 v80, v81
	v_max_f32_e32 v80, v80, v81
	v_mov_b32_e32 v81, v80
	s_nop 1
	v_permlane32_swap_b32_e32 v80, v81
	v_max3_f32 v81, v144, v80, v81
	v_fma_f32 v82, v148, s70, -v81
	v_exp_f32_e32 v171, v82
	v_fma_f32 v82, v149, s70, -v81
	v_exp_f32_e32 v169, v82
	v_fma_f32 v82, v150, s70, -v81
	v_exp_f32_e32 v167, v82
	v_fma_f32 v82, v151, s70, -v81
	v_exp_f32_e32 v165, v82
	v_fma_f32 v82, v198, s70, -v81
	v_exp_f32_e32 v163, v82
	v_fma_f32 v82, v199, s70, -v81
	v_exp_f32_e32 v161, v82
	v_fma_f32 v82, v200, s70, -v81
	v_exp_f32_e32 v159, v82
	v_fma_f32 v82, v201, s70, -v81
	v_exp_f32_e32 v157, v82
	v_fma_f32 v82, v206, s70, -v81
	v_exp_f32_e32 v155, v82
	v_fma_f32 v82, v207, s70, -v81
	v_exp_f32_e32 v153, v82
	v_fma_f32 v82, v208, s70, -v81
	v_exp_f32_e32 v151, v82
	v_fma_f32 v82, v209, s70, -v81
	v_exp_f32_e32 v147, v82
	v_fma_f32 v82, v190, s70, -v81
	v_exp_f32_e32 v87, v82
	v_fma_f32 v82, v191, s70, -v81
	v_exp_f32_e32 v83, v82
	v_fma_f32 v82, v192, s70, -v81
	v_exp_f32_e32 v149, v82
	v_fma_f32 v82, v193, s70, -v81
	v_exp_f32_e32 v145, v82
	v_max3_f32 v82, v194, v195, v196
	v_max3_f32 v82, v82, v197, v202
	v_max3_f32 v82, v82, v203, v204
	v_max3_f32 v82, v82, v205, v210
	v_max3_f32 v82, v82, v211, v212
	v_max3_f32 v82, v82, v213, v214
	v_max3_f32 v82, v82, v215, v216
	v_max_f32_e32 v82, v82, v217
	v_mul_f32_e32 v82, 0x3e16c740, v82
	v_max_f32_e32 v82, s71, v82
	v_mov_b32_e32 v86, v82
	s_nop 1
	v_permlane16_swap_b32_e32 v82, v86
	v_max_f32_e32 v82, v82, v86
	v_mov_b32_e32 v86, v82
	s_nop 1
	v_permlane32_swap_b32_e32 v82, v86
	v_max3_f32 v190, v146, v82, v86
	v_fma_f32 v82, v194, s70, -v190
	v_exp_f32_e32 v170, v82
	v_fma_f32 v82, v195, s70, -v190
	v_exp_f32_e32 v168, v82
	v_fma_f32 v82, v196, s70, -v190
	v_exp_f32_e32 v166, v82
	v_fma_f32 v82, v197, s70, -v190
	v_exp_f32_e32 v164, v82
	v_fma_f32 v82, v202, s70, -v190
	v_exp_f32_e32 v162, v82
	v_fma_f32 v82, v203, s70, -v190
	v_exp_f32_e32 v160, v82
	v_fma_f32 v82, v204, s70, -v190
	v_exp_f32_e32 v158, v82
	v_fma_f32 v82, v205, s70, -v190
	v_exp_f32_e32 v156, v82
	v_fma_f32 v82, v210, s70, -v190
	v_exp_f32_e32 v154, v82
	v_fma_f32 v82, v211, s70, -v190
	v_exp_f32_e32 v152, v82
	v_fma_f32 v82, v212, s70, -v190
	v_exp_f32_e32 v150, v82
	v_fma_f32 v82, v213, s70, -v190
	v_sub_f32_e32 v80, v144, v81
	v_sub_f32_e32 v109, v146, v190
	v_exp_f32_e32 v146, v82
	v_fma_f32 v82, v214, s70, -v190
	v_exp_f32_e32 v80, v80
	v_exp_f32_e32 v86, v82
	v_fma_f32 v82, v215, s70, -v190
	v_fma_f32 v144, v216, s70, -v190
	v_exp_f32_e32 v172, v109
	v_fma_f32 v109, v217, s70, -v190
	v_exp_f32_e32 v82, v82
	v_exp_f32_e32 v148, v144
	v_exp_f32_e32 v144, v109
	v_pk_mul_f32 v[70:71], v[70:71], v[80:81] op_sel_hi:[1,0]
	v_pk_mul_f32 v[68:69], v[68:69], v[80:81] op_sel_hi:[1,0]
	v_pk_mul_f32 v[66:67], v[66:67], v[80:81] op_sel_hi:[1,0]
	v_pk_mul_f32 v[64:65], v[64:65], v[80:81] op_sel_hi:[1,0]
	v_pk_mul_f32 v[74:75], v[74:75], v[80:81] op_sel_hi:[1,0]
	v_pk_mul_f32 v[72:73], v[72:73], v[80:81] op_sel_hi:[1,0]
	v_pk_mul_f32 v[200:201], v[78:79], v[80:81] op_sel_hi:[1,0]
	v_pk_mul_f32 v[198:199], v[76:77], v[80:81] op_sel_hi:[1,0]
	v_cvt_pk_bf16_f32 v76, v155, v153
	v_cvt_pk_bf16_f32 v77, v151, v147
	v_cvt_pk_bf16_f32 v78, v87, v83
	v_cvt_pk_bf16_f32 v79, v149, v145
	v_pk_mul_f32 v[54:55], v[54:55], v[172:173] op_sel_hi:[1,0]
	v_pk_mul_f32 v[52:53], v[52:53], v[172:173] op_sel_hi:[1,0]
	v_pk_mul_f32 v[50:51], v[50:51], v[172:173] op_sel_hi:[1,0]
	v_pk_mul_f32 v[48:49], v[48:49], v[172:173] op_sel_hi:[1,0]
	v_pk_mul_f32 v[58:59], v[58:59], v[172:173] op_sel_hi:[1,0]
	v_pk_mul_f32 v[56:57], v[56:57], v[172:173] op_sel_hi:[1,0]
	v_pk_mul_f32 v[62:63], v[62:63], v[172:173] op_sel_hi:[1,0]
	v_pk_mul_f32 v[60:61], v[60:61], v[172:173] op_sel_hi:[1,0]
	v_cvt_pk_bf16_f32 v206, v171, v169
	v_cvt_pk_bf16_f32 v207, v167, v165
	v_cvt_pk_bf16_f32 v208, v163, v161
	v_cvt_pk_bf16_f32 v209, v159, v157
	v_cvt_pk_bf16_f32 v192, v170, v168
	v_cvt_pk_bf16_f32 v193, v166, v164
	v_cvt_pk_bf16_f32 v194, v162, v160
	v_cvt_pk_bf16_f32 v195, v158, v156
	v_cvt_pk_bf16_f32 v202, v154, v152
	v_cvt_pk_bf16_f32 v203, v150, v146
	v_cvt_pk_bf16_f32 v204, v86, v82
	v_cvt_pk_bf16_f32 v205, v148, v144
	s_nop 0
	ds_read_b64_tr_b16 v[222:223], v85 offset:39424
	ds_read_b64_tr_b16 v[220:221], v85 offset:36864
	ds_read_b64_tr_b16 v[224:225], v85 offset:36896
	ds_read_b64_tr_b16 v[226:227], v85 offset:39456
	ds_read_b64_tr_b16 v[228:229], v85 offset:41984
	ds_read_b64_tr_b16 v[230:231], v85 offset:44544
	ds_read_b64_tr_b16 v[232:233], v85 offset:42016
	ds_read_b64_tr_b16 v[234:235], v85 offset:44576
	ds_read_b64_tr_b16 v[236:237], v85 offset:36928
	ds_read_b64_tr_b16 v[238:239], v85 offset:39488
	ds_read_b64_tr_b16 v[240:241], v85 offset:42048
	ds_read_b64_tr_b16 v[242:243], v85 offset:44608
	ds_read_b64_tr_b16 v[244:245], v85 offset:36960
	ds_read_b64_tr_b16 v[246:247], v85 offset:39520
	ds_read_b64_tr_b16 v[248:249], v85 offset:42080
	ds_read_b64_tr_b16 v[250:251], v85 offset:44640
	s_waitcnt lgkmcnt(14)
	v_mfma_f32_16x16x32_bf16 v[68:71], v[220:223], v[206:209], v[68:71]
	v_mfma_f32_16x16x32_bf16 v[52:55], v[220:223], v[192:195], v[52:55]
	s_waitcnt lgkmcnt(10)
	v_mfma_f32_16x16x32_bf16 v[68:71], v[228:231], v[76:79], v[68:71]
	v_mfma_f32_16x16x32_bf16 v[52:55], v[228:231], v[202:205], v[52:55]
	v_mfma_f32_16x16x32_bf16 v[64:67], v[224:227], v[206:209], v[64:67]
	v_mfma_f32_16x16x32_bf16 v[48:51], v[224:227], v[192:195], v[48:51]
	s_waitcnt lgkmcnt(8)
	v_mfma_f32_16x16x32_bf16 v[64:67], v[232:235], v[76:79], v[64:67]
	v_mfma_f32_16x16x32_bf16 v[48:51], v[232:235], v[202:205], v[48:51]
	s_waitcnt lgkmcnt(6)
	v_mfma_f32_16x16x32_bf16 v[72:75], v[236:239], v[206:209], v[72:75]
	v_mfma_f32_16x16x32_bf16 v[56:59], v[236:239], v[192:195], v[56:59]
	s_waitcnt lgkmcnt(4)
	v_mfma_f32_16x16x32_bf16 v[72:75], v[240:243], v[76:79], v[72:75]
	v_mfma_f32_16x16x32_bf16 v[56:59], v[240:243], v[202:205], v[56:59]
	s_waitcnt lgkmcnt(2)
	v_mfma_f32_16x16x32_bf16 v[60:63], v[244:247], v[192:195], v[60:63]
	v_mfma_f32_16x16x32_bf16 v[196:199], v[244:247], v[206:209], v[198:201]
	s_waitcnt lgkmcnt(0)
	v_mfma_f32_16x16x32_bf16 v[76:79], v[248:251], v[76:79], v[196:199]
	v_mfma_f32_16x16x32_bf16 v[60:63], v[248:251], v[202:205], v[60:63]
	s_nop 3
	s_nop 0
	s_add_i32 s22, s10, 1
	s_cmp_ge_u32 s22, s19
	s_cbranch_scc1 .LBB0_1213
	s_bitcmp1_b32 s22, 0
	s_cselect_b32 s11, 0xb800, 0
	v_add3_u32 v85, s11, v95, v96
	s_waitcnt vmcnt(0)
	ds_write_b128 v85, v[28:31]
	v_add3_u32 v85, s11, v99, v96
	ds_write_b128 v85, v[36:39]
	v_add3_u32 v85, s11, v185, v96
	ds_write_b128 v85, v[32:35] offset:26624
	v_add3_u32 v85, s11, v186, v96
	ds_write_b128 v85, v[40:43] offset:26624
	v_add3_u32 v85, s11, v111, v98
	ds_write_b128 v85, v[44:47] offset:128

.LBB0_1216:
	s_setprio 0
	s_mov_b64 s[98:99], exec
	s_mov_b64 exec, s[4:5]
	s_cbranch_execz .Lqp3
	v_readlane_b32 s8, v252, 23
	v_readlane_b32 s9, v252, 24
	s_nop 1
	v_mov_b64_e32 v[254:255], s[8:9]
	global_atomic_add v253, v[254:255], v177, off sc0

.Lsp1:
	s_bitcmp1_b32 s33, 0
	s_cselect_b32 s78, 0x9800, 0
	s_cmp_lt_i32 s33, s92
	s_cselect_b64 s[6:7], -1, 0
	s_and_b64 s[76:77], s[72:73], s[6:7]
	s_cmp_eq_u64 s[76:77], 0
	s_cbranch_scc1 .Lnm0_entry
	s_nop 0
	v_or_b32_e32 v68, s78, v94
	v_add_u32_e32 v88, v68, v163
	ds_read_b128 v[204:207], v88 offset:2304
	ds_read_b128 v[208:211], v88
	ds_read_b128 v[212:215], v88 offset:4608
	ds_read_b128 v[216:219], v88 offset:6912
	ds_read_b128 v[220:223], v88 offset:64
	ds_read_b128 v[224:227], v88 offset:2368
	ds_read_b128 v[228:231], v88 offset:4672
	ds_read_b128 v[232:235], v88 offset:6976
	s_waitcnt lgkmcnt(7)
	v_mfma_f32_16x16x32_bf16 v[82:85], v[204:207], v[4:7], v[0:3]
	v_mfma_f32_16x16x32_bf16 v[108:111], v[204:207], v[12:15], v[0:3]
	s_waitcnt lgkmcnt(5)
	v_mfma_f32_16x16x32_bf16 v[112:115], v[212:215], v[4:7], v[0:3]
	v_mfma_f32_16x16x32_bf16 v[116:119], v[212:215], v[12:15], v[0:3]
	s_waitcnt lgkmcnt(4)
	v_mfma_f32_16x16x32_bf16 v[120:123], v[216:219], v[4:7], v[0:3]
	v_mfma_f32_16x16x32_bf16 v[124:127], v[216:219], v[12:15], v[0:3]
	v_mfma_f32_16x16x32_bf16 v[74:77], v[208:211], v[4:7], v[0:3]
	v_mfma_f32_16x16x32_bf16 v[68:71], v[208:211], v[12:15], v[0:3]
	s_waitcnt lgkmcnt(3)
	v_mfma_f32_16x16x32_bf16 v[128:131], v[220:223], v[8:11], v[74:77]
	v_mfma_f32_16x16x32_bf16 v[76:79], v[220:223], v[16:19], v[68:71]
	s_waitcnt lgkmcnt(2)
	v_mfma_f32_16x16x32_bf16 v[132:135], v[224:227], v[8:11], v[82:85]
	v_mfma_f32_16x16x32_bf16 v[80:83], v[224:227], v[16:19], v[108:111]
	s_waitcnt lgkmcnt(1)
	v_mfma_f32_16x16x32_bf16 v[108:111], v[228:231], v[8:11], v[112:115]
	v_mfma_f32_16x16x32_bf16 v[84:87], v[228:231], v[16:19], v[116:119]
	s_waitcnt lgkmcnt(0)
	v_mfma_f32_16x16x32_bf16 v[112:115], v[232:235], v[8:11], v[120:123]
	v_mfma_f32_16x16x32_bf16 v[142:145], v[232:235], v[16:19], v[124:127]
	s_nop 1
	s_nop 0
	v_add_u32_e32 v69, 0x73, v166
	v_cmp_gt_u32_e32 vcc, s83, v69
	v_add_u32_e32 v70, 0x72, v166
	s_and_b64 s[12:13], s[76:77], vcc
	v_cmp_gt_u32_e32 vcc, s83, v70
	v_add_u32_e32 v72, 0x71, v166
	s_and_b64 s[14:15], s[76:77], vcc
	v_cmp_gt_u32_e32 vcc, s83, v72
	v_add_u32_e32 v74, 0x70, v166
	s_and_b64 s[16:17], s[76:77], vcc
	v_cmp_gt_u32_e32 vcc, s83, v74
	v_add_u32_e32 v75, 0x63, v166
	s_and_b64 s[18:19], s[76:77], vcc
	v_cmp_gt_u32_e32 vcc, s83, v75
	v_add_u32_e32 v106, 0x62, v166
	s_and_b64 s[20:21], s[76:77], vcc
	v_cmp_gt_u32_e32 vcc, s83, v106
	v_add_u32_e32 v116, 0x61, v166
	s_and_b64 s[22:23], s[76:77], vcc
	v_cmp_gt_u32_e32 vcc, s83, v116
	v_add_u32_e32 v117, 0x60, v166
	s_and_b64 s[24:25], s[76:77], vcc
	v_cmp_gt_u32_e32 vcc, s83, v117
	v_add_u32_e32 v117, 0x53, v166
	s_and_b64 s[26:27], s[76:77], vcc
	v_cmp_gt_u32_e32 vcc, s83, v117
	v_add_u32_e32 v117, 0x52, v166
	v_mul_f32_e32 v68, 0x3e38aa3b, v128
	v_mul_f32_e32 v69, 0x3e38aa3b, v129
	s_and_b64 s[28:29], s[76:77], vcc
	v_cmp_gt_u32_e32 vcc, s83, v117
	v_add_u32_e32 v117, 0x51, v166
	v_cndmask_b32_e64 v68, v68, v182, s[12:13]
	v_cndmask_b32_e64 v69, v69, v182, s[14:15]
	v_mul_f32_e32 v71, 0x3e38aa3b, v130
	v_mul_f32_e32 v72, 0x3e38aa3b, v131
	s_and_b64 s[30:31], s[76:77], vcc
	v_cmp_gt_u32_e32 vcc, s83, v117
	v_add_u32_e32 v117, 0x50, v166
	v_max3_f32 v70, v68, s71, v69
	v_cndmask_b32_e64 v71, v71, v182, s[16:17]
	v_cndmask_b32_e64 v72, v72, v182, s[18:19]
	v_mul_f32_e32 v74, 0x3e38aa3b, v132
	v_mul_f32_e32 v75, 0x3e38aa3b, v133
	s_and_b64 s[34:35], s[76:77], vcc
	v_cmp_gt_u32_e32 vcc, s83, v117
	v_add_u32_e32 v117, 0x43, v166
	v_max3_f32 v70, v70, v71, v72
	v_cndmask_b32_e64 v74, v74, v182, s[20:21]
	v_cndmask_b32_e64 v75, v75, v182, s[22:23]
	v_mul_f32_e32 v106, 0x3e38aa3b, v134
	v_mul_f32_e32 v116, 0x3e38aa3b, v135
	s_and_b64 s[36:37], s[76:77], vcc
	v_cmp_gt_u32_e32 vcc, s83, v117
	v_add_u32_e32 v117, 0x42, v166
	v_max3_f32 v70, v70, v74, v75
	v_cndmask_b32_e64 v106, v106, v182, s[24:25]
	v_cndmask_b32_e64 v116, v116, v182, s[26:27]
	v_mul_f32_e32 v108, 0x3e38aa3b, v108
	v_mul_f32_e32 v109, 0x3e38aa3b, v109
	v_cmp_gt_u32_e64 s[6:7], s83, v117
	v_add_u32_e32 v117, 0x41, v166
	v_max3_f32 v70, v70, v106, v116
	v_cndmask_b32_e64 v108, v108, v182, s[28:29]
	v_cndmask_b32_e64 v109, v109, v182, s[30:31]
	v_mul_f32_e32 v110, 0x3e38aa3b, v110
	v_mul_f32_e32 v111, 0x3e38aa3b, v111
	v_cmp_gt_u32_e64 s[8:9], s83, v117
	v_add_u32_e32 v117, 64, v166
	v_max3_f32 v70, v70, v108, v109
	v_cndmask_b32_e64 v110, v110, v182, s[34:35]
	v_cndmask_b32_e64 v111, v111, v182, s[36:37]
	v_mul_f32_e32 v112, 0x3e38aa3b, v112
	s_and_b64 vcc, s[76:77], vcc
	v_mul_f32_e32 v113, 0x3e38aa3b, v113
	s_and_b64 s[6:7], s[76:77], s[6:7]
	v_cmp_gt_u32_e64 s[10:11], s83, v117
	v_max3_f32 v70, v70, v110, v111
	v_cndmask_b32_e32 v112, v112, v182, vcc
	v_cndmask_b32_e64 v113, v113, v182, s[6:7]
	v_mul_f32_e32 v114, 0x3e38aa3b, v114
	s_and_b64 s[8:9], s[76:77], s[8:9]
	v_mul_f32_e32 v115, 0x3e38aa3b, v115
	s_and_b64 s[10:11], s[76:77], s[10:11]
	v_max3_f32 v70, v70, v112, v113
	v_cndmask_b32_e64 v114, v114, v182, s[8:9]
	v_cndmask_b32_e64 v118, v115, v182, s[10:11]
	v_max3_f32 v70, v70, v114, v118
	v_mov_b32_e32 v115, v70
	s_nop 1
	v_permlane16_swap_b32_e32 v70, v115
	v_max_f32_e32 v70, v70, v115
	v_mov_b32_e32 v115, v70
	s_nop 1
	v_permlane32_swap_b32_e32 v70, v115
	v_max3_f32 v140, v73, v70, v115
	v_sub_f32_e32 v68, v68, v140
	v_exp_f32_e32 v139, v68
	v_sub_f32_e32 v68, v69, v140
	v_exp_f32_e32 v137, v68
	v_sub_f32_e32 v68, v71, v140
	v_exp_f32_e32 v135, v68
	v_sub_f32_e32 v68, v72, v140
	v_exp_f32_e32 v133, v68
	v_sub_f32_e32 v68, v74, v140
	v_exp_f32_e32 v131, v68
	v_sub_f32_e32 v68, v75, v140
	v_exp_f32_e32 v129, v68
	v_sub_f32_e32 v68, v106, v140
	v_exp_f32_e32 v127, v68
	v_sub_f32_e32 v68, v116, v140
	v_exp_f32_e32 v125, v68
	v_sub_f32_e32 v68, v108, v140
	v_add_u32_e32 v108, 0x83, v166
	v_cmp_gt_u32_e64 s[40:41], s83, v108
	v_mul_f32_e32 v76, 0x3e38aa3b, v76
	s_and_b64 s[40:41], s[76:77], s[40:41]
	v_add_u32_e32 v108, 0x82, v166
	v_exp_f32_e32 v123, v68
	v_sub_f32_e32 v68, v109, v140
	v_cndmask_b32_e64 v76, v76, v182, s[40:41]
	v_cmp_gt_u32_e64 s[40:41], s83, v108
	v_exp_f32_e32 v121, v68
	v_sub_f32_e32 v68, v110, v140
	v_mul_f32_e32 v77, 0x3e38aa3b, v77
	s_and_b64 s[40:41], s[76:77], s[40:41]
	v_add_u32_e32 v110, 0x81, v166
	v_cndmask_b32_e64 v77, v77, v182, s[40:41]
	v_cmp_gt_u32_e64 s[40:41], s83, v110
	v_mul_f32_e32 v78, 0x3e38aa3b, v78
	s_and_b64 s[40:41], s[76:77], s[40:41]
	v_cndmask_b32_e64 v110, v78, v182, s[40:41]
	v_mul_f32_e32 v78, 0x3e38aa3b, v79
	v_add_u32_e32 v79, 0x80, v166
	v_cmp_gt_u32_e64 s[40:41], s83, v79
	s_and_b64 s[40:41], s[76:77], s[40:41]
	v_max3_f32 v108, v76, s71, v77
	v_cndmask_b32_e64 v79, v78, v182, s[40:41]
	v_mul_f32_e32 v80, 0x3e38aa3b, v80
	v_mul_f32_e32 v81, 0x3e38aa3b, v81
	v_exp_f32_e32 v119, v68
	v_sub_f32_e32 v68, v111, v140
	v_max3_f32 v78, v108, v110, v79
	v_cndmask_b32_e64 v80, v80, v182, s[12:13]
	v_cndmask_b32_e64 v81, v81, v182, s[14:15]
	v_mul_f32_e32 v82, 0x3e38aa3b, v82
	v_mul_f32_e32 v83, 0x3e38aa3b, v83
	v_exp_f32_e32 v115, v68
	v_sub_f32_e32 v68, v112, v140
	v_max3_f32 v78, v78, v80, v81
	v_cndmask_b32_e64 v82, v82, v182, s[16:17]
	v_cndmask_b32_e64 v83, v83, v182, s[18:19]
	v_mul_f32_e32 v84, 0x3e38aa3b, v84
	v_mul_f32_e32 v85, 0x3e38aa3b, v85
	v_exp_f32_e32 v111, v68
	v_sub_f32_e32 v68, v113, v140
	v_max3_f32 v78, v78, v82, v83
	v_cndmask_b32_e64 v84, v84, v182, s[20:21]
	v_cndmask_b32_e64 v85, v85, v182, s[22:23]
	v_mul_f32_e32 v86, 0x3e38aa3b, v86
	v_mul_f32_e32 v87, 0x3e38aa3b, v87
	v_exp_f32_e32 v109, v68
	v_sub_f32_e32 v68, v114, v140
	v_max3_f32 v78, v78, v84, v85
	v_cndmask_b32_e64 v86, v86, v182, s[24:25]
	v_cndmask_b32_e64 v87, v87, v182, s[26:27]
	v_mul_f32_e32 v108, 0x3e38aa3b, v142
	v_mul_f32_e32 v112, 0x3e38aa3b, v143
	v_mul_f32_e32 v114, 0x3e38aa3b, v144
	v_max3_f32 v78, v78, v86, v87
	v_cndmask_b32_e64 v108, v108, v182, s[28:29]
	v_cndmask_b32_e64 v112, v112, v182, s[30:31]
	v_cndmask_b32_e64 v116, v114, v182, s[34:35]
	v_mul_f32_e32 v114, 0x3e38aa3b, v145
	v_max3_f32 v78, v78, v108, v112
	v_cndmask_b32_e64 v141, v114, v182, s[36:37]
	v_max3_f32 v78, v78, v116, v141
	v_mov_b32_e32 v114, v78
	s_nop 1
	v_permlane16_swap_b32_e32 v78, v114
	v_max_f32_e32 v78, v78, v114
	v_mov_b32_e32 v114, v78
	s_nop 1
	v_permlane32_swap_b32_e32 v78, v114
	v_max3_f32 v78, v167, v78, v114
	v_sub_f32_e32 v76, v76, v78
	v_exp_f32_e32 v138, v76
	v_sub_f32_e32 v76, v77, v78
	v_exp_f32_e32 v136, v76
	v_sub_f32_e32 v76, v110, v78
	v_exp_f32_e32 v134, v76
	v_sub_f32_e32 v76, v79, v78
	v_exp_f32_e32 v132, v76
	v_sub_f32_e32 v76, v80, v78
	v_exp_f32_e32 v130, v76
	v_sub_f32_e32 v76, v81, v78
	v_exp_f32_e32 v128, v76
	v_sub_f32_e32 v76, v82, v78
	v_exp_f32_e32 v126, v76
	v_sub_f32_e32 v76, v83, v78
	v_exp_f32_e32 v124, v76
	v_sub_f32_e32 v76, v84, v78
	v_exp_f32_e32 v122, v76
	v_sub_f32_e32 v76, v85, v78
	v_exp_f32_e32 v120, v76
	v_sub_f32_e32 v76, v86, v78
	v_exp_f32_e32 v117, v68
	v_sub_f32_e32 v68, v118, v140
	v_exp_f32_e32 v118, v76
	v_sub_f32_e32 v76, v87, v78
	v_exp_f32_e32 v114, v76
	v_sub_f32_e32 v76, v108, v78
	v_sub_f32_e32 v77, v116, v78
	v_sub_f32_e32 v70, v73, v140
	v_sub_f32_e32 v142, v167, v78
	v_exp_f32_e32 v110, v76
	v_sub_f32_e32 v76, v112, v78
	v_exp_f32_e32 v116, v77
	v_sub_f32_e32 v77, v141, v78
	v_exp_f32_e32 v106, v70
	v_exp_f32_e32 v113, v68
	v_exp_f32_e32 v108, v76
	v_exp_f32_e32 v76, v142
	v_exp_f32_e32 v112, v77
	v_pk_mul_f32 v[58:59], v[58:59], v[106:107] op_sel_hi:[1,0]
	v_pk_mul_f32 v[56:57], v[56:57], v[106:107] op_sel_hi:[1,0]
	v_pk_mul_f32 v[54:55], v[54:55], v[106:107] op_sel_hi:[1,0]
	v_pk_mul_f32 v[52:53], v[52:53], v[106:107] op_sel_hi:[1,0]
	v_pk_mul_f32 v[62:63], v[62:63], v[106:107] op_sel_hi:[1,0]
	v_pk_mul_f32 v[60:61], v[60:61], v[106:107] op_sel_hi:[1,0]
	v_pk_mul_f32 v[70:71], v[66:67], v[106:107] op_sel_hi:[1,0]
	v_pk_mul_f32 v[68:69], v[64:65], v[106:107] op_sel_hi:[1,0]
	v_cvt_pk_bf16_f32 v72, v139, v137
	v_cvt_pk_bf16_f32 v73, v135, v133
	v_cvt_pk_bf16_f32 v74, v131, v129
	v_cvt_pk_bf16_f32 v75, v127, v125
	v_cvt_pk_bf16_f32 v64, v123, v121
	v_cvt_pk_bf16_f32 v65, v119, v115
	v_cvt_pk_bf16_f32 v66, v111, v109
	v_cvt_pk_bf16_f32 v67, v117, v113
	v_pk_mul_f32 v[42:43], v[42:43], v[76:77] op_sel_hi:[1,0]
	v_pk_mul_f32 v[40:41], v[40:41], v[76:77] op_sel_hi:[1,0]
	v_pk_mul_f32 v[38:39], v[38:39], v[76:77] op_sel_hi:[1,0]
	v_pk_mul_f32 v[36:37], v[36:37], v[76:77] op_sel_hi:[1,0]
	v_pk_mul_f32 v[46:47], v[46:47], v[76:77] op_sel_hi:[1,0]
	v_pk_mul_f32 v[44:45], v[44:45], v[76:77] op_sel_hi:[1,0]
	v_pk_mul_f32 v[50:51], v[50:51], v[76:77] op_sel_hi:[1,0]
	v_pk_mul_f32 v[48:49], v[48:49], v[76:77] op_sel_hi:[1,0]
	v_cvt_pk_bf16_f32 v80, v138, v136
	v_cvt_pk_bf16_f32 v81, v134, v132
	v_cvt_pk_bf16_f32 v82, v130, v128
	v_cvt_pk_bf16_f32 v83, v126, v124
	v_cvt_pk_bf16_f32 v84, v122, v120
	v_cvt_pk_bf16_f32 v85, v118, v114
	v_cvt_pk_bf16_f32 v86, v110, v108
	v_cvt_pk_bf16_f32 v87, v116, v112
	s_nop 0
	v_add3_u32 v77, s78, v164, v165
	ds_read_b64_tr_b16 v[206:207], v77 offset:20992
	ds_read_b64_tr_b16 v[204:205], v77 offset:18432
	ds_read_b64_tr_b16 v[208:209], v77 offset:18464
	ds_read_b64_tr_b16 v[210:211], v77 offset:21024
	ds_read_b64_tr_b16 v[212:213], v77 offset:23552
	ds_read_b64_tr_b16 v[214:215], v77 offset:26112
	ds_read_b64_tr_b16 v[216:217], v77 offset:23584
	ds_read_b64_tr_b16 v[218:219], v77 offset:26144
	ds_read_b64_tr_b16 v[220:221], v77 offset:18496
	ds_read_b64_tr_b16 v[222:223], v77 offset:21056
	ds_read_b64_tr_b16 v[224:225], v77 offset:23616
	ds_read_b64_tr_b16 v[226:227], v77 offset:26176
	ds_read_b64_tr_b16 v[228:229], v77 offset:18528
	ds_read_b64_tr_b16 v[230:231], v77 offset:21088
	ds_read_b64_tr_b16 v[232:233], v77 offset:23648
	ds_read_b64_tr_b16 v[234:235], v77 offset:26208
	s_waitcnt lgkmcnt(14)
	v_mfma_f32_16x16x32_bf16 v[56:59], v[204:207], v[72:75], v[56:59]
	v_mfma_f32_16x16x32_bf16 v[40:43], v[204:207], v[80:83], v[40:43]
	s_waitcnt lgkmcnt(10)
	v_mfma_f32_16x16x32_bf16 v[56:59], v[212:215], v[64:67], v[56:59]
	v_mfma_f32_16x16x32_bf16 v[40:43], v[212:215], v[84:87], v[40:43]
	v_mfma_f32_16x16x32_bf16 v[52:55], v[208:211], v[72:75], v[52:55]
	v_mfma_f32_16x16x32_bf16 v[36:39], v[208:211], v[80:83], v[36:39]
	s_waitcnt lgkmcnt(8)
	v_mfma_f32_16x16x32_bf16 v[52:55], v[216:219], v[64:67], v[52:55]
	v_mfma_f32_16x16x32_bf16 v[36:39], v[216:219], v[84:87], v[36:39]
	s_waitcnt lgkmcnt(6)
	v_mfma_f32_16x16x32_bf16 v[60:63], v[220:223], v[72:75], v[60:63]
	v_mfma_f32_16x16x32_bf16 v[44:47], v[220:223], v[80:83], v[44:47]
	s_waitcnt lgkmcnt(4)
	v_mfma_f32_16x16x32_bf16 v[60:63], v[224:227], v[64:67], v[60:63]
	v_mfma_f32_16x16x32_bf16 v[44:47], v[224:227], v[84:87], v[44:47]
	s_waitcnt lgkmcnt(2)
	v_mfma_f32_16x16x32_bf16 v[68:71], v[228:231], v[72:75], v[68:71]
	v_mfma_f32_16x16x32_bf16 v[48:51], v[228:231], v[80:83], v[48:51]
	s_waitcnt lgkmcnt(0)
	v_mfma_f32_16x16x32_bf16 v[64:67], v[232:235], v[64:67], v[68:71]
	v_mfma_f32_16x16x32_bf16 v[48:51], v[232:235], v[84:87], v[48:51]
	s_nop 3
	s_nop 0
	s_nop 0
	ds_read_b128 v[204:207], v88 offset:9216
	ds_read_b128 v[208:211], v88 offset:9280
	ds_read_b128 v[212:215], v88 offset:11520
	ds_read_b128 v[216:219], v88 offset:13824
	ds_read_b128 v[220:223], v88 offset:16128
	ds_read_b128 v[224:227], v88 offset:11584
	ds_read_b128 v[228:231], v88 offset:13888
	ds_read_b128 v[232:235], v88 offset:16192
	s_waitcnt lgkmcnt(7)
	v_mfma_f32_16x16x32_bf16 v[72:75], v[204:207], v[4:7], v[0:3]
	v_mfma_f32_16x16x32_bf16 v[68:71], v[204:207], v[12:15], v[0:3]
	s_waitcnt lgkmcnt(6)
	v_mfma_f32_16x16x32_bf16 v[168:171], v[208:211], v[16:19], v[68:71]
	v_mfma_f32_16x16x32_bf16 v[72:75], v[208:211], v[8:11], v[72:75]
	s_waitcnt lgkmcnt(5)
	v_mfma_f32_16x16x32_bf16 v[84:87], v[212:215], v[4:7], v[0:3]
	v_mfma_f32_16x16x32_bf16 v[80:83], v[212:215], v[12:15], v[0:3]
	s_waitcnt lgkmcnt(2)
	v_mfma_f32_16x16x32_bf16 v[84:87], v[224:227], v[8:11], v[84:87]
	v_mfma_f32_16x16x32_bf16 v[186:189], v[224:227], v[16:19], v[80:83]
	v_mfma_f32_16x16x32_bf16 v[146:149], v[216:219], v[4:7], v[0:3]
	v_mfma_f32_16x16x32_bf16 v[142:145], v[216:219], v[12:15], v[0:3]
	s_waitcnt lgkmcnt(1)
	v_mfma_f32_16x16x32_bf16 v[80:83], v[228:231], v[8:11], v[146:149]
	v_mfma_f32_16x16x32_bf16 v[190:193], v[228:231], v[16:19], v[142:145]
	v_mfma_f32_16x16x32_bf16 v[154:157], v[220:223], v[4:7], v[0:3]
	v_mfma_f32_16x16x32_bf16 v[150:153], v[220:223], v[12:15], v[0:3]
	s_waitcnt lgkmcnt(0)
	v_mfma_f32_16x16x32_bf16 v[142:145], v[232:235], v[8:11], v[154:157]
	v_mfma_f32_16x16x32_bf16 v[194:197], v[232:235], v[16:19], v[150:153]
	s_nop 0
	s_nop 0
	v_mul_f32_e32 v68, 0x3e38aa3b, v72
	v_add_u32_e32 v69, 51, v166
	v_mul_f32_e32 v71, 0x3e38aa3b, v74
	v_add_u32_e32 v72, 49, v166
	v_add_u32_e32 v74, 35, v166
	v_cmp_gt_u32_e64 s[12:13], s83, v69
	v_mul_f32_e32 v69, 0x3e38aa3b, v73
	v_cmp_gt_u32_e64 s[16:17], s83, v72
	v_mul_f32_e32 v72, 0x3e38aa3b, v75
	v_add_u32_e32 v73, 48, v166
	v_cmp_gt_u32_e64 s[20:21], s83, v74
	v_add_u32_e32 v75, 34, v166
	v_cmp_gt_u32_e64 s[18:19], s83, v73
	v_mul_f32_e32 v73, 0x3e38aa3b, v84
	s_and_b64 s[20:21], s[76:77], s[20:21]
	v_cmp_gt_u32_e64 s[22:23], s83, v75
	v_add_u32_e32 v79, 33, v166
	v_cndmask_b32_e64 v74, v73, v182, s[20:21]
	v_mul_f32_e32 v73, 0x3e38aa3b, v85
	s_and_b64 s[22:23], s[76:77], s[22:23]
	v_cmp_gt_u32_e64 s[24:25], s83, v79
	v_add_u32_e32 v84, 32, v166
	v_cndmask_b32_e64 v75, v73, v182, s[22:23]
	v_mul_f32_e32 v73, 0x3e38aa3b, v86
	s_and_b64 s[24:25], s[76:77], s[24:25]
	v_cmp_gt_u32_e64 s[26:27], s83, v84
	v_cndmask_b32_e64 v79, v73, v182, s[24:25]
	v_mul_f32_e32 v73, 0x3e38aa3b, v87
	s_and_b64 s[26:27], s[76:77], s[26:27]
	v_cndmask_b32_e64 v84, v73, v182, s[26:27]
	v_mul_f32_e32 v73, 0x3e38aa3b, v80
	v_add_u32_e32 v80, 19, v166
	v_cmp_gt_u32_e64 s[28:29], s83, v80
	s_and_b64 s[28:29], s[76:77], s[28:29]
	v_add_u32_e32 v70, 50, v166
	v_cndmask_b32_e64 v80, v73, v182, s[28:29]
	v_mul_f32_e32 v73, 0x3e38aa3b, v81
	v_add_u32_e32 v81, 18, v166
	v_cmp_gt_u32_e64 s[30:31], s83, v81
	s_and_b64 s[30:31], s[76:77], s[30:31]
	v_cmp_gt_u32_e64 s[14:15], s83, v70
	v_cndmask_b32_e64 v81, v73, v182, s[30:31]
	v_mul_f32_e32 v73, 0x3e38aa3b, v82
	v_add_u32_e32 v82, 17, v166
	v_cmp_gt_u32_e64 s[34:35], s83, v82
	s_and_b64 s[34:35], s[76:77], s[34:35]
	v_add_u32_e32 v85, 3, v166
	v_cndmask_b32_e64 v82, v73, v182, s[34:35]
	v_mul_f32_e32 v73, 0x3e38aa3b, v83
	v_add_u32_e32 v83, 16, v166
	v_cmp_gt_u32_e64 s[36:37], s83, v83
	s_and_b64 s[12:13], s[76:77], s[12:13]
	s_and_b64 s[14:15], s[76:77], s[14:15]
	s_and_b64 s[36:37], s[76:77], s[36:37]
	v_cmp_gt_u32_e64 s[40:41], s83, v85
	v_cndmask_b32_e64 v68, v68, v182, s[12:13]
	v_cndmask_b32_e64 v69, v69, v182, s[14:15]
	s_and_b64 s[16:17], s[76:77], s[16:17]
	s_and_b64 s[18:19], s[76:77], s[18:19]
	v_cndmask_b32_e64 v83, v73, v182, s[36:37]
	v_mul_f32_e32 v73, 0x3e38aa3b, v142
	s_and_b64 s[40:41], s[76:77], s[40:41]
	v_add_u32_e32 v86, 2, v166
	v_max3_f32 v70, v68, s71, v69
	v_cndmask_b32_e64 v71, v71, v182, s[16:17]
	v_cndmask_b32_e64 v72, v72, v182, s[18:19]
	v_cndmask_b32_e64 v85, v73, v182, s[40:41]
	v_cmp_gt_u32_e64 s[40:41], s83, v86
	v_max3_f32 v70, v70, v71, v72
	v_mul_f32_e32 v73, 0x3e38aa3b, v143
	s_and_b64 s[40:41], s[76:77], s[40:41]
	v_add_u32_e32 v87, 1, v166
	v_max3_f32 v70, v70, v74, v75
	v_cndmask_b32_e64 v86, v73, v182, s[40:41]
	v_cmp_gt_u32_e64 s[40:41], s83, v87
	v_max3_f32 v70, v70, v79, v84
	v_mul_f32_e32 v73, 0x3e38aa3b, v144
	s_and_b64 s[40:41], s[76:77], s[40:41]
	v_max3_f32 v70, v70, v80, v81
	v_cndmask_b32_e64 v88, v73, v182, s[40:41]
	v_cmp_gt_u32_e64 s[40:41], s83, v166
	v_max3_f32 v70, v70, v82, v83
	v_mul_f32_e32 v73, 0x3e38aa3b, v145
	s_and_b64 s[40:41], s[76:77], s[40:41]
	v_max3_f32 v70, v70, v85, v86
	v_cndmask_b32_e64 v142, v73, v182, s[40:41]
	v_max3_f32 v70, v70, v88, v142
	v_mov_b32_e32 v73, v70
	s_nop 1
	v_permlane16_swap_b32_e32 v70, v73
	v_max_f32_e32 v70, v70, v73
	v_mov_b32_e32 v73, v70
	s_nop 1
	v_permlane32_swap_b32_e32 v70, v73
	v_max3_f32 v73, v140, v70, v73
	v_sub_f32_e32 v68, v68, v73
	v_exp_f32_e32 v159, v68
	v_sub_f32_e32 v68, v69, v73
	v_exp_f32_e32 v157, v68
	v_sub_f32_e32 v68, v71, v73
	v_exp_f32_e32 v155, v68
	v_sub_f32_e32 v68, v72, v73
	v_exp_f32_e32 v153, v68
	v_sub_f32_e32 v68, v74, v73
	v_exp_f32_e32 v151, v68
	v_sub_f32_e32 v68, v75, v73
	v_exp_f32_e32 v149, v68
	v_sub_f32_e32 v68, v79, v73
	v_exp_f32_e32 v147, v68
	v_sub_f32_e32 v68, v84, v73
	v_exp_f32_e32 v145, v68
	v_sub_f32_e32 v68, v80, v73
	v_exp_f32_e32 v143, v68
	v_sub_f32_e32 v68, v81, v73
	v_exp_f32_e32 v141, v68
	v_sub_f32_e32 v68, v82, v73
	v_sub_f32_e32 v70, v140, v73
	v_exp_f32_e32 v87, v68
	v_sub_f32_e32 v68, v83, v73
	v_exp_f32_e32 v83, v68
	v_sub_f32_e32 v68, v85, v73
	v_exp_f32_e32 v72, v70
	v_exp_f32_e32 v79, v68
	v_sub_f32_e32 v68, v86, v73
	v_exp_f32_e32 v75, v68
	v_sub_f32_e32 v68, v88, v73
	v_exp_f32_e32 v85, v68
	v_sub_f32_e32 v68, v142, v73
	v_exp_f32_e32 v81, v68
	v_pk_mul_f32 v[68:69], v[64:65], v[72:73] op_sel_hi:[1,0]
	v_mul_f32_e32 v64, 0x3e38aa3b, v168
	v_cndmask_b32_e32 v74, v64, v182, vcc
	v_mul_f32_e32 v64, 0x3e38aa3b, v169
	v_cndmask_b32_e64 v80, v64, v182, s[6:7]
	v_mul_f32_e32 v64, 0x3e38aa3b, v170
	v_cndmask_b32_e64 v82, v64, v182, s[8:9]
	v_mul_f32_e32 v64, 0x3e38aa3b, v171
	v_cndmask_b32_e64 v84, v64, v182, s[10:11]
	v_mul_f32_e32 v64, 0x3e38aa3b, v186
	v_cndmask_b32_e64 v86, v64, v182, s[12:13]
	v_mul_f32_e32 v64, 0x3e38aa3b, v187
	v_cndmask_b32_e64 v88, v64, v182, s[14:15]
	v_mul_f32_e32 v64, 0x3e38aa3b, v188
	v_cndmask_b32_e64 v140, v64, v182, s[16:17]
	v_mul_f32_e32 v64, 0x3e38aa3b, v189
	v_cndmask_b32_e64 v142, v64, v182, s[18:19]
	v_mul_f32_e32 v64, 0x3e38aa3b, v190
	v_cndmask_b32_e64 v160, v64, v182, s[20:21]
	v_mul_f32_e32 v64, 0x3e38aa3b, v191
	v_cndmask_b32_e64 v161, v64, v182, s[22:23]
	v_mul_f32_e32 v64, 0x3e38aa3b, v192
	v_cndmask_b32_e64 v172, v64, v182, s[24:25]
	v_mul_f32_e32 v64, 0x3e38aa3b, v193
	v_cndmask_b32_e64 v173, v64, v182, s[26:27]
	v_mul_f32_e32 v64, 0x3e38aa3b, v194
	v_cndmask_b32_e64 v185, v64, v182, s[28:29]
	v_mul_f32_e32 v64, 0x3e38aa3b, v195
	v_cndmask_b32_e64 v186, v64, v182, s[30:31]
	v_mul_f32_e32 v64, 0x3e38aa3b, v196
	v_cndmask_b32_e64 v187, v64, v182, s[34:35]
	v_mul_f32_e32 v64, 0x3e38aa3b, v197
	v_cndmask_b32_e64 v188, v64, v182, s[36:37]
	v_max3_f32 v64, v74, s71, v80
	v_max3_f32 v64, v64, v82, v84
	v_max3_f32 v64, v64, v86, v88
	v_max3_f32 v64, v64, v140, v142
	v_max3_f32 v64, v64, v160, v161
	v_max3_f32 v64, v64, v172, v173
	v_max3_f32 v144, v64, v185, v186
	v_max3_f32 v144, v144, v187, v188
	v_mov_b32_e32 v146, v144
	s_nop 1
	v_permlane16_swap_b32_e32 v144, v146
	v_max_f32_e32 v144, v144, v146
	v_mov_b32_e32 v146, v144
	s_nop 1
	v_permlane32_swap_b32_e32 v144, v146
	v_max3_f32 v167, v78, v144, v146
	v_sub_f32_e32 v74, v74, v167
	v_exp_f32_e32 v158, v74
	v_sub_f32_e32 v74, v80, v167
	v_exp_f32_e32 v156, v74
	v_sub_f32_e32 v74, v82, v167
	v_exp_f32_e32 v154, v74
	v_sub_f32_e32 v74, v84, v167
	v_exp_f32_e32 v152, v74
	v_sub_f32_e32 v74, v86, v167
	v_exp_f32_e32 v150, v74
	v_sub_f32_e32 v74, v88, v167
	v_exp_f32_e32 v148, v74
	v_sub_f32_e32 v74, v140, v167
	v_exp_f32_e32 v146, v74
	v_sub_f32_e32 v74, v142, v167
	v_exp_f32_e32 v144, v74
	v_sub_f32_e32 v74, v160, v167
	v_exp_f32_e32 v142, v74
	v_sub_f32_e32 v74, v161, v167
	v_exp_f32_e32 v140, v74
	v_sub_f32_e32 v74, v172, v167
	v_exp_f32_e32 v86, v74
	v_sub_f32_e32 v74, v173, v167
	v_sub_f32_e32 v189, v78, v167
	v_exp_f32_e32 v82, v74
	v_sub_f32_e32 v74, v185, v167
	v_sub_f32_e32 v80, v187, v167
	v_exp_f32_e32 v78, v74
	v_sub_f32_e32 v74, v186, v167
	v_exp_f32_e32 v160, v189
	v_exp_f32_e32 v84, v80
	v_sub_f32_e32 v80, v188, v167
	v_exp_f32_e32 v74, v74
	v_exp_f32_e32 v80, v80
	v_pk_mul_f32 v[58:59], v[58:59], v[72:73] op_sel_hi:[1,0]
	v_pk_mul_f32 v[56:57], v[56:57], v[72:73] op_sel_hi:[1,0]
	v_pk_mul_f32 v[54:55], v[54:55], v[72:73] op_sel_hi:[1,0]
	v_pk_mul_f32 v[52:53], v[52:53], v[72:73] op_sel_hi:[1,0]
	v_pk_mul_f32 v[62:63], v[62:63], v[72:73] op_sel_hi:[1,0]
	v_pk_mul_f32 v[60:61], v[60:61], v[72:73] op_sel_hi:[1,0]
	v_pk_mul_f32 v[70:71], v[66:67], v[72:73] op_sel_hi:[1,0]
	v_cvt_pk_bf16_f32 v64, v143, v141
	v_cvt_pk_bf16_f32 v65, v87, v83
	v_cvt_pk_bf16_f32 v66, v79, v75
	v_cvt_pk_bf16_f32 v67, v85, v81
	v_pk_mul_f32 v[42:43], v[42:43], v[160:161] op_sel_hi:[1,0]
	v_pk_mul_f32 v[40:41], v[40:41], v[160:161] op_sel_hi:[1,0]
	v_pk_mul_f32 v[38:39], v[38:39], v[160:161] op_sel_hi:[1,0]
	v_pk_mul_f32 v[36:37], v[36:37], v[160:161] op_sel_hi:[1,0]
	v_pk_mul_f32 v[46:47], v[46:47], v[160:161] op_sel_hi:[1,0]
	v_pk_mul_f32 v[44:45], v[44:45], v[160:161] op_sel_hi:[1,0]
	v_pk_mul_f32 v[50:51], v[50:51], v[160:161] op_sel_hi:[1,0]
	v_pk_mul_f32 v[48:49], v[48:49], v[160:161] op_sel_hi:[1,0]
	v_cvt_pk_bf16_f32 v168, v159, v157
	v_cvt_pk_bf16_f32 v169, v155, v153
	v_cvt_pk_bf16_f32 v170, v151, v149
	v_cvt_pk_bf16_f32 v171, v147, v145
	v_cvt_pk_bf16_f32 v186, v158, v156
	v_cvt_pk_bf16_f32 v187, v154, v152
	v_cvt_pk_bf16_f32 v188, v150, v148
	v_cvt_pk_bf16_f32 v189, v146, v144
	v_cvt_pk_bf16_f32 v190, v142, v140
	v_cvt_pk_bf16_f32 v191, v86, v82
	v_cvt_pk_bf16_f32 v192, v78, v74
	v_cvt_pk_bf16_f32 v193, v84, v80
	s_nop 0
	ds_read_b64_tr_b16 v[206:207], v77 offset:31232
	ds_read_b64_tr_b16 v[204:205], v77 offset:28672
	ds_read_b64_tr_b16 v[208:209], v77 offset:28704
	ds_read_b64_tr_b16 v[210:211], v77 offset:31264
	ds_read_b64_tr_b16 v[212:213], v77 offset:33792
	ds_read_b64_tr_b16 v[214:215], v77 offset:36352
	ds_read_b64_tr_b16 v[216:217], v77 offset:33824
	ds_read_b64_tr_b16 v[218:219], v77 offset:36384
	ds_read_b64_tr_b16 v[220:221], v77 offset:28736
	ds_read_b64_tr_b16 v[222:223], v77 offset:31296
	ds_read_b64_tr_b16 v[224:225], v77 offset:33856
	ds_read_b64_tr_b16 v[226:227], v77 offset:36416
	ds_read_b64_tr_b16 v[228:229], v77 offset:28768
	ds_read_b64_tr_b16 v[230:231], v77 offset:31328
	ds_read_b64_tr_b16 v[232:233], v77 offset:33888
	ds_read_b64_tr_b16 v[234:235], v77 offset:36448
	s_waitcnt lgkmcnt(14)
	v_mfma_f32_16x16x32_bf16 v[56:59], v[204:207], v[168:171], v[56:59]
	v_mfma_f32_16x16x32_bf16 v[40:43], v[204:207], v[186:189], v[40:43]
	s_waitcnt lgkmcnt(10)
	v_mfma_f32_16x16x32_bf16 v[56:59], v[212:215], v[64:67], v[56:59]
	v_mfma_f32_16x16x32_bf16 v[40:43], v[212:215], v[190:193], v[40:43]
	v_mfma_f32_16x16x32_bf16 v[52:55], v[208:211], v[168:171], v[52:55]
	v_mfma_f32_16x16x32_bf16 v[36:39], v[208:211], v[186:189], v[36:39]
	s_waitcnt lgkmcnt(8)
	v_mfma_f32_16x16x32_bf16 v[52:55], v[216:219], v[64:67], v[52:55]
	v_mfma_f32_16x16x32_bf16 v[36:39], v[216:219], v[190:193], v[36:39]
	s_waitcnt lgkmcnt(6)
	v_mfma_f32_16x16x32_bf16 v[60:63], v[220:223], v[168:171], v[60:63]
	v_mfma_f32_16x16x32_bf16 v[44:47], v[220:223], v[186:189], v[44:47]
	s_waitcnt lgkmcnt(4)
	v_mfma_f32_16x16x32_bf16 v[60:63], v[224:227], v[64:67], v[60:63]
	v_mfma_f32_16x16x32_bf16 v[44:47], v[224:227], v[190:193], v[44:47]
	s_waitcnt lgkmcnt(2)
	v_mfma_f32_16x16x32_bf16 v[68:71], v[228:231], v[168:171], v[68:71]
	v_mfma_f32_16x16x32_bf16 v[48:51], v[228:231], v[186:189], v[48:51]
	s_waitcnt lgkmcnt(0)
	v_mfma_f32_16x16x32_bf16 v[64:67], v[232:235], v[64:67], v[68:71]
	v_mfma_f32_16x16x32_bf16 v[48:51], v[232:235], v[190:193], v[48:51]
	s_nop 3
	s_nop 0
	s_add_i32 s12, s33, 1
	s_cmp_ge_i32 s12, s44
	s_cbranch_scc1 .LBB0_1303
	s_bitcmp1_b32 s12, 0
	s_cselect_b32 s6, 0x9800, 0
	v_add3_u32 v71, s6, v99, v98
	v_add3_u32 v68, s6, v162, v98
	v_add3_u32 v69, s6, v107, v98
	v_add3_u32 v70, s6, v103, v98
	s_waitcnt vmcnt(0)
	ds_write_b128 v71, v[20:23]
	ds_write_b128 v70, v[24:27]
	ds_write_b128 v69, v[28:31] offset:18432
	ds_write_b128 v68, v[32:35] offset:18432

.Lnm0_entry:
	s_nop 0
	v_or_b32_e32 v68, s78, v94
	v_add_u32_e32 v88, v68, v163
	ds_read_b128 v[204:207], v88 offset:2304
	ds_read_b128 v[208:211], v88
	ds_read_b128 v[212:215], v88 offset:4608
	ds_read_b128 v[216:219], v88 offset:6912
	ds_read_b128 v[220:223], v88 offset:64
	ds_read_b128 v[224:227], v88 offset:2368
	ds_read_b128 v[228:231], v88 offset:4672
	ds_read_b128 v[232:235], v88 offset:6976
	s_waitcnt lgkmcnt(7)
	v_mfma_f32_16x16x32_bf16 v[82:85], v[204:207], v[4:7], v[0:3]
	v_mfma_f32_16x16x32_bf16 v[108:111], v[204:207], v[12:15], v[0:3]
	s_waitcnt lgkmcnt(5)
	v_mfma_f32_16x16x32_bf16 v[112:115], v[212:215], v[4:7], v[0:3]
	v_mfma_f32_16x16x32_bf16 v[116:119], v[212:215], v[12:15], v[0:3]
	s_waitcnt lgkmcnt(4)
	v_mfma_f32_16x16x32_bf16 v[120:123], v[216:219], v[4:7], v[0:3]
	v_mfma_f32_16x16x32_bf16 v[124:127], v[216:219], v[12:15], v[0:3]
	v_mfma_f32_16x16x32_bf16 v[74:77], v[208:211], v[4:7], v[0:3]
	v_mfma_f32_16x16x32_bf16 v[68:71], v[208:211], v[12:15], v[0:3]
	s_waitcnt lgkmcnt(3)
	v_mfma_f32_16x16x32_bf16 v[128:131], v[220:223], v[8:11], v[74:77]
	v_mfma_f32_16x16x32_bf16 v[76:79], v[220:223], v[16:19], v[68:71]
	s_waitcnt lgkmcnt(2)
	v_mfma_f32_16x16x32_bf16 v[132:135], v[224:227], v[8:11], v[82:85]
	v_mfma_f32_16x16x32_bf16 v[80:83], v[224:227], v[16:19], v[108:111]
	s_waitcnt lgkmcnt(1)
	v_mfma_f32_16x16x32_bf16 v[108:111], v[228:231], v[8:11], v[112:115]
	v_mfma_f32_16x16x32_bf16 v[84:87], v[228:231], v[16:19], v[116:119]
	s_waitcnt lgkmcnt(0)
	v_mfma_f32_16x16x32_bf16 v[112:115], v[232:235], v[8:11], v[120:123]
	v_mfma_f32_16x16x32_bf16 v[142:145], v[232:235], v[16:19], v[124:127]
	s_nop 1
	s_nop 0
	v_mul_f32_e32 v68, 0x3e38aa3b, v128
	v_mul_f32_e32 v69, 0x3e38aa3b, v129
	v_mul_f32_e32 v71, 0x3e38aa3b, v130
	v_mul_f32_e32 v72, 0x3e38aa3b, v131
	v_max3_f32 v70, v68, s71, v69
	v_mul_f32_e32 v74, 0x3e38aa3b, v132
	v_mul_f32_e32 v75, 0x3e38aa3b, v133
	v_max3_f32 v70, v70, v71, v72
	v_mul_f32_e32 v106, 0x3e38aa3b, v134
	v_mul_f32_e32 v116, 0x3e38aa3b, v135
	v_max3_f32 v70, v70, v74, v75
	v_mul_f32_e32 v108, 0x3e38aa3b, v108
	v_mul_f32_e32 v109, 0x3e38aa3b, v109
	v_max3_f32 v70, v70, v106, v116
	v_mul_f32_e32 v110, 0x3e38aa3b, v110
	v_mul_f32_e32 v111, 0x3e38aa3b, v111
	v_max3_f32 v70, v70, v108, v109
	v_mul_f32_e32 v112, 0x3e38aa3b, v112
	v_mul_f32_e32 v113, 0x3e38aa3b, v113
	v_max3_f32 v70, v70, v110, v111
	v_mul_f32_e32 v114, 0x3e38aa3b, v114
	v_mul_f32_e32 v115, 0x3e38aa3b, v115
	v_max3_f32 v70, v70, v112, v113
	v_mov_b32_e32 v118, v115
	v_max3_f32 v70, v70, v114, v118
	v_mov_b32_e32 v115, v70
	s_nop 1
	v_permlane16_swap_b32_e32 v70, v115
	v_max_f32_e32 v70, v70, v115
	v_mov_b32_e32 v115, v70
	s_nop 1
	v_permlane32_swap_b32_e32 v70, v115
	v_max3_f32 v140, v73, v70, v115
	v_sub_f32_e32 v68, v68, v140
	v_exp_f32_e32 v139, v68
	v_sub_f32_e32 v68, v69, v140
	v_exp_f32_e32 v137, v68
	v_sub_f32_e32 v68, v71, v140
	v_exp_f32_e32 v135, v68
	v_sub_f32_e32 v68, v72, v140
	v_exp_f32_e32 v133, v68
	v_sub_f32_e32 v68, v74, v140
	v_exp_f32_e32 v131, v68
	v_sub_f32_e32 v68, v75, v140
	v_exp_f32_e32 v129, v68
	v_sub_f32_e32 v68, v106, v140
	v_exp_f32_e32 v127, v68
	v_sub_f32_e32 v68, v116, v140
	v_exp_f32_e32 v125, v68
	v_sub_f32_e32 v68, v108, v140
	v_mul_f32_e32 v76, 0x3e38aa3b, v76
	v_exp_f32_e32 v123, v68
	v_sub_f32_e32 v68, v109, v140
	v_exp_f32_e32 v121, v68
	v_sub_f32_e32 v68, v110, v140
	v_mul_f32_e32 v77, 0x3e38aa3b, v77
	v_mul_f32_e32 v78, 0x3e38aa3b, v78
	v_mov_b32_e32 v110, v78
	v_mul_f32_e32 v78, 0x3e38aa3b, v79
	v_max3_f32 v108, v76, s71, v77
	v_mov_b32_e32 v79, v78
	v_mul_f32_e32 v80, 0x3e38aa3b, v80
	v_mul_f32_e32 v81, 0x3e38aa3b, v81
	v_exp_f32_e32 v119, v68
	v_sub_f32_e32 v68, v111, v140
	v_max3_f32 v78, v108, v110, v79
	v_mul_f32_e32 v82, 0x3e38aa3b, v82
	v_mul_f32_e32 v83, 0x3e38aa3b, v83
	v_exp_f32_e32 v115, v68
	v_sub_f32_e32 v68, v112, v140
	v_max3_f32 v78, v78, v80, v81
	v_mul_f32_e32 v84, 0x3e38aa3b, v84
	v_mul_f32_e32 v85, 0x3e38aa3b, v85
	v_exp_f32_e32 v111, v68
	v_sub_f32_e32 v68, v113, v140
	v_max3_f32 v78, v78, v82, v83
	v_mul_f32_e32 v86, 0x3e38aa3b, v86
	v_mul_f32_e32 v87, 0x3e38aa3b, v87
	v_exp_f32_e32 v109, v68
	v_sub_f32_e32 v68, v114, v140
	v_max3_f32 v78, v78, v84, v85
	v_mul_f32_e32 v108, 0x3e38aa3b, v142
	v_mul_f32_e32 v112, 0x3e38aa3b, v143
	v_mul_f32_e32 v114, 0x3e38aa3b, v144
	v_max3_f32 v78, v78, v86, v87
	v_mov_b32_e32 v116, v114
	v_mul_f32_e32 v114, 0x3e38aa3b, v145
	v_max3_f32 v78, v78, v108, v112
	v_mov_b32_e32 v141, v114
	v_max3_f32 v78, v78, v116, v141
	v_mov_b32_e32 v114, v78
	s_nop 1
	v_permlane16_swap_b32_e32 v78, v114
	v_max_f32_e32 v78, v78, v114
	v_mov_b32_e32 v114, v78
	s_nop 1
	v_permlane32_swap_b32_e32 v78, v114
	v_max3_f32 v78, v167, v78, v114
	v_sub_f32_e32 v76, v76, v78
	v_exp_f32_e32 v138, v76
	v_sub_f32_e32 v76, v77, v78
	v_exp_f32_e32 v136, v76
	v_sub_f32_e32 v76, v110, v78
	v_exp_f32_e32 v134, v76
	v_sub_f32_e32 v76, v79, v78
	v_exp_f32_e32 v132, v76
	v_sub_f32_e32 v76, v80, v78
	v_exp_f32_e32 v130, v76
	v_sub_f32_e32 v76, v81, v78
	v_exp_f32_e32 v128, v76
	v_sub_f32_e32 v76, v82, v78
	v_exp_f32_e32 v126, v76
	v_sub_f32_e32 v76, v83, v78
	v_exp_f32_e32 v124, v76
	v_sub_f32_e32 v76, v84, v78
	v_exp_f32_e32 v122, v76
	v_sub_f32_e32 v76, v85, v78
	v_exp_f32_e32 v120, v76
	v_sub_f32_e32 v76, v86, v78
	v_exp_f32_e32 v117, v68
	v_sub_f32_e32 v68, v118, v140
	v_exp_f32_e32 v118, v76
	v_sub_f32_e32 v76, v87, v78
	v_exp_f32_e32 v114, v76
	v_sub_f32_e32 v76, v108, v78
	v_sub_f32_e32 v77, v116, v78
	v_sub_f32_e32 v70, v73, v140
	v_sub_f32_e32 v142, v167, v78
	v_exp_f32_e32 v110, v76
	v_sub_f32_e32 v76, v112, v78
	v_exp_f32_e32 v116, v77
	v_sub_f32_e32 v77, v141, v78
	v_exp_f32_e32 v106, v70
	v_exp_f32_e32 v113, v68
	v_exp_f32_e32 v108, v76
	v_exp_f32_e32 v76, v142
	v_exp_f32_e32 v112, v77
	v_pk_mul_f32 v[58:59], v[58:59], v[106:107] op_sel_hi:[1,0]
	v_pk_mul_f32 v[56:57], v[56:57], v[106:107] op_sel_hi:[1,0]
	v_pk_mul_f32 v[54:55], v[54:55], v[106:107] op_sel_hi:[1,0]
	v_pk_mul_f32 v[52:53], v[52:53], v[106:107] op_sel_hi:[1,0]
	v_pk_mul_f32 v[62:63], v[62:63], v[106:107] op_sel_hi:[1,0]
	v_pk_mul_f32 v[60:61], v[60:61], v[106:107] op_sel_hi:[1,0]
	v_pk_mul_f32 v[70:71], v[66:67], v[106:107] op_sel_hi:[1,0]
	v_pk_mul_f32 v[68:69], v[64:65], v[106:107] op_sel_hi:[1,0]
	v_cvt_pk_bf16_f32 v72, v139, v137
	v_cvt_pk_bf16_f32 v73, v135, v133
	v_cvt_pk_bf16_f32 v74, v131, v129
	v_cvt_pk_bf16_f32 v75, v127, v125
	v_cvt_pk_bf16_f32 v64, v123, v121
	v_cvt_pk_bf16_f32 v65, v119, v115
	v_cvt_pk_bf16_f32 v66, v111, v109
	v_cvt_pk_bf16_f32 v67, v117, v113
	v_pk_mul_f32 v[42:43], v[42:43], v[76:77] op_sel_hi:[1,0]
	v_pk_mul_f32 v[40:41], v[40:41], v[76:77] op_sel_hi:[1,0]
	v_pk_mul_f32 v[38:39], v[38:39], v[76:77] op_sel_hi:[1,0]
	v_pk_mul_f32 v[36:37], v[36:37], v[76:77] op_sel_hi:[1,0]
	v_pk_mul_f32 v[46:47], v[46:47], v[76:77] op_sel_hi:[1,0]
	v_pk_mul_f32 v[44:45], v[44:45], v[76:77] op_sel_hi:[1,0]
	v_pk_mul_f32 v[50:51], v[50:51], v[76:77] op_sel_hi:[1,0]
	v_pk_mul_f32 v[48:49], v[48:49], v[76:77] op_sel_hi:[1,0]
	v_cvt_pk_bf16_f32 v80, v138, v136
	v_cvt_pk_bf16_f32 v81, v134, v132
	v_cvt_pk_bf16_f32 v82, v130, v128
	v_cvt_pk_bf16_f32 v83, v126, v124
	v_cvt_pk_bf16_f32 v84, v122, v120
	v_cvt_pk_bf16_f32 v85, v118, v114
	v_cvt_pk_bf16_f32 v86, v110, v108
	v_cvt_pk_bf16_f32 v87, v116, v112
	s_nop 0
	v_add3_u32 v77, s78, v164, v165
	ds_read_b64_tr_b16 v[206:207], v77 offset:20992
	ds_read_b64_tr_b16 v[204:205], v77 offset:18432
	ds_read_b64_tr_b16 v[208:209], v77 offset:18464
	ds_read_b64_tr_b16 v[210:211], v77 offset:21024
	ds_read_b64_tr_b16 v[212:213], v77 offset:23552
	ds_read_b64_tr_b16 v[214:215], v77 offset:26112
	ds_read_b64_tr_b16 v[216:217], v77 offset:23584
	ds_read_b64_tr_b16 v[218:219], v77 offset:26144
	ds_read_b64_tr_b16 v[220:221], v77 offset:18496
	ds_read_b64_tr_b16 v[222:223], v77 offset:21056
	ds_read_b64_tr_b16 v[224:225], v77 offset:23616
	ds_read_b64_tr_b16 v[226:227], v77 offset:26176
	ds_read_b64_tr_b16 v[228:229], v77 offset:18528
	ds_read_b64_tr_b16 v[230:231], v77 offset:21088
	ds_read_b64_tr_b16 v[232:233], v77 offset:23648
	ds_read_b64_tr_b16 v[234:235], v77 offset:26208
	s_waitcnt lgkmcnt(14)
	v_mfma_f32_16x16x32_bf16 v[56:59], v[204:207], v[72:75], v[56:59]
	v_mfma_f32_16x16x32_bf16 v[40:43], v[204:207], v[80:83], v[40:43]
	s_waitcnt lgkmcnt(10)
	v_mfma_f32_16x16x32_bf16 v[56:59], v[212:215], v[64:67], v[56:59]
	v_mfma_f32_16x16x32_bf16 v[40:43], v[212:215], v[84:87], v[40:43]
	v_mfma_f32_16x16x32_bf16 v[52:55], v[208:211], v[72:75], v[52:55]
	v_mfma_f32_16x16x32_bf16 v[36:39], v[208:211], v[80:83], v[36:39]
	s_waitcnt lgkmcnt(8)
	v_mfma_f32_16x16x32_bf16 v[52:55], v[216:219], v[64:67], v[52:55]
	v_mfma_f32_16x16x32_bf16 v[36:39], v[216:219], v[84:87], v[36:39]
	s_waitcnt lgkmcnt(6)
	v_mfma_f32_16x16x32_bf16 v[60:63], v[220:223], v[72:75], v[60:63]
	v_mfma_f32_16x16x32_bf16 v[44:47], v[220:223], v[80:83], v[44:47]
	s_waitcnt lgkmcnt(4)
	v_mfma_f32_16x16x32_bf16 v[60:63], v[224:227], v[64:67], v[60:63]
	v_mfma_f32_16x16x32_bf16 v[44:47], v[224:227], v[84:87], v[44:47]
	s_waitcnt lgkmcnt(2)
	v_mfma_f32_16x16x32_bf16 v[68:71], v[228:231], v[72:75], v[68:71]
	v_mfma_f32_16x16x32_bf16 v[48:51], v[228:231], v[80:83], v[48:51]
	s_waitcnt lgkmcnt(0)
	v_mfma_f32_16x16x32_bf16 v[64:67], v[232:235], v[64:67], v[68:71]
	v_mfma_f32_16x16x32_bf16 v[48:51], v[232:235], v[84:87], v[48:51]
	s_nop 3
	s_nop 0
	s_nop 0
	ds_read_b128 v[204:207], v88 offset:9216
	ds_read_b128 v[208:211], v88 offset:9280
	ds_read_b128 v[212:215], v88 offset:11520
	ds_read_b128 v[216:219], v88 offset:13824
	ds_read_b128 v[220:223], v88 offset:16128
	ds_read_b128 v[224:227], v88 offset:11584
	ds_read_b128 v[228:231], v88 offset:13888
	ds_read_b128 v[232:235], v88 offset:16192
	s_waitcnt lgkmcnt(7)
	v_mfma_f32_16x16x32_bf16 v[72:75], v[204:207], v[4:7], v[0:3]
	v_mfma_f32_16x16x32_bf16 v[68:71], v[204:207], v[12:15], v[0:3]
	s_waitcnt lgkmcnt(6)
	v_mfma_f32_16x16x32_bf16 v[168:171], v[208:211], v[16:19], v[68:71]
	v_mfma_f32_16x16x32_bf16 v[72:75], v[208:211], v[8:11], v[72:75]
	s_waitcnt lgkmcnt(5)
	v_mfma_f32_16x16x32_bf16 v[84:87], v[212:215], v[4:7], v[0:3]
	v_mfma_f32_16x16x32_bf16 v[80:83], v[212:215], v[12:15], v[0:3]
	s_waitcnt lgkmcnt(2)
	v_mfma_f32_16x16x32_bf16 v[84:87], v[224:227], v[8:11], v[84:87]
	v_mfma_f32_16x16x32_bf16 v[186:189], v[224:227], v[16:19], v[80:83]
	v_mfma_f32_16x16x32_bf16 v[146:149], v[216:219], v[4:7], v[0:3]
	v_mfma_f32_16x16x32_bf16 v[142:145], v[216:219], v[12:15], v[0:3]
	s_waitcnt lgkmcnt(1)
	v_mfma_f32_16x16x32_bf16 v[80:83], v[228:231], v[8:11], v[146:149]
	v_mfma_f32_16x16x32_bf16 v[190:193], v[228:231], v[16:19], v[142:145]
	v_mfma_f32_16x16x32_bf16 v[154:157], v[220:223], v[4:7], v[0:3]
	v_mfma_f32_16x16x32_bf16 v[150:153], v[220:223], v[12:15], v[0:3]
	s_waitcnt lgkmcnt(0)
	v_mfma_f32_16x16x32_bf16 v[142:145], v[232:235], v[8:11], v[154:157]
	v_mfma_f32_16x16x32_bf16 v[194:197], v[232:235], v[16:19], v[150:153]
	s_nop 0
	s_nop 0
	v_mul_f32_e32 v68, 0x3e38aa3b, v72
	v_mul_f32_e32 v71, 0x3e38aa3b, v74
	v_mul_f32_e32 v69, 0x3e38aa3b, v73
	v_mul_f32_e32 v72, 0x3e38aa3b, v75
	v_mul_f32_e32 v73, 0x3e38aa3b, v84
	v_mov_b32_e32 v74, v73
	v_mul_f32_e32 v73, 0x3e38aa3b, v85
	v_mov_b32_e32 v75, v73
	v_mul_f32_e32 v73, 0x3e38aa3b, v86
	v_mov_b32_e32 v79, v73
	v_mul_f32_e32 v73, 0x3e38aa3b, v87
	v_mov_b32_e32 v84, v73
	v_mul_f32_e32 v73, 0x3e38aa3b, v80
	v_mov_b32_e32 v80, v73
	v_mul_f32_e32 v73, 0x3e38aa3b, v81
	v_mov_b32_e32 v81, v73
	v_mul_f32_e32 v73, 0x3e38aa3b, v82
	v_mov_b32_e32 v82, v73
	v_mul_f32_e32 v73, 0x3e38aa3b, v83
	v_mov_b32_e32 v83, v73
	v_mul_f32_e32 v73, 0x3e38aa3b, v142
	v_max3_f32 v70, v68, s71, v69
	v_mov_b32_e32 v85, v73
	v_max3_f32 v70, v70, v71, v72
	v_mul_f32_e32 v73, 0x3e38aa3b, v143
	v_max3_f32 v70, v70, v74, v75
	v_mov_b32_e32 v86, v73
	v_max3_f32 v70, v70, v79, v84
	v_mul_f32_e32 v73, 0x3e38aa3b, v144
	v_max3_f32 v70, v70, v80, v81
	v_mov_b32_e32 v88, v73
	v_max3_f32 v70, v70, v82, v83
	v_mul_f32_e32 v73, 0x3e38aa3b, v145
	v_max3_f32 v70, v70, v85, v86
	v_mov_b32_e32 v142, v73
	v_max3_f32 v70, v70, v88, v142
	v_mov_b32_e32 v73, v70
	s_nop 1
	v_permlane16_swap_b32_e32 v70, v73
	v_max_f32_e32 v70, v70, v73
	v_mov_b32_e32 v73, v70
	s_nop 1
	v_permlane32_swap_b32_e32 v70, v73
	v_max3_f32 v73, v140, v70, v73
	v_sub_f32_e32 v68, v68, v73
	v_exp_f32_e32 v159, v68
	v_sub_f32_e32 v68, v69, v73
	v_exp_f32_e32 v157, v68
	v_sub_f32_e32 v68, v71, v73
	v_exp_f32_e32 v155, v68
	v_sub_f32_e32 v68, v72, v73
	v_exp_f32_e32 v153, v68
	v_sub_f32_e32 v68, v74, v73
	v_exp_f32_e32 v151, v68
	v_sub_f32_e32 v68, v75, v73
	v_exp_f32_e32 v149, v68
	v_sub_f32_e32 v68, v79, v73
	v_exp_f32_e32 v147, v68
	v_sub_f32_e32 v68, v84, v73
	v_exp_f32_e32 v145, v68
	v_sub_f32_e32 v68, v80, v73
	v_exp_f32_e32 v143, v68
	v_sub_f32_e32 v68, v81, v73
	v_exp_f32_e32 v141, v68
	v_sub_f32_e32 v68, v82, v73
	v_sub_f32_e32 v70, v140, v73
	v_exp_f32_e32 v87, v68
	v_sub_f32_e32 v68, v83, v73
	v_exp_f32_e32 v83, v68
	v_sub_f32_e32 v68, v85, v73
	v_exp_f32_e32 v72, v70
	v_exp_f32_e32 v79, v68
	v_sub_f32_e32 v68, v86, v73
	v_exp_f32_e32 v75, v68
	v_sub_f32_e32 v68, v88, v73
	v_exp_f32_e32 v85, v68
	v_sub_f32_e32 v68, v142, v73
	v_exp_f32_e32 v81, v68
	v_pk_mul_f32 v[68:69], v[64:65], v[72:73] op_sel_hi:[1,0]
	v_mul_f32_e32 v64, 0x3e38aa3b, v168
	v_mov_b32_e32 v74, v64
	v_mul_f32_e32 v64, 0x3e38aa3b, v169
	v_mov_b32_e32 v80, v64
	v_mul_f32_e32 v64, 0x3e38aa3b, v170
	v_mov_b32_e32 v82, v64
	v_mul_f32_e32 v64, 0x3e38aa3b, v171
	v_mov_b32_e32 v84, v64
	v_mul_f32_e32 v64, 0x3e38aa3b, v186
	v_mov_b32_e32 v86, v64
	v_mul_f32_e32 v64, 0x3e38aa3b, v187
	v_mov_b32_e32 v88, v64
	v_mul_f32_e32 v64, 0x3e38aa3b, v188
	v_mov_b32_e32 v140, v64
	v_mul_f32_e32 v64, 0x3e38aa3b, v189
	v_mov_b32_e32 v142, v64
	v_mul_f32_e32 v64, 0x3e38aa3b, v190
	v_mov_b32_e32 v160, v64
	v_mul_f32_e32 v64, 0x3e38aa3b, v191
	v_mov_b32_e32 v161, v64
	v_mul_f32_e32 v64, 0x3e38aa3b, v192
	v_mov_b32_e32 v172, v64
	v_mul_f32_e32 v64, 0x3e38aa3b, v193
	v_mov_b32_e32 v173, v64
	v_mul_f32_e32 v64, 0x3e38aa3b, v194
	v_mov_b32_e32 v185, v64
	v_mul_f32_e32 v64, 0x3e38aa3b, v195
	v_mov_b32_e32 v186, v64
	v_mul_f32_e32 v64, 0x3e38aa3b, v196
	v_mov_b32_e32 v187, v64
	v_mul_f32_e32 v64, 0x3e38aa3b, v197
	v_mov_b32_e32 v188, v64
	v_max3_f32 v64, v74, s71, v80
	v_max3_f32 v64, v64, v82, v84
	v_max3_f32 v64, v64, v86, v88
	v_max3_f32 v64, v64, v140, v142
	v_max3_f32 v64, v64, v160, v161
	v_max3_f32 v64, v64, v172, v173
	v_max3_f32 v144, v64, v185, v186
	v_max3_f32 v144, v144, v187, v188
	v_mov_b32_e32 v146, v144
	s_nop 1
	v_permlane16_swap_b32_e32 v144, v146
	v_max_f32_e32 v144, v144, v146
	v_mov_b32_e32 v146, v144
	s_nop 1
	v_permlane32_swap_b32_e32 v144, v146
	v_max3_f32 v167, v78, v144, v146
	v_sub_f32_e32 v74, v74, v167
	v_exp_f32_e32 v158, v74
	v_sub_f32_e32 v74, v80, v167
	v_exp_f32_e32 v156, v74
	v_sub_f32_e32 v74, v82, v167
	v_exp_f32_e32 v154, v74
	v_sub_f32_e32 v74, v84, v167
	v_exp_f32_e32 v152, v74
	v_sub_f32_e32 v74, v86, v167
	v_exp_f32_e32 v150, v74
	v_sub_f32_e32 v74, v88, v167
	v_exp_f32_e32 v148, v74
	v_sub_f32_e32 v74, v140, v167
	v_exp_f32_e32 v146, v74
	v_sub_f32_e32 v74, v142, v167
	v_exp_f32_e32 v144, v74
	v_sub_f32_e32 v74, v160, v167
	v_exp_f32_e32 v142, v74
	v_sub_f32_e32 v74, v161, v167
	v_exp_f32_e32 v140, v74
	v_sub_f32_e32 v74, v172, v167
	v_exp_f32_e32 v86, v74
	v_sub_f32_e32 v74, v173, v167
	v_sub_f32_e32 v189, v78, v167
	v_exp_f32_e32 v82, v74
	v_sub_f32_e32 v74, v185, v167
	v_sub_f32_e32 v80, v187, v167
	v_exp_f32_e32 v78, v74
	v_sub_f32_e32 v74, v186, v167
	v_exp_f32_e32 v160, v189
	v_exp_f32_e32 v84, v80
	v_sub_f32_e32 v80, v188, v167
	v_exp_f32_e32 v74, v74
	v_exp_f32_e32 v80, v80
	v_pk_mul_f32 v[58:59], v[58:59], v[72:73] op_sel_hi:[1,0]
	v_pk_mul_f32 v[56:57], v[56:57], v[72:73] op_sel_hi:[1,0]
	v_pk_mul_f32 v[54:55], v[54:55], v[72:73] op_sel_hi:[1,0]
	v_pk_mul_f32 v[52:53], v[52:53], v[72:73] op_sel_hi:[1,0]
	v_pk_mul_f32 v[62:63], v[62:63], v[72:73] op_sel_hi:[1,0]
	v_pk_mul_f32 v[60:61], v[60:61], v[72:73] op_sel_hi:[1,0]
	v_pk_mul_f32 v[70:71], v[66:67], v[72:73] op_sel_hi:[1,0]
	v_cvt_pk_bf16_f32 v64, v143, v141
	v_cvt_pk_bf16_f32 v65, v87, v83
	v_cvt_pk_bf16_f32 v66, v79, v75
	v_cvt_pk_bf16_f32 v67, v85, v81
	v_pk_mul_f32 v[42:43], v[42:43], v[160:161] op_sel_hi:[1,0]
	v_pk_mul_f32 v[40:41], v[40:41], v[160:161] op_sel_hi:[1,0]
	v_pk_mul_f32 v[38:39], v[38:39], v[160:161] op_sel_hi:[1,0]
	v_pk_mul_f32 v[36:37], v[36:37], v[160:161] op_sel_hi:[1,0]
	v_pk_mul_f32 v[46:47], v[46:47], v[160:161] op_sel_hi:[1,0]
	v_pk_mul_f32 v[44:45], v[44:45], v[160:161] op_sel_hi:[1,0]
	v_pk_mul_f32 v[50:51], v[50:51], v[160:161] op_sel_hi:[1,0]
	v_pk_mul_f32 v[48:49], v[48:49], v[160:161] op_sel_hi:[1,0]
	v_cvt_pk_bf16_f32 v168, v159, v157
	v_cvt_pk_bf16_f32 v169, v155, v153
	v_cvt_pk_bf16_f32 v170, v151, v149
	v_cvt_pk_bf16_f32 v171, v147, v145
	v_cvt_pk_bf16_f32 v186, v158, v156
	v_cvt_pk_bf16_f32 v187, v154, v152
	v_cvt_pk_bf16_f32 v188, v150, v148
	v_cvt_pk_bf16_f32 v189, v146, v144
	v_cvt_pk_bf16_f32 v190, v142, v140
	v_cvt_pk_bf16_f32 v191, v86, v82
	v_cvt_pk_bf16_f32 v192, v78, v74
	v_cvt_pk_bf16_f32 v193, v84, v80
	s_nop 0
	ds_read_b64_tr_b16 v[206:207], v77 offset:31232
	ds_read_b64_tr_b16 v[204:205], v77 offset:28672
	ds_read_b64_tr_b16 v[208:209], v77 offset:28704
	ds_read_b64_tr_b16 v[210:211], v77 offset:31264
	ds_read_b64_tr_b16 v[212:213], v77 offset:33792
	ds_read_b64_tr_b16 v[214:215], v77 offset:36352
	ds_read_b64_tr_b16 v[216:217], v77 offset:33824
	ds_read_b64_tr_b16 v[218:219], v77 offset:36384
	ds_read_b64_tr_b16 v[220:221], v77 offset:28736
	ds_read_b64_tr_b16 v[222:223], v77 offset:31296
	ds_read_b64_tr_b16 v[224:225], v77 offset:33856
	ds_read_b64_tr_b16 v[226:227], v77 offset:36416
	ds_read_b64_tr_b16 v[228:229], v77 offset:28768
	ds_read_b64_tr_b16 v[230:231], v77 offset:31328
	ds_read_b64_tr_b16 v[232:233], v77 offset:33888
	ds_read_b64_tr_b16 v[234:235], v77 offset:36448
	s_waitcnt lgkmcnt(14)
	v_mfma_f32_16x16x32_bf16 v[56:59], v[204:207], v[168:171], v[56:59]
	v_mfma_f32_16x16x32_bf16 v[40:43], v[204:207], v[186:189], v[40:43]
	s_waitcnt lgkmcnt(10)
	v_mfma_f32_16x16x32_bf16 v[56:59], v[212:215], v[64:67], v[56:59]
	v_mfma_f32_16x16x32_bf16 v[40:43], v[212:215], v[190:193], v[40:43]
	v_mfma_f32_16x16x32_bf16 v[52:55], v[208:211], v[168:171], v[52:55]
	v_mfma_f32_16x16x32_bf16 v[36:39], v[208:211], v[186:189], v[36:39]
	s_waitcnt lgkmcnt(8)
	v_mfma_f32_16x16x32_bf16 v[52:55], v[216:219], v[64:67], v[52:55]
	v_mfma_f32_16x16x32_bf16 v[36:39], v[216:219], v[190:193], v[36:39]
	s_waitcnt lgkmcnt(6)
	v_mfma_f32_16x16x32_bf16 v[60:63], v[220:223], v[168:171], v[60:63]
	v_mfma_f32_16x16x32_bf16 v[44:47], v[220:223], v[186:189], v[44:47]
	s_waitcnt lgkmcnt(4)
	v_mfma_f32_16x16x32_bf16 v[60:63], v[224:227], v[64:67], v[60:63]
	v_mfma_f32_16x16x32_bf16 v[44:47], v[224:227], v[190:193], v[44:47]
	s_waitcnt lgkmcnt(2)
	v_mfma_f32_16x16x32_bf16 v[68:71], v[228:231], v[168:171], v[68:71]
	v_mfma_f32_16x16x32_bf16 v[48:51], v[228:231], v[186:189], v[48:51]
	s_waitcnt lgkmcnt(0)
	v_mfma_f32_16x16x32_bf16 v[64:67], v[232:235], v[64:67], v[68:71]
	v_mfma_f32_16x16x32_bf16 v[48:51], v[232:235], v[190:193], v[48:51]
	s_nop 3
	s_nop 0
	s_add_i32 s12, s33, 1
	s_cmp_ge_i32 s12, s44
	s_cbranch_scc1 .Lnm0_b1303
	s_bitcmp1_b32 s12, 0
	s_cselect_b32 s6, 0x9800, 0
	v_add3_u32 v71, s6, v99, v98
	v_add3_u32 v68, s6, v162, v98
	v_add3_u32 v69, s6, v107, v98
	v_add3_u32 v70, s6, v103, v98
	s_waitcnt vmcnt(0)
	ds_write_b128 v71, v[20:23]
	ds_write_b128 v70, v[24:27]
	ds_write_b128 v69, v[28:31] offset:18432
	ds_write_b128 v68, v[32:35] offset:18432

.LBB0_1312:
	s_setprio 0
	v_mov_b32_e32 v4, v97
	s_nop 1
	v_permlane16_swap_b32_e32 v97, v4
	v_add_f32_e32 v4, v97, v4
	v_mov_b32_e32 v5, v4
	s_nop 1
	v_permlane32_swap_b32_e32 v4, v5
	v_add_f32_e32 v4, v4, v5
	v_div_scale_f32 v5, s[6:7], v4, v4, 1.0
	v_rcp_f32_e32 v6, v5
	v_mov_b32_e32 v103, v89
	s_lshl_b32 s44, s94, 1
	s_mov_b64 s[8:9], 0x4552200
	v_fma_f32 v7, -v5, v6, 1.0
	v_fmac_f32_e32 v6, v7, v6
	v_div_scale_f32 v7, vcc, 1.0, v4, 1.0
	v_mul_f32_e32 v8, v7, v6
	v_fma_f32 v9, -v5, v8, v7
	v_fmac_f32_e32 v8, v9, v6
	v_fma_f32 v5, -v5, v8, v7
	v_div_fmas_f32 v5, v5, v6, v8
	v_lshlrev_b64 v[6:7], 11, v[92:93]
	v_lshl_add_u64 v[6:7], s[42:43], 0, v[6:7]
	v_lshl_add_u64 v[6:7], v[6:7], 0, s[44:45]
	v_lshlrev_b64 v[8:9], 1, v[102:103]
	v_div_fixup_f32 v4, v5, v4, 1.0
	v_lshl_add_u64 v[6:7], v[6:7], 0, v[8:9]
	s_mov_b32 s2, 0x4552000
	v_lshl_add_u64 v[10:11], v[6:7], 0, s[8:9]
	v_pk_mul_f32 v[12:13], v[56:57], v[4:5] op_sel_hi:[1,0]
	v_pk_mul_f32 v[14:15], v[58:59], v[4:5] op_sel_hi:[1,0]
	v_add_co_u32_e32 v6, vcc, s2, v6
	v_cvt_pk_bf16_f32 v12, v12, v13
	v_cvt_pk_bf16_f32 v13, v14, v15
	v_addc_co_u32_e32 v7, vcc, 0, v7, vcc
	flat_store_dwordx2 v[6:7], v[12:13] offset:512
	v_pk_mul_f32 v[6:7], v[52:53], v[4:5] op_sel_hi:[1,0]
	v_pk_mul_f32 v[12:13], v[54:55], v[4:5] op_sel_hi:[1,0]
	v_cvt_pk_bf16_f32 v6, v6, v7
	v_cvt_pk_bf16_f32 v7, v12, v13
	flat_store_dwordx2 v[10:11], v[6:7] offset:32
	v_pk_mul_f32 v[6:7], v[60:61], v[4:5] op_sel_hi:[1,0]
	v_pk_mul_f32 v[12:13], v[62:63], v[4:5] op_sel_hi:[1,0]
	v_cvt_pk_bf16_f32 v6, v6, v7
	v_cvt_pk_bf16_f32 v7, v12, v13
	flat_store_dwordx2 v[10:11], v[6:7] offset:64
	v_pk_mul_f32 v[6:7], v[64:65], v[4:5] op_sel_hi:[1,0]
	v_mov_b32_e32 v5, v96
	s_nop 1
	v_permlane16_swap_b32_e32 v96, v5
	v_add_f32_e32 v5, v96, v5
	v_cvt_pk_bf16_f32 v6, v6, v7
	v_mov_b32_e32 v7, v5
	s_nop 1
	v_permlane32_swap_b32_e32 v5, v7
	v_add_f32_e32 v12, v5, v7
	v_div_scale_f32 v13, s[6:7], v12, v12, 1.0
	v_rcp_f32_e32 v14, v13
	v_pk_mul_f32 v[4:5], v[66:67], v[4:5] op_sel_hi:[1,0]
	s_mov_b64 s[92:93], s[68:69]
	v_cvt_pk_bf16_f32 v7, v4, v5
	v_fma_f32 v4, -v13, v14, 1.0
	v_fmac_f32_e32 v14, v4, v14
	v_div_scale_f32 v4, vcc, 1.0, v12, 1.0
	v_mul_f32_e32 v5, v4, v14
	flat_store_dwordx2 v[10:11], v[6:7] offset:96
	v_fma_f32 v6, -v13, v5, v4
	v_fmac_f32_e32 v5, v6, v14
	v_lshlrev_b64 v[6:7], 11, v[90:91]
	v_fma_f32 v4, -v13, v5, v4
	v_lshl_add_u64 v[6:7], s[42:43], 0, v[6:7]
	v_div_fmas_f32 v4, v4, v14, v5
	v_lshl_add_u64 v[6:7], v[6:7], 0, s[44:45]
	v_div_fixup_f32 v4, v4, v12, 1.0
	v_lshl_add_u64 v[6:7], v[6:7], 0, v[8:9]
	v_lshl_add_u64 v[8:9], v[6:7], 0, s[8:9]
	v_pk_mul_f32 v[10:11], v[40:41], v[4:5] op_sel_hi:[1,0]
	v_pk_mul_f32 v[12:13], v[42:43], v[4:5] op_sel_hi:[1,0]
	v_add_co_u32_e32 v6, vcc, s2, v6
	v_cvt_pk_bf16_f32 v10, v10, v11
	v_cvt_pk_bf16_f32 v11, v12, v13
	v_addc_co_u32_e32 v7, vcc, 0, v7, vcc
	flat_store_dwordx2 v[6:7], v[10:11] offset:512
	v_pk_mul_f32 v[6:7], v[36:37], v[4:5] op_sel_hi:[1,0]
	v_pk_mul_f32 v[10:11], v[38:39], v[4:5] op_sel_hi:[1,0]
	v_cvt_pk_bf16_f32 v6, v6, v7
	v_cvt_pk_bf16_f32 v7, v10, v11
	flat_store_dwordx2 v[8:9], v[6:7] offset:32
	v_pk_mul_f32 v[6:7], v[44:45], v[4:5] op_sel_hi:[1,0]
	v_pk_mul_f32 v[10:11], v[46:47], v[4:5] op_sel_hi:[1,0]
	v_cvt_pk_bf16_f32 v6, v6, v7
	v_cvt_pk_bf16_f32 v7, v10, v11
	flat_store_dwordx2 v[8:9], v[6:7] offset:64
	v_pk_mul_f32 v[6:7], v[48:49], v[4:5] op_sel_hi:[1,0]
	v_pk_mul_f32 v[4:5], v[50:51], v[4:5] op_sel_hi:[1,0]
	v_cvt_pk_bf16_f32 v6, v6, v7
	v_cvt_pk_bf16_f32 v7, v4, v5
	flat_store_dwordx2 v[8:9], v[6:7] offset:96
	s_waitcnt lgkmcnt(0)
	s_barrier
	s_and_saveexec_b64 s[6:7], s[4:5]
	s_cbranch_execz .LBB0_1284
	s_cmp_eq_u32 s32, 0
	s_cbranch_scc1 .Lqf3
	s_waitcnt vmcnt(0) lgkmcnt(0)
	ds_write_b32 v178, v253
	s_mov_b32 s32, 0
	s_branch .LBB0_1284

.LBB0_2968:
	v_readfirstlane_b32 s98, v175
	s_bitcmp1_b32 s98, 8
	s_cbranch_scc0 .Lsp2
	s_setprio 1
.Lsp2:
	s_bitcmp1_b32 s10, 0
	s_cselect_b32 s11, 0xb800, 0
	s_nop 0
	v_or_b32_e32 v80, s11, v94
	v_add_u32_e32 v109, v80, v186
	ds_read_b128 v[220:223], v109
	ds_read_b128 v[224:227], v109 offset:64
	ds_read_b128 v[228:231], v109 offset:3328
	ds_read_b128 v[232:235], v109 offset:6656
	ds_read_b128 v[236:239], v109 offset:9984
	ds_read_b128 v[240:243], v109 offset:3392
	ds_read_b128 v[244:247], v109 offset:6720
	ds_read_b128 v[248:251], v109 offset:10048
	s_waitcnt lgkmcnt(7)
	v_mfma_f32_16x16x32_bf16 v[112:115], v[220:223], v[4:7], v[0:3]
	v_mfma_f32_16x16x32_bf16 v[82:85], v[220:223], v[16:19], v[0:3]
	ds_read_b128 v[220:223], v109 offset:128
	s_waitcnt lgkmcnt(7)
	v_mfma_f32_16x16x32_bf16 v[112:115], v[224:227], v[8:11], v[112:115]
	v_mfma_f32_16x16x32_bf16 v[82:85], v[224:227], v[20:23], v[82:85]
	ds_read_b128 v[224:227], v109 offset:3456
	s_waitcnt lgkmcnt(7)
	v_mfma_f32_16x16x32_bf16 v[120:123], v[228:231], v[4:7], v[0:3]
	v_mfma_f32_16x16x32_bf16 v[116:119], v[228:231], v[16:19], v[0:3]
	ds_read_b128 v[228:231], v109 offset:6784
	s_waitcnt lgkmcnt(5)
	v_mfma_f32_16x16x32_bf16 v[120:123], v[240:243], v[8:11], v[120:123]
	v_mfma_f32_16x16x32_bf16 v[116:119], v[240:243], v[20:23], v[116:119]
	ds_read_b128 v[240:243], v109 offset:10112
	v_mfma_f32_16x16x32_bf16 v[128:131], v[232:235], v[4:7], v[0:3]
	v_mfma_f32_16x16x32_bf16 v[124:127], v[232:235], v[16:19], v[0:3]
	s_waitcnt lgkmcnt(5)
	v_mfma_f32_16x16x32_bf16 v[128:131], v[244:247], v[8:11], v[128:131]
	v_mfma_f32_16x16x32_bf16 v[124:127], v[244:247], v[20:23], v[124:127]
	v_mfma_f32_16x16x32_bf16 v[136:139], v[236:239], v[4:7], v[0:3]
	v_mfma_f32_16x16x32_bf16 v[132:135], v[236:239], v[16:19], v[0:3]
	s_waitcnt lgkmcnt(4)
	v_mfma_f32_16x16x32_bf16 v[136:139], v[248:251], v[8:11], v[136:139]
	v_mfma_f32_16x16x32_bf16 v[132:135], v[248:251], v[20:23], v[132:135]
	s_waitcnt lgkmcnt(3)
	v_mfma_f32_16x16x32_bf16 v[148:151], v[220:223], v[24:27], v[82:85]
	s_waitcnt lgkmcnt(2)
	v_mfma_f32_16x16x32_bf16 v[120:123], v[224:227], v[12:15], v[120:123]
	v_mfma_f32_16x16x32_bf16 v[84:87], v[224:227], v[24:27], v[116:119]
	s_waitcnt lgkmcnt(1)
	v_mfma_f32_16x16x32_bf16 v[152:155], v[228:231], v[12:15], v[128:131]
	v_mfma_f32_16x16x32_bf16 v[156:159], v[228:231], v[24:27], v[124:127]
	v_mfma_f32_16x16x32_bf16 v[112:115], v[220:223], v[12:15], v[112:115]
	s_waitcnt lgkmcnt(0)
	v_mfma_f32_16x16x32_bf16 v[160:163], v[240:243], v[12:15], v[136:139]
	v_mfma_f32_16x16x32_bf16 v[164:167], v[240:243], v[24:27], v[132:135]
	s_nop 2
	s_nop 0
	s_nop 3
	v_max3_f32 v80, v112, v113, v114
	v_max3_f32 v80, v80, v115, v120
	v_max3_f32 v80, v80, v121, v122
	v_max3_f32 v80, v80, v123, v152
	v_max3_f32 v80, v80, v153, v154
	v_max3_f32 v80, v80, v155, v160
	v_max3_f32 v80, v80, v161, v162
	v_max_f32_e32 v80, v80, v163
	v_mul_f32_e32 v80, 0x3e16c740, v80
	v_max_f32_e32 v80, s68, v80
	v_mov_b32_e32 v82, v80
	s_nop 1
	v_permlane16_swap_b32_e32 v80, v82
	v_max_f32_e32 v80, v80, v82
	v_mov_b32_e32 v82, v80
	s_nop 1
	v_permlane32_swap_b32_e32 v80, v82
	v_max3_f32 v144, v81, v80, v82
	v_sub_f32_e32 v80, v81, v144
	v_fma_f32 v81, v112, s38, -v144
	v_exp_f32_e32 v143, v81
	v_fma_f32 v81, v113, s38, -v144
	v_exp_f32_e32 v141, v81
	v_fma_f32 v81, v114, s38, -v144
	v_max3_f32 v112, v148, v149, v150
	v_max3_f32 v112, v112, v151, v84
	v_max3_f32 v112, v112, v85, v86
	v_max3_f32 v112, v112, v87, v156
	v_max3_f32 v112, v112, v157, v158
	v_max3_f32 v112, v112, v159, v164
	v_max3_f32 v112, v112, v165, v166
	v_max_f32_e32 v112, v112, v167
	v_mul_f32_e32 v112, 0x3e16c740, v112
	v_max_f32_e32 v112, s68, v112
	v_mov_b32_e32 v114, v112
	s_nop 1
	v_permlane16_swap_b32_e32 v112, v114
	v_max_f32_e32 v112, v112, v114
	v_mov_b32_e32 v114, v112
	v_exp_f32_e32 v139, v81
	v_fma_f32 v81, v115, s38, -v144
	v_permlane32_swap_b32_e32 v112, v114
	v_exp_f32_e32 v137, v81
	v_fma_f32 v81, v120, s38, -v144
	v_max3_f32 v146, v189, v112, v114
	v_exp_f32_e32 v135, v81
	v_fma_f32 v81, v121, s38, -v144
	v_fma_f32 v84, v84, s38, -v146
	v_exp_f32_e32 v133, v81
	v_fma_f32 v81, v122, s38, -v144
	v_exp_f32_e32 v134, v84
	v_fma_f32 v84, v85, s38, -v146
	v_exp_f32_e32 v131, v81
	v_fma_f32 v81, v123, s38, -v144
	v_exp_f32_e32 v132, v84
	v_fma_f32 v84, v86, s38, -v146
	v_exp_f32_e32 v129, v81
	v_fma_f32 v81, v152, s38, -v144
	v_exp_f32_e32 v130, v84
	v_fma_f32 v84, v87, s38, -v146
	v_exp_f32_e32 v127, v81
	v_fma_f32 v81, v153, s38, -v144
	v_exp_f32_e32 v128, v84
	v_fma_f32 v84, v156, s38, -v146
	v_exp_f32_e32 v125, v81
	v_fma_f32 v81, v154, s38, -v144
	v_exp_f32_e32 v126, v84
	v_fma_f32 v84, v157, s38, -v146
	v_exp_f32_e32 v123, v81
	v_fma_f32 v81, v155, s38, -v144
	v_fma_f32 v112, v148, s38, -v146
	v_exp_f32_e32 v124, v84
	v_fma_f32 v84, v158, s38, -v146
	v_exp_f32_e32 v119, v81
	v_fma_f32 v81, v160, s38, -v144
	v_exp_f32_e32 v142, v112
	v_fma_f32 v112, v149, s38, -v146
	v_exp_f32_e32 v122, v84
	v_fma_f32 v84, v159, s38, -v146
	v_exp_f32_e32 v115, v81
	v_fma_f32 v81, v161, s38, -v144
	v_exp_f32_e32 v140, v112
	v_fma_f32 v112, v150, s38, -v146
	v_exp_f32_e32 v118, v84
	v_fma_f32 v84, v164, s38, -v146
	v_fma_f32 v85, v166, s38, -v146
	v_exp_f32_e32 v113, v81
	v_fma_f32 v81, v162, s38, -v144
	v_exp_f32_e32 v110, v80
	v_fma_f32 v80, v163, s38, -v144
	v_sub_f32_e32 v116, v189, v146
	v_exp_f32_e32 v138, v112
	v_fma_f32 v112, v151, s38, -v146
	v_exp_f32_e32 v114, v84
	v_fma_f32 v84, v165, s38, -v146
	v_exp_f32_e32 v120, v85
	v_fma_f32 v85, v167, s38, -v146
	v_exp_f32_e32 v121, v81
	v_exp_f32_e32 v117, v80
	v_exp_f32_e32 v136, v112
	v_exp_f32_e32 v112, v84
	v_exp_f32_e32 v84, v116
	v_exp_f32_e32 v116, v85
	v_pk_mul_f32 v[70:71], v[70:71], v[110:111] op_sel_hi:[1,0]
	v_pk_mul_f32 v[68:69], v[68:69], v[110:111] op_sel_hi:[1,0]
	v_pk_mul_f32 v[66:67], v[66:67], v[110:111] op_sel_hi:[1,0]
	v_pk_mul_f32 v[64:65], v[64:65], v[110:111] op_sel_hi:[1,0]
	v_pk_mul_f32 v[74:75], v[74:75], v[110:111] op_sel_hi:[1,0]
	v_pk_mul_f32 v[72:73], v[72:73], v[110:111] op_sel_hi:[1,0]
	v_pk_mul_f32 v[82:83], v[78:79], v[110:111] op_sel_hi:[1,0]
	v_pk_mul_f32 v[80:81], v[76:77], v[110:111] op_sel_hi:[1,0]
	v_cvt_pk_bf16_f32 v152, v143, v141
	v_cvt_pk_bf16_f32 v153, v139, v137
	v_cvt_pk_bf16_f32 v154, v135, v133
	v_cvt_pk_bf16_f32 v155, v131, v129
	v_cvt_pk_bf16_f32 v76, v127, v125
	v_cvt_pk_bf16_f32 v77, v123, v119
	v_cvt_pk_bf16_f32 v78, v115, v113
	v_cvt_pk_bf16_f32 v79, v121, v117
	v_pk_mul_f32 v[54:55], v[54:55], v[84:85] op_sel_hi:[1,0]
	v_pk_mul_f32 v[52:53], v[52:53], v[84:85] op_sel_hi:[1,0]
	v_pk_mul_f32 v[50:51], v[50:51], v[84:85] op_sel_hi:[1,0]
	v_pk_mul_f32 v[48:49], v[48:49], v[84:85] op_sel_hi:[1,0]
	v_pk_mul_f32 v[58:59], v[58:59], v[84:85] op_sel_hi:[1,0]
	v_pk_mul_f32 v[56:57], v[56:57], v[84:85] op_sel_hi:[1,0]
	v_pk_mul_f32 v[62:63], v[62:63], v[84:85] op_sel_hi:[1,0]
	v_pk_mul_f32 v[60:61], v[60:61], v[84:85] op_sel_hi:[1,0]
	v_cvt_pk_bf16_f32 v148, v142, v140
	v_cvt_pk_bf16_f32 v149, v138, v136
	v_cvt_pk_bf16_f32 v150, v134, v132
	v_cvt_pk_bf16_f32 v151, v130, v128
	v_cvt_pk_bf16_f32 v156, v126, v124
	v_cvt_pk_bf16_f32 v157, v122, v118
	v_cvt_pk_bf16_f32 v158, v114, v112
	v_cvt_pk_bf16_f32 v159, v120, v116
	s_nop 0
	v_add3_u32 v85, s11, v187, v188
	ds_read_b64_tr_b16 v[222:223], v85 offset:29184
	ds_read_b64_tr_b16 v[220:221], v85 offset:26624
	ds_read_b64_tr_b16 v[224:225], v85 offset:26656
	ds_read_b64_tr_b16 v[226:227], v85 offset:29216
	ds_read_b64_tr_b16 v[228:229], v85 offset:31744
	ds_read_b64_tr_b16 v[230:231], v85 offset:34304
	ds_read_b64_tr_b16 v[232:233], v85 offset:31776
	ds_read_b64_tr_b16 v[234:235], v85 offset:34336
	ds_read_b64_tr_b16 v[236:237], v85 offset:26688
	ds_read_b64_tr_b16 v[238:239], v85 offset:29248
	ds_read_b64_tr_b16 v[240:241], v85 offset:31808
	ds_read_b64_tr_b16 v[242:243], v85 offset:34368
	ds_read_b64_tr_b16 v[244:245], v85 offset:26720
	ds_read_b64_tr_b16 v[246:247], v85 offset:29280
	ds_read_b64_tr_b16 v[248:249], v85 offset:31840
	ds_read_b64_tr_b16 v[250:251], v85 offset:34400
	s_waitcnt lgkmcnt(14)
	v_mfma_f32_16x16x32_bf16 v[68:71], v[220:223], v[152:155], v[68:71]
	v_mfma_f32_16x16x32_bf16 v[52:55], v[220:223], v[148:151], v[52:55]
	s_waitcnt lgkmcnt(10)
	v_mfma_f32_16x16x32_bf16 v[68:71], v[228:231], v[76:79], v[68:71]
	v_mfma_f32_16x16x32_bf16 v[52:55], v[228:231], v[156:159], v[52:55]
	v_mfma_f32_16x16x32_bf16 v[64:67], v[224:227], v[152:155], v[64:67]
	v_mfma_f32_16x16x32_bf16 v[48:51], v[224:227], v[148:151], v[48:51]
	s_waitcnt lgkmcnt(8)
	v_mfma_f32_16x16x32_bf16 v[64:67], v[232:235], v[76:79], v[64:67]
	v_mfma_f32_16x16x32_bf16 v[48:51], v[232:235], v[156:159], v[48:51]
	s_waitcnt lgkmcnt(6)
	v_mfma_f32_16x16x32_bf16 v[72:75], v[236:239], v[152:155], v[72:75]
	v_mfma_f32_16x16x32_bf16 v[56:59], v[236:239], v[148:151], v[56:59]
	s_waitcnt lgkmcnt(4)
	v_mfma_f32_16x16x32_bf16 v[72:75], v[240:243], v[76:79], v[72:75]
	v_mfma_f32_16x16x32_bf16 v[56:59], v[240:243], v[156:159], v[56:59]
	s_waitcnt lgkmcnt(2)
	v_mfma_f32_16x16x32_bf16 v[60:63], v[244:247], v[148:151], v[60:63]
	v_mfma_f32_16x16x32_bf16 v[80:83], v[244:247], v[152:155], v[80:83]
	s_waitcnt lgkmcnt(0)
	v_mfma_f32_16x16x32_bf16 v[76:79], v[248:251], v[76:79], v[80:83]
	v_mfma_f32_16x16x32_bf16 v[60:63], v[248:251], v[156:159], v[60:63]
	s_nop 3
	s_nop 0
	s_nop 0
	ds_read_b128 v[220:223], v109 offset:13312
	ds_read_b128 v[224:227], v109 offset:13376
	ds_read_b128 v[228:231], v109 offset:16640
	ds_read_b128 v[232:235], v109 offset:19968
	ds_read_b128 v[236:239], v109 offset:23296
	ds_read_b128 v[240:243], v109 offset:16704
	ds_read_b128 v[244:247], v109 offset:20032
	ds_read_b128 v[248:251], v109 offset:23360
	s_waitcnt lgkmcnt(7)
	v_mfma_f32_16x16x32_bf16 v[148:151], v[220:223], v[4:7], v[0:3]
	v_mfma_f32_16x16x32_bf16 v[80:83], v[220:223], v[16:19], v[0:3]
	ds_read_b128 v[220:223], v109 offset:13440
	s_waitcnt lgkmcnt(7)
	v_mfma_f32_16x16x32_bf16 v[148:151], v[224:227], v[8:11], v[148:151]
	v_mfma_f32_16x16x32_bf16 v[80:83], v[224:227], v[20:23], v[80:83]
	ds_read_b128 v[224:227], v109 offset:16768
	s_waitcnt lgkmcnt(7)
	v_mfma_f32_16x16x32_bf16 v[156:159], v[228:231], v[4:7], v[0:3]
	v_mfma_f32_16x16x32_bf16 v[152:155], v[228:231], v[16:19], v[0:3]
	ds_read_b128 v[228:231], v109 offset:20096
	s_waitcnt lgkmcnt(5)
	v_mfma_f32_16x16x32_bf16 v[156:159], v[240:243], v[8:11], v[156:159]
	v_mfma_f32_16x16x32_bf16 v[152:155], v[240:243], v[20:23], v[152:155]
	ds_read_b128 v[240:243], v109 offset:23424
	v_mfma_f32_16x16x32_bf16 v[164:167], v[232:235], v[4:7], v[0:3]
	v_mfma_f32_16x16x32_bf16 v[160:163], v[232:235], v[16:19], v[0:3]
	s_waitcnt lgkmcnt(5)
	v_mfma_f32_16x16x32_bf16 v[164:167], v[244:247], v[8:11], v[164:167]
	v_mfma_f32_16x16x32_bf16 v[160:163], v[244:247], v[20:23], v[160:163]
	v_mfma_f32_16x16x32_bf16 v[190:193], v[236:239], v[4:7], v[0:3]
	v_mfma_f32_16x16x32_bf16 v[168:171], v[236:239], v[16:19], v[0:3]
	s_waitcnt lgkmcnt(4)
	v_mfma_f32_16x16x32_bf16 v[190:193], v[248:251], v[8:11], v[190:193]
	v_mfma_f32_16x16x32_bf16 v[168:171], v[248:251], v[20:23], v[168:171]
	s_waitcnt lgkmcnt(3)
	v_mfma_f32_16x16x32_bf16 v[148:151], v[220:223], v[12:15], v[148:151]
	v_mfma_f32_16x16x32_bf16 v[194:197], v[220:223], v[24:27], v[80:83]
	s_waitcnt lgkmcnt(2)
	v_mfma_f32_16x16x32_bf16 v[198:201], v[224:227], v[12:15], v[156:159]
	v_mfma_f32_16x16x32_bf16 v[202:205], v[224:227], v[24:27], v[152:155]
	s_waitcnt lgkmcnt(1)
	v_mfma_f32_16x16x32_bf16 v[206:209], v[228:231], v[12:15], v[164:167]
	v_mfma_f32_16x16x32_bf16 v[210:213], v[228:231], v[24:27], v[160:163]
	s_waitcnt lgkmcnt(0)
	v_mfma_f32_16x16x32_bf16 v[190:193], v[240:243], v[12:15], v[190:193]
	v_mfma_f32_16x16x32_bf16 v[214:217], v[240:243], v[24:27], v[168:171]
	s_nop 1
	s_nop 0
	v_max3_f32 v80, v148, v149, v150
	v_max3_f32 v80, v80, v151, v198
	v_max3_f32 v80, v80, v199, v200
	v_max3_f32 v80, v80, v201, v206
	v_max3_f32 v80, v80, v207, v208
	v_max3_f32 v80, v80, v209, v190
	v_max3_f32 v80, v80, v191, v192
	v_max_f32_e32 v80, v80, v193
	v_mul_f32_e32 v80, 0x3e16c740, v80
	v_max_f32_e32 v80, s68, v80
	v_mov_b32_e32 v81, v80
	s_nop 1
	v_permlane16_swap_b32_e32 v80, v81
	v_max_f32_e32 v80, v80, v81
	v_mov_b32_e32 v81, v80
	s_nop 1
	v_permlane32_swap_b32_e32 v80, v81
	v_max3_f32 v81, v144, v80, v81
	v_fma_f32 v82, v148, s38, -v81
	v_exp_f32_e32 v171, v82
	v_fma_f32 v82, v149, s38, -v81
	v_exp_f32_e32 v169, v82
	v_fma_f32 v82, v150, s38, -v81
	v_exp_f32_e32 v167, v82
	v_fma_f32 v82, v151, s38, -v81
	v_exp_f32_e32 v165, v82
	v_fma_f32 v82, v198, s38, -v81
	v_exp_f32_e32 v163, v82
	v_fma_f32 v82, v199, s38, -v81
	v_exp_f32_e32 v161, v82
	v_fma_f32 v82, v200, s38, -v81
	v_exp_f32_e32 v159, v82
	v_fma_f32 v82, v201, s38, -v81
	v_exp_f32_e32 v157, v82
	v_fma_f32 v82, v206, s38, -v81
	v_exp_f32_e32 v155, v82
	v_fma_f32 v82, v207, s38, -v81
	v_exp_f32_e32 v153, v82
	v_fma_f32 v82, v208, s38, -v81
	v_exp_f32_e32 v151, v82
	v_fma_f32 v82, v209, s38, -v81
	v_exp_f32_e32 v147, v82
	v_fma_f32 v82, v190, s38, -v81
	v_exp_f32_e32 v87, v82
	v_fma_f32 v82, v191, s38, -v81
	v_exp_f32_e32 v83, v82
	v_fma_f32 v82, v192, s38, -v81
	v_exp_f32_e32 v149, v82
	v_fma_f32 v82, v193, s38, -v81
	v_exp_f32_e32 v145, v82
	v_max3_f32 v82, v194, v195, v196
	v_max3_f32 v82, v82, v197, v202
	v_max3_f32 v82, v82, v203, v204
	v_max3_f32 v82, v82, v205, v210
	v_max3_f32 v82, v82, v211, v212
	v_max3_f32 v82, v82, v213, v214
	v_max3_f32 v82, v82, v215, v216
	v_max_f32_e32 v82, v82, v217
	v_mul_f32_e32 v82, 0x3e16c740, v82
	v_max_f32_e32 v82, s68, v82
	v_mov_b32_e32 v86, v82
	s_nop 1
	v_permlane16_swap_b32_e32 v82, v86
	v_max_f32_e32 v82, v82, v86
	v_mov_b32_e32 v86, v82
	s_nop 1
	v_permlane32_swap_b32_e32 v82, v86
	v_max3_f32 v189, v146, v82, v86
	v_fma_f32 v82, v194, s38, -v189
	v_exp_f32_e32 v170, v82
	v_fma_f32 v82, v195, s38, -v189
	v_exp_f32_e32 v168, v82
	v_fma_f32 v82, v196, s38, -v189
	v_exp_f32_e32 v166, v82
	v_fma_f32 v82, v197, s38, -v189
	v_exp_f32_e32 v164, v82
	v_fma_f32 v82, v202, s38, -v189
	v_exp_f32_e32 v162, v82
	v_fma_f32 v82, v203, s38, -v189
	v_exp_f32_e32 v160, v82
	v_fma_f32 v82, v204, s38, -v189
	v_exp_f32_e32 v158, v82
	v_fma_f32 v82, v205, s38, -v189
	v_exp_f32_e32 v156, v82
	v_fma_f32 v82, v210, s38, -v189
	v_exp_f32_e32 v154, v82
	v_fma_f32 v82, v211, s38, -v189
	v_exp_f32_e32 v152, v82
	v_fma_f32 v82, v212, s38, -v189
	v_exp_f32_e32 v150, v82
	v_fma_f32 v82, v213, s38, -v189
	v_sub_f32_e32 v80, v144, v81
	v_sub_f32_e32 v109, v146, v189
	v_exp_f32_e32 v146, v82
	v_fma_f32 v82, v214, s38, -v189
	v_exp_f32_e32 v80, v80
	v_exp_f32_e32 v86, v82
	v_fma_f32 v82, v215, s38, -v189
	v_fma_f32 v144, v216, s38, -v189
	v_exp_f32_e32 v172, v109
	v_fma_f32 v109, v217, s38, -v189
	v_exp_f32_e32 v82, v82
	v_exp_f32_e32 v148, v144
	v_exp_f32_e32 v144, v109
	v_pk_mul_f32 v[70:71], v[70:71], v[80:81] op_sel_hi:[1,0]
	v_pk_mul_f32 v[68:69], v[68:69], v[80:81] op_sel_hi:[1,0]
	v_pk_mul_f32 v[66:67], v[66:67], v[80:81] op_sel_hi:[1,0]
	v_pk_mul_f32 v[64:65], v[64:65], v[80:81] op_sel_hi:[1,0]
	v_pk_mul_f32 v[74:75], v[74:75], v[80:81] op_sel_hi:[1,0]
	v_pk_mul_f32 v[72:73], v[72:73], v[80:81] op_sel_hi:[1,0]
	v_pk_mul_f32 v[192:193], v[78:79], v[80:81] op_sel_hi:[1,0]
	v_pk_mul_f32 v[190:191], v[76:77], v[80:81] op_sel_hi:[1,0]
	v_cvt_pk_bf16_f32 v76, v155, v153
	v_cvt_pk_bf16_f32 v77, v151, v147
	v_cvt_pk_bf16_f32 v78, v87, v83
	v_cvt_pk_bf16_f32 v79, v149, v145
	v_pk_mul_f32 v[54:55], v[54:55], v[172:173] op_sel_hi:[1,0]
	v_pk_mul_f32 v[52:53], v[52:53], v[172:173] op_sel_hi:[1,0]
	v_pk_mul_f32 v[50:51], v[50:51], v[172:173] op_sel_hi:[1,0]
	v_pk_mul_f32 v[48:49], v[48:49], v[172:173] op_sel_hi:[1,0]
	v_pk_mul_f32 v[58:59], v[58:59], v[172:173] op_sel_hi:[1,0]
	v_pk_mul_f32 v[56:57], v[56:57], v[172:173] op_sel_hi:[1,0]
	v_pk_mul_f32 v[62:63], v[62:63], v[172:173] op_sel_hi:[1,0]
	v_pk_mul_f32 v[60:61], v[60:61], v[172:173] op_sel_hi:[1,0]
	v_cvt_pk_bf16_f32 v198, v171, v169
	v_cvt_pk_bf16_f32 v199, v167, v165
	v_cvt_pk_bf16_f32 v200, v163, v161
	v_cvt_pk_bf16_f32 v201, v159, v157
	v_cvt_pk_bf16_f32 v194, v170, v168
	v_cvt_pk_bf16_f32 v195, v166, v164
	v_cvt_pk_bf16_f32 v196, v162, v160
	v_cvt_pk_bf16_f32 v197, v158, v156
	v_cvt_pk_bf16_f32 v202, v154, v152
	v_cvt_pk_bf16_f32 v203, v150, v146
	v_cvt_pk_bf16_f32 v204, v86, v82
	v_cvt_pk_bf16_f32 v205, v148, v144
	s_nop 0
	ds_read_b64_tr_b16 v[222:223], v85 offset:39424
	ds_read_b64_tr_b16 v[220:221], v85 offset:36864
	ds_read_b64_tr_b16 v[224:225], v85 offset:36896
	ds_read_b64_tr_b16 v[226:227], v85 offset:39456
	ds_read_b64_tr_b16 v[228:229], v85 offset:41984
	ds_read_b64_tr_b16 v[230:231], v85 offset:44544
	ds_read_b64_tr_b16 v[232:233], v85 offset:42016
	ds_read_b64_tr_b16 v[234:235], v85 offset:44576
	ds_read_b64_tr_b16 v[236:237], v85 offset:36928
	ds_read_b64_tr_b16 v[238:239], v85 offset:39488
	ds_read_b64_tr_b16 v[240:241], v85 offset:42048
	ds_read_b64_tr_b16 v[242:243], v85 offset:44608
	ds_read_b64_tr_b16 v[244:245], v85 offset:36960
	ds_read_b64_tr_b16 v[246:247], v85 offset:39520
	ds_read_b64_tr_b16 v[248:249], v85 offset:42080
	ds_read_b64_tr_b16 v[250:251], v85 offset:44640
	s_waitcnt lgkmcnt(14)
	v_mfma_f32_16x16x32_bf16 v[68:71], v[220:223], v[198:201], v[68:71]
	v_mfma_f32_16x16x32_bf16 v[52:55], v[220:223], v[194:197], v[52:55]
	s_waitcnt lgkmcnt(10)
	v_mfma_f32_16x16x32_bf16 v[68:71], v[228:231], v[76:79], v[68:71]
	v_mfma_f32_16x16x32_bf16 v[52:55], v[228:231], v[202:205], v[52:55]
	v_mfma_f32_16x16x32_bf16 v[64:67], v[224:227], v[198:201], v[64:67]
	v_mfma_f32_16x16x32_bf16 v[48:51], v[224:227], v[194:197], v[48:51]
	s_waitcnt lgkmcnt(8)
	v_mfma_f32_16x16x32_bf16 v[64:67], v[232:235], v[76:79], v[64:67]
	v_mfma_f32_16x16x32_bf16 v[48:51], v[232:235], v[202:205], v[48:51]
	s_waitcnt lgkmcnt(6)
	v_mfma_f32_16x16x32_bf16 v[72:75], v[236:239], v[198:201], v[72:75]
	v_mfma_f32_16x16x32_bf16 v[56:59], v[236:239], v[194:197], v[56:59]
	s_waitcnt lgkmcnt(4)
	v_mfma_f32_16x16x32_bf16 v[72:75], v[240:243], v[76:79], v[72:75]
	v_mfma_f32_16x16x32_bf16 v[56:59], v[240:243], v[202:205], v[56:59]
	s_waitcnt lgkmcnt(2)
	v_mfma_f32_16x16x32_bf16 v[60:63], v[244:247], v[194:197], v[60:63]
	v_mfma_f32_16x16x32_bf16 v[190:193], v[244:247], v[198:201], v[190:193]
	s_waitcnt lgkmcnt(0)
	v_mfma_f32_16x16x32_bf16 v[76:79], v[248:251], v[76:79], v[190:193]
	v_mfma_f32_16x16x32_bf16 v[60:63], v[248:251], v[202:205], v[60:63]
	s_nop 3
	s_nop 0
	s_add_i32 s22, s10, 1
	s_cmp_ge_u32 s22, s19
	s_cbranch_scc1 .LBB0_2970
	s_bitcmp1_b32 s22, 0
	s_cselect_b32 s11, 0xb800, 0
	v_add3_u32 v85, s11, v95, v96
	s_waitcnt vmcnt(0)
	ds_write_b128 v85, v[28:31]
	v_add3_u32 v85, s11, v99, v96
	ds_write_b128 v85, v[36:39]
	v_add3_u32 v85, s11, v184, v96
	ds_write_b128 v85, v[32:35] offset:26624
	v_add3_u32 v85, s11, v185, v96
	ds_write_b128 v85, v[40:43] offset:26624
	v_add3_u32 v85, s11, v111, v98
	ds_write_b128 v85, v[44:47] offset:128

.LBB0_2973:
	s_setprio 0
	s_mov_b64 s[98:99], exec
	s_mov_b64 exec, s[4:5]
	s_cbranch_execz .Lqp7
	v_readlane_b32 s8, v252, 23
	v_readlane_b32 s9, v252, 24
	s_nop 1
	v_mov_b64_e32 v[254:255], s[8:9]
	global_atomic_add v253, v[254:255], v176, off sc0

.Lsp3:
	s_bitcmp1_b32 s82, 0
	s_cselect_b32 s83, 0x9800, 0
	s_cmp_lt_i32 s82, s76
	s_cselect_b64 s[6:7], -1, 0
	s_and_b64 s[74:75], s[70:71], s[6:7]
	s_cmp_eq_u64 s[74:75], 0
	s_cbranch_scc1 .Lnm1_entry
	s_nop 0
	v_or_b32_e32 v68, s83, v94
	v_add_u32_e32 v88, v68, v163
	ds_read_b128 v[204:207], v88 offset:2304
	ds_read_b128 v[208:211], v88
	ds_read_b128 v[212:215], v88 offset:4608
	ds_read_b128 v[216:219], v88 offset:6912
	ds_read_b128 v[220:223], v88 offset:64
	ds_read_b128 v[224:227], v88 offset:2368
	ds_read_b128 v[228:231], v88 offset:4672
	ds_read_b128 v[232:235], v88 offset:6976
	s_waitcnt lgkmcnt(7)
	v_mfma_f32_16x16x32_bf16 v[82:85], v[204:207], v[4:7], v[0:3]
	v_mfma_f32_16x16x32_bf16 v[108:111], v[204:207], v[12:15], v[0:3]
	s_waitcnt lgkmcnt(5)
	v_mfma_f32_16x16x32_bf16 v[112:115], v[212:215], v[4:7], v[0:3]
	v_mfma_f32_16x16x32_bf16 v[116:119], v[212:215], v[12:15], v[0:3]
	s_waitcnt lgkmcnt(4)
	v_mfma_f32_16x16x32_bf16 v[120:123], v[216:219], v[4:7], v[0:3]
	v_mfma_f32_16x16x32_bf16 v[124:127], v[216:219], v[12:15], v[0:3]
	v_mfma_f32_16x16x32_bf16 v[74:77], v[208:211], v[4:7], v[0:3]
	v_mfma_f32_16x16x32_bf16 v[68:71], v[208:211], v[12:15], v[0:3]
	s_waitcnt lgkmcnt(3)
	v_mfma_f32_16x16x32_bf16 v[128:131], v[220:223], v[8:11], v[74:77]
	v_mfma_f32_16x16x32_bf16 v[76:79], v[220:223], v[16:19], v[68:71]
	s_waitcnt lgkmcnt(2)
	v_mfma_f32_16x16x32_bf16 v[132:135], v[224:227], v[8:11], v[82:85]
	v_mfma_f32_16x16x32_bf16 v[80:83], v[224:227], v[16:19], v[108:111]
	s_waitcnt lgkmcnt(1)
	v_mfma_f32_16x16x32_bf16 v[108:111], v[228:231], v[8:11], v[112:115]
	v_mfma_f32_16x16x32_bf16 v[84:87], v[228:231], v[16:19], v[116:119]
	s_waitcnt lgkmcnt(0)
	v_mfma_f32_16x16x32_bf16 v[112:115], v[232:235], v[8:11], v[120:123]
	v_mfma_f32_16x16x32_bf16 v[142:145], v[232:235], v[16:19], v[124:127]
	s_nop 1
	s_nop 0
	v_add_u32_e32 v69, 0x73, v166
	v_cmp_gt_u32_e32 vcc, s39, v69
	v_add_u32_e32 v70, 0x72, v166
	s_and_b64 s[12:13], s[74:75], vcc
	v_cmp_gt_u32_e32 vcc, s39, v70
	v_add_u32_e32 v72, 0x71, v166
	s_and_b64 s[14:15], s[74:75], vcc
	v_cmp_gt_u32_e32 vcc, s39, v72
	v_add_u32_e32 v74, 0x70, v166
	s_and_b64 s[16:17], s[74:75], vcc
	v_cmp_gt_u32_e32 vcc, s39, v74
	v_add_u32_e32 v75, 0x63, v166
	s_and_b64 s[18:19], s[74:75], vcc
	v_cmp_gt_u32_e32 vcc, s39, v75
	v_add_u32_e32 v106, 0x62, v166
	s_and_b64 s[20:21], s[74:75], vcc
	v_cmp_gt_u32_e32 vcc, s39, v106
	v_add_u32_e32 v116, 0x61, v166
	s_and_b64 s[22:23], s[74:75], vcc
	v_cmp_gt_u32_e32 vcc, s39, v116
	v_add_u32_e32 v117, 0x60, v166
	s_and_b64 s[24:25], s[74:75], vcc
	v_cmp_gt_u32_e32 vcc, s39, v117
	v_add_u32_e32 v117, 0x53, v166
	s_and_b64 s[26:27], s[74:75], vcc
	v_cmp_gt_u32_e32 vcc, s39, v117
	v_add_u32_e32 v117, 0x52, v166
	v_mul_f32_e32 v68, 0x3e38aa3b, v128
	v_mul_f32_e32 v69, 0x3e38aa3b, v129
	s_and_b64 s[28:29], s[74:75], vcc
	v_cmp_gt_u32_e32 vcc, s39, v117
	v_add_u32_e32 v117, 0x51, v166
	v_cndmask_b32_e64 v68, v68, v181, s[12:13]
	v_cndmask_b32_e64 v69, v69, v181, s[14:15]
	v_mul_f32_e32 v71, 0x3e38aa3b, v130
	v_mul_f32_e32 v72, 0x3e38aa3b, v131
	s_and_b64 s[30:31], s[74:75], vcc
	v_cmp_gt_u32_e32 vcc, s39, v117
	v_add_u32_e32 v117, 0x50, v166
	v_max3_f32 v70, v68, s68, v69
	v_cndmask_b32_e64 v71, v71, v181, s[16:17]
	v_cndmask_b32_e64 v72, v72, v181, s[18:19]
	v_mul_f32_e32 v74, 0x3e38aa3b, v132
	v_mul_f32_e32 v75, 0x3e38aa3b, v133
	s_and_b64 s[34:35], s[74:75], vcc
	v_cmp_gt_u32_e32 vcc, s39, v117
	v_add_u32_e32 v117, 0x43, v166
	v_max3_f32 v70, v70, v71, v72
	v_cndmask_b32_e64 v74, v74, v181, s[20:21]
	v_cndmask_b32_e64 v75, v75, v181, s[22:23]
	v_mul_f32_e32 v106, 0x3e38aa3b, v134
	v_mul_f32_e32 v116, 0x3e38aa3b, v135
	s_and_b64 s[36:37], s[74:75], vcc
	v_cmp_gt_u32_e32 vcc, s39, v117
	v_add_u32_e32 v117, 0x42, v166
	v_max3_f32 v70, v70, v74, v75
	v_cndmask_b32_e64 v106, v106, v181, s[24:25]
	v_cndmask_b32_e64 v116, v116, v181, s[26:27]
	v_mul_f32_e32 v108, 0x3e38aa3b, v108
	v_mul_f32_e32 v109, 0x3e38aa3b, v109
	v_cmp_gt_u32_e64 s[6:7], s39, v117
	v_add_u32_e32 v117, 0x41, v166
	v_max3_f32 v70, v70, v106, v116
	v_cndmask_b32_e64 v108, v108, v181, s[28:29]
	v_cndmask_b32_e64 v109, v109, v181, s[30:31]
	v_mul_f32_e32 v110, 0x3e38aa3b, v110
	v_mul_f32_e32 v111, 0x3e38aa3b, v111
	v_cmp_gt_u32_e64 s[8:9], s39, v117
	v_add_u32_e32 v117, 64, v166
	v_max3_f32 v70, v70, v108, v109
	v_cndmask_b32_e64 v110, v110, v181, s[34:35]
	v_cndmask_b32_e64 v111, v111, v181, s[36:37]
	v_mul_f32_e32 v112, 0x3e38aa3b, v112
	s_and_b64 vcc, s[74:75], vcc
	v_mul_f32_e32 v113, 0x3e38aa3b, v113
	s_and_b64 s[6:7], s[74:75], s[6:7]
	v_cmp_gt_u32_e64 s[10:11], s39, v117
	v_max3_f32 v70, v70, v110, v111
	v_cndmask_b32_e32 v112, v112, v181, vcc
	v_cndmask_b32_e64 v113, v113, v181, s[6:7]
	v_mul_f32_e32 v114, 0x3e38aa3b, v114
	s_and_b64 s[8:9], s[74:75], s[8:9]
	v_mul_f32_e32 v115, 0x3e38aa3b, v115
	s_and_b64 s[10:11], s[74:75], s[10:11]
	v_max3_f32 v70, v70, v112, v113
	v_cndmask_b32_e64 v114, v114, v181, s[8:9]
	v_cndmask_b32_e64 v118, v115, v181, s[10:11]
	v_max3_f32 v70, v70, v114, v118
	v_mov_b32_e32 v115, v70
	s_nop 1
	v_permlane16_swap_b32_e32 v70, v115
	v_max_f32_e32 v70, v70, v115
	v_mov_b32_e32 v115, v70
	s_nop 1
	v_permlane32_swap_b32_e32 v70, v115
	v_max3_f32 v140, v73, v70, v115
	v_sub_f32_e32 v68, v68, v140
	v_exp_f32_e32 v139, v68
	v_sub_f32_e32 v68, v69, v140
	v_exp_f32_e32 v137, v68
	v_sub_f32_e32 v68, v71, v140
	v_exp_f32_e32 v135, v68
	v_sub_f32_e32 v68, v72, v140
	v_exp_f32_e32 v133, v68
	v_sub_f32_e32 v68, v74, v140
	v_exp_f32_e32 v131, v68
	v_sub_f32_e32 v68, v75, v140
	v_exp_f32_e32 v129, v68
	v_sub_f32_e32 v68, v106, v140
	v_exp_f32_e32 v127, v68
	v_sub_f32_e32 v68, v116, v140
	v_exp_f32_e32 v125, v68
	v_sub_f32_e32 v68, v108, v140
	v_add_u32_e32 v108, 0x83, v166
	v_cmp_gt_u32_e64 s[40:41], s39, v108
	v_mul_f32_e32 v76, 0x3e38aa3b, v76
	s_and_b64 s[40:41], s[74:75], s[40:41]
	v_add_u32_e32 v108, 0x82, v166
	v_exp_f32_e32 v123, v68
	v_sub_f32_e32 v68, v109, v140
	v_cndmask_b32_e64 v76, v76, v181, s[40:41]
	v_cmp_gt_u32_e64 s[40:41], s39, v108
	v_exp_f32_e32 v121, v68
	v_sub_f32_e32 v68, v110, v140
	v_mul_f32_e32 v77, 0x3e38aa3b, v77
	s_and_b64 s[40:41], s[74:75], s[40:41]
	v_add_u32_e32 v110, 0x81, v166
	v_cndmask_b32_e64 v77, v77, v181, s[40:41]
	v_cmp_gt_u32_e64 s[40:41], s39, v110
	v_mul_f32_e32 v78, 0x3e38aa3b, v78
	s_and_b64 s[40:41], s[74:75], s[40:41]
	v_cndmask_b32_e64 v110, v78, v181, s[40:41]
	v_mul_f32_e32 v78, 0x3e38aa3b, v79
	v_add_u32_e32 v79, 0x80, v166
	v_cmp_gt_u32_e64 s[40:41], s39, v79
	s_and_b64 s[40:41], s[74:75], s[40:41]
	v_max3_f32 v108, v76, s68, v77
	v_cndmask_b32_e64 v79, v78, v181, s[40:41]
	v_mul_f32_e32 v80, 0x3e38aa3b, v80
	v_mul_f32_e32 v81, 0x3e38aa3b, v81
	v_exp_f32_e32 v119, v68
	v_sub_f32_e32 v68, v111, v140
	v_max3_f32 v78, v108, v110, v79
	v_cndmask_b32_e64 v80, v80, v181, s[12:13]
	v_cndmask_b32_e64 v81, v81, v181, s[14:15]
	v_mul_f32_e32 v82, 0x3e38aa3b, v82
	v_mul_f32_e32 v83, 0x3e38aa3b, v83
	v_exp_f32_e32 v115, v68
	v_sub_f32_e32 v68, v112, v140
	v_max3_f32 v78, v78, v80, v81
	v_cndmask_b32_e64 v82, v82, v181, s[16:17]
	v_cndmask_b32_e64 v83, v83, v181, s[18:19]
	v_mul_f32_e32 v84, 0x3e38aa3b, v84
	v_mul_f32_e32 v85, 0x3e38aa3b, v85
	v_exp_f32_e32 v111, v68
	v_sub_f32_e32 v68, v113, v140
	v_max3_f32 v78, v78, v82, v83
	v_cndmask_b32_e64 v84, v84, v181, s[20:21]
	v_cndmask_b32_e64 v85, v85, v181, s[22:23]
	v_mul_f32_e32 v86, 0x3e38aa3b, v86
	v_mul_f32_e32 v87, 0x3e38aa3b, v87
	v_exp_f32_e32 v109, v68
	v_sub_f32_e32 v68, v114, v140
	v_max3_f32 v78, v78, v84, v85
	v_cndmask_b32_e64 v86, v86, v181, s[24:25]
	v_cndmask_b32_e64 v87, v87, v181, s[26:27]
	v_mul_f32_e32 v108, 0x3e38aa3b, v142
	v_mul_f32_e32 v112, 0x3e38aa3b, v143
	v_mul_f32_e32 v114, 0x3e38aa3b, v144
	v_max3_f32 v78, v78, v86, v87
	v_cndmask_b32_e64 v108, v108, v181, s[28:29]
	v_cndmask_b32_e64 v112, v112, v181, s[30:31]
	v_cndmask_b32_e64 v116, v114, v181, s[34:35]
	v_mul_f32_e32 v114, 0x3e38aa3b, v145
	v_max3_f32 v78, v78, v108, v112
	v_cndmask_b32_e64 v141, v114, v181, s[36:37]
	v_max3_f32 v78, v78, v116, v141
	v_mov_b32_e32 v114, v78
	s_nop 1
	v_permlane16_swap_b32_e32 v78, v114
	v_max_f32_e32 v78, v78, v114
	v_mov_b32_e32 v114, v78
	s_nop 1
	v_permlane32_swap_b32_e32 v78, v114
	v_max3_f32 v78, v167, v78, v114
	v_sub_f32_e32 v76, v76, v78
	v_exp_f32_e32 v138, v76
	v_sub_f32_e32 v76, v77, v78
	v_exp_f32_e32 v136, v76
	v_sub_f32_e32 v76, v110, v78
	v_exp_f32_e32 v134, v76
	v_sub_f32_e32 v76, v79, v78
	v_exp_f32_e32 v132, v76
	v_sub_f32_e32 v76, v80, v78
	v_exp_f32_e32 v130, v76
	v_sub_f32_e32 v76, v81, v78
	v_exp_f32_e32 v128, v76
	v_sub_f32_e32 v76, v82, v78
	v_exp_f32_e32 v126, v76
	v_sub_f32_e32 v76, v83, v78
	v_exp_f32_e32 v124, v76
	v_sub_f32_e32 v76, v84, v78
	v_exp_f32_e32 v122, v76
	v_sub_f32_e32 v76, v85, v78
	v_exp_f32_e32 v120, v76
	v_sub_f32_e32 v76, v86, v78
	v_exp_f32_e32 v117, v68
	v_sub_f32_e32 v68, v118, v140
	v_exp_f32_e32 v118, v76
	v_sub_f32_e32 v76, v87, v78
	v_exp_f32_e32 v114, v76
	v_sub_f32_e32 v76, v108, v78
	v_sub_f32_e32 v77, v116, v78
	v_sub_f32_e32 v70, v73, v140
	v_sub_f32_e32 v142, v167, v78
	v_exp_f32_e32 v110, v76
	v_sub_f32_e32 v76, v112, v78
	v_exp_f32_e32 v116, v77
	v_sub_f32_e32 v77, v141, v78
	v_exp_f32_e32 v106, v70
	v_exp_f32_e32 v113, v68
	v_exp_f32_e32 v108, v76
	v_exp_f32_e32 v76, v142
	v_exp_f32_e32 v112, v77
	v_pk_mul_f32 v[58:59], v[58:59], v[106:107] op_sel_hi:[1,0]
	v_pk_mul_f32 v[56:57], v[56:57], v[106:107] op_sel_hi:[1,0]
	v_pk_mul_f32 v[54:55], v[54:55], v[106:107] op_sel_hi:[1,0]
	v_pk_mul_f32 v[52:53], v[52:53], v[106:107] op_sel_hi:[1,0]
	v_pk_mul_f32 v[62:63], v[62:63], v[106:107] op_sel_hi:[1,0]
	v_pk_mul_f32 v[60:61], v[60:61], v[106:107] op_sel_hi:[1,0]
	v_pk_mul_f32 v[70:71], v[66:67], v[106:107] op_sel_hi:[1,0]
	v_pk_mul_f32 v[68:69], v[64:65], v[106:107] op_sel_hi:[1,0]
	v_cvt_pk_bf16_f32 v72, v139, v137
	v_cvt_pk_bf16_f32 v73, v135, v133
	v_cvt_pk_bf16_f32 v74, v131, v129
	v_cvt_pk_bf16_f32 v75, v127, v125
	v_cvt_pk_bf16_f32 v64, v123, v121
	v_cvt_pk_bf16_f32 v65, v119, v115
	v_cvt_pk_bf16_f32 v66, v111, v109
	v_cvt_pk_bf16_f32 v67, v117, v113
	v_pk_mul_f32 v[42:43], v[42:43], v[76:77] op_sel_hi:[1,0]
	v_pk_mul_f32 v[40:41], v[40:41], v[76:77] op_sel_hi:[1,0]
	v_pk_mul_f32 v[38:39], v[38:39], v[76:77] op_sel_hi:[1,0]
	v_pk_mul_f32 v[36:37], v[36:37], v[76:77] op_sel_hi:[1,0]
	v_pk_mul_f32 v[46:47], v[46:47], v[76:77] op_sel_hi:[1,0]
	v_pk_mul_f32 v[44:45], v[44:45], v[76:77] op_sel_hi:[1,0]
	v_pk_mul_f32 v[50:51], v[50:51], v[76:77] op_sel_hi:[1,0]
	v_pk_mul_f32 v[48:49], v[48:49], v[76:77] op_sel_hi:[1,0]
	v_cvt_pk_bf16_f32 v80, v138, v136
	v_cvt_pk_bf16_f32 v81, v134, v132
	v_cvt_pk_bf16_f32 v82, v130, v128
	v_cvt_pk_bf16_f32 v83, v126, v124
	v_cvt_pk_bf16_f32 v84, v122, v120
	v_cvt_pk_bf16_f32 v85, v118, v114
	v_cvt_pk_bf16_f32 v86, v110, v108
	v_cvt_pk_bf16_f32 v87, v116, v112
	s_nop 0
	v_add3_u32 v77, s83, v164, v165
	ds_read_b64_tr_b16 v[206:207], v77 offset:20992
	ds_read_b64_tr_b16 v[204:205], v77 offset:18432
	ds_read_b64_tr_b16 v[208:209], v77 offset:18464
	ds_read_b64_tr_b16 v[210:211], v77 offset:21024
	ds_read_b64_tr_b16 v[212:213], v77 offset:23552
	ds_read_b64_tr_b16 v[214:215], v77 offset:26112
	ds_read_b64_tr_b16 v[216:217], v77 offset:23584
	ds_read_b64_tr_b16 v[218:219], v77 offset:26144
	ds_read_b64_tr_b16 v[220:221], v77 offset:18496
	ds_read_b64_tr_b16 v[222:223], v77 offset:21056
	ds_read_b64_tr_b16 v[224:225], v77 offset:23616
	ds_read_b64_tr_b16 v[226:227], v77 offset:26176
	ds_read_b64_tr_b16 v[228:229], v77 offset:18528
	ds_read_b64_tr_b16 v[230:231], v77 offset:21088
	ds_read_b64_tr_b16 v[232:233], v77 offset:23648
	ds_read_b64_tr_b16 v[234:235], v77 offset:26208
	s_waitcnt lgkmcnt(14)
	v_mfma_f32_16x16x32_bf16 v[56:59], v[204:207], v[72:75], v[56:59]
	v_mfma_f32_16x16x32_bf16 v[40:43], v[204:207], v[80:83], v[40:43]
	s_waitcnt lgkmcnt(10)
	v_mfma_f32_16x16x32_bf16 v[56:59], v[212:215], v[64:67], v[56:59]
	v_mfma_f32_16x16x32_bf16 v[40:43], v[212:215], v[84:87], v[40:43]
	v_mfma_f32_16x16x32_bf16 v[52:55], v[208:211], v[72:75], v[52:55]
	v_mfma_f32_16x16x32_bf16 v[36:39], v[208:211], v[80:83], v[36:39]
	s_waitcnt lgkmcnt(8)
	v_mfma_f32_16x16x32_bf16 v[52:55], v[216:219], v[64:67], v[52:55]
	v_mfma_f32_16x16x32_bf16 v[36:39], v[216:219], v[84:87], v[36:39]
	s_waitcnt lgkmcnt(6)
	v_mfma_f32_16x16x32_bf16 v[60:63], v[220:223], v[72:75], v[60:63]
	v_mfma_f32_16x16x32_bf16 v[44:47], v[220:223], v[80:83], v[44:47]
	s_waitcnt lgkmcnt(4)
	v_mfma_f32_16x16x32_bf16 v[60:63], v[224:227], v[64:67], v[60:63]
	v_mfma_f32_16x16x32_bf16 v[44:47], v[224:227], v[84:87], v[44:47]
	s_waitcnt lgkmcnt(2)
	v_mfma_f32_16x16x32_bf16 v[68:71], v[228:231], v[72:75], v[68:71]
	v_mfma_f32_16x16x32_bf16 v[48:51], v[228:231], v[80:83], v[48:51]
	s_waitcnt lgkmcnt(0)
	v_mfma_f32_16x16x32_bf16 v[64:67], v[232:235], v[64:67], v[68:71]
	v_mfma_f32_16x16x32_bf16 v[48:51], v[232:235], v[84:87], v[48:51]
	s_nop 3
	s_nop 0
	s_nop 0
	ds_read_b128 v[204:207], v88 offset:9216
	ds_read_b128 v[208:211], v88 offset:9280
	ds_read_b128 v[212:215], v88 offset:11520
	ds_read_b128 v[216:219], v88 offset:13824
	ds_read_b128 v[220:223], v88 offset:16128
	ds_read_b128 v[224:227], v88 offset:11584
	ds_read_b128 v[228:231], v88 offset:13888
	ds_read_b128 v[232:235], v88 offset:16192
	s_waitcnt lgkmcnt(7)
	v_mfma_f32_16x16x32_bf16 v[72:75], v[204:207], v[4:7], v[0:3]
	v_mfma_f32_16x16x32_bf16 v[68:71], v[204:207], v[12:15], v[0:3]
	s_waitcnt lgkmcnt(6)
	v_mfma_f32_16x16x32_bf16 v[168:171], v[208:211], v[16:19], v[68:71]
	v_mfma_f32_16x16x32_bf16 v[72:75], v[208:211], v[8:11], v[72:75]
	s_waitcnt lgkmcnt(5)
	v_mfma_f32_16x16x32_bf16 v[84:87], v[212:215], v[4:7], v[0:3]
	v_mfma_f32_16x16x32_bf16 v[80:83], v[212:215], v[12:15], v[0:3]
	s_waitcnt lgkmcnt(2)
	v_mfma_f32_16x16x32_bf16 v[84:87], v[224:227], v[8:11], v[84:87]
	v_mfma_f32_16x16x32_bf16 v[184:187], v[224:227], v[16:19], v[80:83]
	v_mfma_f32_16x16x32_bf16 v[146:149], v[216:219], v[4:7], v[0:3]
	v_mfma_f32_16x16x32_bf16 v[142:145], v[216:219], v[12:15], v[0:3]
	s_waitcnt lgkmcnt(1)
	v_mfma_f32_16x16x32_bf16 v[80:83], v[228:231], v[8:11], v[146:149]
	v_mfma_f32_16x16x32_bf16 v[188:191], v[228:231], v[16:19], v[142:145]
	v_mfma_f32_16x16x32_bf16 v[154:157], v[220:223], v[4:7], v[0:3]
	v_mfma_f32_16x16x32_bf16 v[150:153], v[220:223], v[12:15], v[0:3]
	s_waitcnt lgkmcnt(0)
	v_mfma_f32_16x16x32_bf16 v[142:145], v[232:235], v[8:11], v[154:157]
	v_mfma_f32_16x16x32_bf16 v[192:195], v[232:235], v[16:19], v[150:153]
	s_nop 0
	s_nop 0
	v_mul_f32_e32 v68, 0x3e38aa3b, v72
	v_add_u32_e32 v69, 51, v166
	v_mul_f32_e32 v71, 0x3e38aa3b, v74
	v_add_u32_e32 v72, 49, v166
	v_add_u32_e32 v74, 35, v166
	v_cmp_gt_u32_e64 s[12:13], s39, v69
	v_mul_f32_e32 v69, 0x3e38aa3b, v73
	v_cmp_gt_u32_e64 s[16:17], s39, v72
	v_mul_f32_e32 v72, 0x3e38aa3b, v75
	v_add_u32_e32 v73, 48, v166
	v_cmp_gt_u32_e64 s[20:21], s39, v74
	v_add_u32_e32 v75, 34, v166
	v_cmp_gt_u32_e64 s[18:19], s39, v73
	v_mul_f32_e32 v73, 0x3e38aa3b, v84
	s_and_b64 s[20:21], s[74:75], s[20:21]
	v_cmp_gt_u32_e64 s[22:23], s39, v75
	v_add_u32_e32 v79, 33, v166
	v_cndmask_b32_e64 v74, v73, v181, s[20:21]
	v_mul_f32_e32 v73, 0x3e38aa3b, v85
	s_and_b64 s[22:23], s[74:75], s[22:23]
	v_cmp_gt_u32_e64 s[24:25], s39, v79
	v_add_u32_e32 v84, 32, v166
	v_cndmask_b32_e64 v75, v73, v181, s[22:23]
	v_mul_f32_e32 v73, 0x3e38aa3b, v86
	s_and_b64 s[24:25], s[74:75], s[24:25]
	v_cmp_gt_u32_e64 s[26:27], s39, v84
	v_cndmask_b32_e64 v79, v73, v181, s[24:25]
	v_mul_f32_e32 v73, 0x3e38aa3b, v87
	s_and_b64 s[26:27], s[74:75], s[26:27]
	v_cndmask_b32_e64 v84, v73, v181, s[26:27]
	v_mul_f32_e32 v73, 0x3e38aa3b, v80
	v_add_u32_e32 v80, 19, v166
	v_cmp_gt_u32_e64 s[28:29], s39, v80
	s_and_b64 s[28:29], s[74:75], s[28:29]
	v_add_u32_e32 v70, 50, v166
	v_cndmask_b32_e64 v80, v73, v181, s[28:29]
	v_mul_f32_e32 v73, 0x3e38aa3b, v81
	v_add_u32_e32 v81, 18, v166
	v_cmp_gt_u32_e64 s[30:31], s39, v81
	s_and_b64 s[30:31], s[74:75], s[30:31]
	v_cmp_gt_u32_e64 s[14:15], s39, v70
	v_cndmask_b32_e64 v81, v73, v181, s[30:31]
	v_mul_f32_e32 v73, 0x3e38aa3b, v82
	v_add_u32_e32 v82, 17, v166
	v_cmp_gt_u32_e64 s[34:35], s39, v82
	s_and_b64 s[34:35], s[74:75], s[34:35]
	v_add_u32_e32 v85, 3, v166
	v_cndmask_b32_e64 v82, v73, v181, s[34:35]
	v_mul_f32_e32 v73, 0x3e38aa3b, v83
	v_add_u32_e32 v83, 16, v166
	v_cmp_gt_u32_e64 s[36:37], s39, v83
	s_and_b64 s[12:13], s[74:75], s[12:13]
	s_and_b64 s[14:15], s[74:75], s[14:15]
	s_and_b64 s[36:37], s[74:75], s[36:37]
	v_cmp_gt_u32_e64 s[40:41], s39, v85
	v_cndmask_b32_e64 v68, v68, v181, s[12:13]
	v_cndmask_b32_e64 v69, v69, v181, s[14:15]
	s_and_b64 s[16:17], s[74:75], s[16:17]
	s_and_b64 s[18:19], s[74:75], s[18:19]
	v_cndmask_b32_e64 v83, v73, v181, s[36:37]
	v_mul_f32_e32 v73, 0x3e38aa3b, v142
	s_and_b64 s[40:41], s[74:75], s[40:41]
	v_add_u32_e32 v86, 2, v166
	v_max3_f32 v70, v68, s68, v69
	v_cndmask_b32_e64 v71, v71, v181, s[16:17]
	v_cndmask_b32_e64 v72, v72, v181, s[18:19]
	v_cndmask_b32_e64 v85, v73, v181, s[40:41]
	v_cmp_gt_u32_e64 s[40:41], s39, v86
	v_max3_f32 v70, v70, v71, v72
	v_mul_f32_e32 v73, 0x3e38aa3b, v143
	s_and_b64 s[40:41], s[74:75], s[40:41]
	v_add_u32_e32 v87, 1, v166
	v_max3_f32 v70, v70, v74, v75
	v_cndmask_b32_e64 v86, v73, v181, s[40:41]
	v_cmp_gt_u32_e64 s[40:41], s39, v87
	v_max3_f32 v70, v70, v79, v84
	v_mul_f32_e32 v73, 0x3e38aa3b, v144
	s_and_b64 s[40:41], s[74:75], s[40:41]
	v_max3_f32 v70, v70, v80, v81
	v_cndmask_b32_e64 v88, v73, v181, s[40:41]
	v_cmp_gt_u32_e64 s[40:41], s39, v166
	v_max3_f32 v70, v70, v82, v83
	v_mul_f32_e32 v73, 0x3e38aa3b, v145
	s_and_b64 s[40:41], s[74:75], s[40:41]
	v_max3_f32 v70, v70, v85, v86
	v_cndmask_b32_e64 v142, v73, v181, s[40:41]
	v_max3_f32 v70, v70, v88, v142
	v_mov_b32_e32 v73, v70
	s_nop 1
	v_permlane16_swap_b32_e32 v70, v73
	v_max_f32_e32 v70, v70, v73
	v_mov_b32_e32 v73, v70
	s_nop 1
	v_permlane32_swap_b32_e32 v70, v73
	v_max3_f32 v73, v140, v70, v73
	v_sub_f32_e32 v68, v68, v73
	v_exp_f32_e32 v159, v68
	v_sub_f32_e32 v68, v69, v73
	v_exp_f32_e32 v157, v68
	v_sub_f32_e32 v68, v71, v73
	v_exp_f32_e32 v155, v68
	v_sub_f32_e32 v68, v72, v73
	v_exp_f32_e32 v153, v68
	v_sub_f32_e32 v68, v74, v73
	v_exp_f32_e32 v151, v68
	v_sub_f32_e32 v68, v75, v73
	v_exp_f32_e32 v149, v68
	v_sub_f32_e32 v68, v79, v73
	v_exp_f32_e32 v147, v68
	v_sub_f32_e32 v68, v84, v73
	v_exp_f32_e32 v145, v68
	v_sub_f32_e32 v68, v80, v73
	v_exp_f32_e32 v143, v68
	v_sub_f32_e32 v68, v81, v73
	v_exp_f32_e32 v141, v68
	v_sub_f32_e32 v68, v82, v73
	v_sub_f32_e32 v70, v140, v73
	v_exp_f32_e32 v87, v68
	v_sub_f32_e32 v68, v83, v73
	v_exp_f32_e32 v83, v68
	v_sub_f32_e32 v68, v85, v73
	v_exp_f32_e32 v72, v70
	v_exp_f32_e32 v79, v68
	v_sub_f32_e32 v68, v86, v73
	v_exp_f32_e32 v75, v68
	v_sub_f32_e32 v68, v88, v73
	v_exp_f32_e32 v85, v68
	v_sub_f32_e32 v68, v142, v73
	v_exp_f32_e32 v81, v68
	v_pk_mul_f32 v[68:69], v[64:65], v[72:73] op_sel_hi:[1,0]
	v_mul_f32_e32 v64, 0x3e38aa3b, v168
	v_cndmask_b32_e32 v74, v64, v181, vcc
	v_mul_f32_e32 v64, 0x3e38aa3b, v169
	v_cndmask_b32_e64 v80, v64, v181, s[6:7]
	v_mul_f32_e32 v64, 0x3e38aa3b, v170
	v_cndmask_b32_e64 v82, v64, v181, s[8:9]
	v_mul_f32_e32 v64, 0x3e38aa3b, v171
	v_cndmask_b32_e64 v84, v64, v181, s[10:11]
	v_mul_f32_e32 v64, 0x3e38aa3b, v184
	v_cndmask_b32_e64 v86, v64, v181, s[12:13]
	v_mul_f32_e32 v64, 0x3e38aa3b, v185
	v_cndmask_b32_e64 v88, v64, v181, s[14:15]
	v_mul_f32_e32 v64, 0x3e38aa3b, v186
	v_cndmask_b32_e64 v140, v64, v181, s[16:17]
	v_mul_f32_e32 v64, 0x3e38aa3b, v187
	v_cndmask_b32_e64 v142, v64, v181, s[18:19]
	v_mul_f32_e32 v64, 0x3e38aa3b, v188
	v_cndmask_b32_e64 v160, v64, v181, s[20:21]
	v_mul_f32_e32 v64, 0x3e38aa3b, v189
	v_cndmask_b32_e64 v161, v64, v181, s[22:23]
	v_mul_f32_e32 v64, 0x3e38aa3b, v190
	v_cndmask_b32_e64 v172, v64, v181, s[24:25]
	v_mul_f32_e32 v64, 0x3e38aa3b, v191
	v_cndmask_b32_e64 v173, v64, v181, s[26:27]
	v_mul_f32_e32 v64, 0x3e38aa3b, v192
	v_cndmask_b32_e64 v184, v64, v181, s[28:29]
	v_mul_f32_e32 v64, 0x3e38aa3b, v193
	v_cndmask_b32_e64 v185, v64, v181, s[30:31]
	v_mul_f32_e32 v64, 0x3e38aa3b, v194
	v_cndmask_b32_e64 v186, v64, v181, s[34:35]
	v_mul_f32_e32 v64, 0x3e38aa3b, v195
	v_cndmask_b32_e64 v187, v64, v181, s[36:37]
	v_max3_f32 v64, v74, s68, v80
	v_max3_f32 v64, v64, v82, v84
	v_max3_f32 v64, v64, v86, v88
	v_max3_f32 v64, v64, v140, v142
	v_max3_f32 v64, v64, v160, v161
	v_max3_f32 v64, v64, v172, v173
	v_max3_f32 v144, v64, v184, v185
	v_max3_f32 v144, v144, v186, v187
	v_mov_b32_e32 v146, v144
	s_nop 1
	v_permlane16_swap_b32_e32 v144, v146
	v_max_f32_e32 v144, v144, v146
	v_mov_b32_e32 v146, v144
	s_nop 1
	v_permlane32_swap_b32_e32 v144, v146
	v_max3_f32 v167, v78, v144, v146
	v_sub_f32_e32 v74, v74, v167
	v_exp_f32_e32 v158, v74
	v_sub_f32_e32 v74, v80, v167
	v_exp_f32_e32 v156, v74
	v_sub_f32_e32 v74, v82, v167
	v_exp_f32_e32 v154, v74
	v_sub_f32_e32 v74, v84, v167
	v_exp_f32_e32 v152, v74
	v_sub_f32_e32 v74, v86, v167
	v_exp_f32_e32 v150, v74
	v_sub_f32_e32 v74, v88, v167
	v_exp_f32_e32 v148, v74
	v_sub_f32_e32 v74, v140, v167
	v_exp_f32_e32 v146, v74
	v_sub_f32_e32 v74, v142, v167
	v_exp_f32_e32 v144, v74
	v_sub_f32_e32 v74, v160, v167
	v_exp_f32_e32 v142, v74
	v_sub_f32_e32 v74, v161, v167
	v_exp_f32_e32 v140, v74
	v_sub_f32_e32 v74, v172, v167
	v_exp_f32_e32 v86, v74
	v_sub_f32_e32 v74, v173, v167
	v_sub_f32_e32 v188, v78, v167
	v_exp_f32_e32 v82, v74
	v_sub_f32_e32 v74, v184, v167
	v_sub_f32_e32 v80, v186, v167
	v_exp_f32_e32 v78, v74
	v_sub_f32_e32 v74, v185, v167
	v_exp_f32_e32 v160, v188
	v_exp_f32_e32 v84, v80
	v_sub_f32_e32 v80, v187, v167
	v_exp_f32_e32 v74, v74
	v_exp_f32_e32 v80, v80
	v_pk_mul_f32 v[58:59], v[58:59], v[72:73] op_sel_hi:[1,0]
	v_pk_mul_f32 v[56:57], v[56:57], v[72:73] op_sel_hi:[1,0]
	v_pk_mul_f32 v[54:55], v[54:55], v[72:73] op_sel_hi:[1,0]
	v_pk_mul_f32 v[52:53], v[52:53], v[72:73] op_sel_hi:[1,0]
	v_pk_mul_f32 v[62:63], v[62:63], v[72:73] op_sel_hi:[1,0]
	v_pk_mul_f32 v[60:61], v[60:61], v[72:73] op_sel_hi:[1,0]
	v_pk_mul_f32 v[70:71], v[66:67], v[72:73] op_sel_hi:[1,0]
	v_cvt_pk_bf16_f32 v64, v143, v141
	v_cvt_pk_bf16_f32 v65, v87, v83
	v_cvt_pk_bf16_f32 v66, v79, v75
	v_cvt_pk_bf16_f32 v67, v85, v81
	v_pk_mul_f32 v[42:43], v[42:43], v[160:161] op_sel_hi:[1,0]
	v_pk_mul_f32 v[40:41], v[40:41], v[160:161] op_sel_hi:[1,0]
	v_pk_mul_f32 v[38:39], v[38:39], v[160:161] op_sel_hi:[1,0]
	v_pk_mul_f32 v[36:37], v[36:37], v[160:161] op_sel_hi:[1,0]
	v_pk_mul_f32 v[46:47], v[46:47], v[160:161] op_sel_hi:[1,0]
	v_pk_mul_f32 v[44:45], v[44:45], v[160:161] op_sel_hi:[1,0]
	v_pk_mul_f32 v[50:51], v[50:51], v[160:161] op_sel_hi:[1,0]
	v_pk_mul_f32 v[48:49], v[48:49], v[160:161] op_sel_hi:[1,0]
	v_cvt_pk_bf16_f32 v168, v159, v157
	v_cvt_pk_bf16_f32 v169, v155, v153
	v_cvt_pk_bf16_f32 v170, v151, v149
	v_cvt_pk_bf16_f32 v171, v147, v145
	v_cvt_pk_bf16_f32 v184, v158, v156
	v_cvt_pk_bf16_f32 v185, v154, v152
	v_cvt_pk_bf16_f32 v186, v150, v148
	v_cvt_pk_bf16_f32 v187, v146, v144
	v_cvt_pk_bf16_f32 v188, v142, v140
	v_cvt_pk_bf16_f32 v189, v86, v82
	v_cvt_pk_bf16_f32 v190, v78, v74
	v_cvt_pk_bf16_f32 v191, v84, v80
	s_nop 0
	ds_read_b64_tr_b16 v[206:207], v77 offset:31232
	ds_read_b64_tr_b16 v[204:205], v77 offset:28672
	ds_read_b64_tr_b16 v[208:209], v77 offset:28704
	ds_read_b64_tr_b16 v[210:211], v77 offset:31264
	ds_read_b64_tr_b16 v[212:213], v77 offset:33792
	ds_read_b64_tr_b16 v[214:215], v77 offset:36352
	ds_read_b64_tr_b16 v[216:217], v77 offset:33824
	ds_read_b64_tr_b16 v[218:219], v77 offset:36384
	ds_read_b64_tr_b16 v[220:221], v77 offset:28736
	ds_read_b64_tr_b16 v[222:223], v77 offset:31296
	ds_read_b64_tr_b16 v[224:225], v77 offset:33856
	ds_read_b64_tr_b16 v[226:227], v77 offset:36416
	ds_read_b64_tr_b16 v[228:229], v77 offset:28768
	ds_read_b64_tr_b16 v[230:231], v77 offset:31328
	ds_read_b64_tr_b16 v[232:233], v77 offset:33888
	ds_read_b64_tr_b16 v[234:235], v77 offset:36448
	s_waitcnt lgkmcnt(14)
	v_mfma_f32_16x16x32_bf16 v[56:59], v[204:207], v[168:171], v[56:59]
	v_mfma_f32_16x16x32_bf16 v[40:43], v[204:207], v[184:187], v[40:43]
	s_waitcnt lgkmcnt(10)
	v_mfma_f32_16x16x32_bf16 v[56:59], v[212:215], v[64:67], v[56:59]
	v_mfma_f32_16x16x32_bf16 v[40:43], v[212:215], v[188:191], v[40:43]
	v_mfma_f32_16x16x32_bf16 v[52:55], v[208:211], v[168:171], v[52:55]
	v_mfma_f32_16x16x32_bf16 v[36:39], v[208:211], v[184:187], v[36:39]
	s_waitcnt lgkmcnt(8)
	v_mfma_f32_16x16x32_bf16 v[52:55], v[216:219], v[64:67], v[52:55]
	v_mfma_f32_16x16x32_bf16 v[36:39], v[216:219], v[188:191], v[36:39]
	s_waitcnt lgkmcnt(6)
	v_mfma_f32_16x16x32_bf16 v[60:63], v[220:223], v[168:171], v[60:63]
	v_mfma_f32_16x16x32_bf16 v[44:47], v[220:223], v[184:187], v[44:47]
	s_waitcnt lgkmcnt(4)
	v_mfma_f32_16x16x32_bf16 v[60:63], v[224:227], v[64:67], v[60:63]
	v_mfma_f32_16x16x32_bf16 v[44:47], v[224:227], v[188:191], v[44:47]
	s_waitcnt lgkmcnt(2)
	v_mfma_f32_16x16x32_bf16 v[68:71], v[228:231], v[168:171], v[68:71]
	v_mfma_f32_16x16x32_bf16 v[48:51], v[228:231], v[184:187], v[48:51]
	s_waitcnt lgkmcnt(0)
	v_mfma_f32_16x16x32_bf16 v[64:67], v[232:235], v[64:67], v[68:71]
	v_mfma_f32_16x16x32_bf16 v[48:51], v[232:235], v[188:191], v[48:51]
	s_nop 3
	s_nop 0
	s_add_i32 s12, s82, 1
	s_cmp_ge_i32 s12, s44
	s_cbranch_scc1 .LBB0_3060
	s_bitcmp1_b32 s12, 0
	s_cselect_b32 s6, 0x9800, 0
	v_add3_u32 v71, s6, v99, v98
	v_add3_u32 v68, s6, v162, v98
	v_add3_u32 v69, s6, v107, v98
	v_add3_u32 v70, s6, v105, v98
	s_waitcnt vmcnt(0)
	ds_write_b128 v71, v[20:23]
	ds_write_b128 v70, v[24:27]
	ds_write_b128 v69, v[28:31] offset:18432
	ds_write_b128 v68, v[32:35] offset:18432

.Lnm1_entry:
	s_nop 0
	v_or_b32_e32 v68, s83, v94
	v_add_u32_e32 v88, v68, v163
	ds_read_b128 v[204:207], v88 offset:2304
	ds_read_b128 v[208:211], v88
	ds_read_b128 v[212:215], v88 offset:4608
	ds_read_b128 v[216:219], v88 offset:6912
	ds_read_b128 v[220:223], v88 offset:64
	ds_read_b128 v[224:227], v88 offset:2368
	ds_read_b128 v[228:231], v88 offset:4672
	ds_read_b128 v[232:235], v88 offset:6976
	s_waitcnt lgkmcnt(7)
	v_mfma_f32_16x16x32_bf16 v[82:85], v[204:207], v[4:7], v[0:3]
	v_mfma_f32_16x16x32_bf16 v[108:111], v[204:207], v[12:15], v[0:3]
	s_waitcnt lgkmcnt(5)
	v_mfma_f32_16x16x32_bf16 v[112:115], v[212:215], v[4:7], v[0:3]
	v_mfma_f32_16x16x32_bf16 v[116:119], v[212:215], v[12:15], v[0:3]
	s_waitcnt lgkmcnt(4)
	v_mfma_f32_16x16x32_bf16 v[120:123], v[216:219], v[4:7], v[0:3]
	v_mfma_f32_16x16x32_bf16 v[124:127], v[216:219], v[12:15], v[0:3]
	v_mfma_f32_16x16x32_bf16 v[74:77], v[208:211], v[4:7], v[0:3]
	v_mfma_f32_16x16x32_bf16 v[68:71], v[208:211], v[12:15], v[0:3]
	s_waitcnt lgkmcnt(3)
	v_mfma_f32_16x16x32_bf16 v[128:131], v[220:223], v[8:11], v[74:77]
	v_mfma_f32_16x16x32_bf16 v[76:79], v[220:223], v[16:19], v[68:71]
	s_waitcnt lgkmcnt(2)
	v_mfma_f32_16x16x32_bf16 v[132:135], v[224:227], v[8:11], v[82:85]
	v_mfma_f32_16x16x32_bf16 v[80:83], v[224:227], v[16:19], v[108:111]
	s_waitcnt lgkmcnt(1)
	v_mfma_f32_16x16x32_bf16 v[108:111], v[228:231], v[8:11], v[112:115]
	v_mfma_f32_16x16x32_bf16 v[84:87], v[228:231], v[16:19], v[116:119]
	s_waitcnt lgkmcnt(0)
	v_mfma_f32_16x16x32_bf16 v[112:115], v[232:235], v[8:11], v[120:123]
	v_mfma_f32_16x16x32_bf16 v[142:145], v[232:235], v[16:19], v[124:127]
	s_nop 1
	s_nop 0
	v_mul_f32_e32 v68, 0x3e38aa3b, v128
	v_mul_f32_e32 v69, 0x3e38aa3b, v129
	v_mul_f32_e32 v71, 0x3e38aa3b, v130
	v_mul_f32_e32 v72, 0x3e38aa3b, v131
	v_max3_f32 v70, v68, s68, v69
	v_mul_f32_e32 v74, 0x3e38aa3b, v132
	v_mul_f32_e32 v75, 0x3e38aa3b, v133
	v_max3_f32 v70, v70, v71, v72
	v_mul_f32_e32 v106, 0x3e38aa3b, v134
	v_mul_f32_e32 v116, 0x3e38aa3b, v135
	v_max3_f32 v70, v70, v74, v75
	v_mul_f32_e32 v108, 0x3e38aa3b, v108
	v_mul_f32_e32 v109, 0x3e38aa3b, v109
	v_max3_f32 v70, v70, v106, v116
	v_mul_f32_e32 v110, 0x3e38aa3b, v110
	v_mul_f32_e32 v111, 0x3e38aa3b, v111
	v_max3_f32 v70, v70, v108, v109
	v_mul_f32_e32 v112, 0x3e38aa3b, v112
	v_mul_f32_e32 v113, 0x3e38aa3b, v113
	v_max3_f32 v70, v70, v110, v111
	v_mul_f32_e32 v114, 0x3e38aa3b, v114
	v_mul_f32_e32 v115, 0x3e38aa3b, v115
	v_max3_f32 v70, v70, v112, v113
	v_mov_b32_e32 v118, v115
	v_max3_f32 v70, v70, v114, v118
	v_mov_b32_e32 v115, v70
	s_nop 1
	v_permlane16_swap_b32_e32 v70, v115
	v_max_f32_e32 v70, v70, v115
	v_mov_b32_e32 v115, v70
	s_nop 1
	v_permlane32_swap_b32_e32 v70, v115
	v_max3_f32 v140, v73, v70, v115
	v_sub_f32_e32 v68, v68, v140
	v_exp_f32_e32 v139, v68
	v_sub_f32_e32 v68, v69, v140
	v_exp_f32_e32 v137, v68
	v_sub_f32_e32 v68, v71, v140
	v_exp_f32_e32 v135, v68
	v_sub_f32_e32 v68, v72, v140
	v_exp_f32_e32 v133, v68
	v_sub_f32_e32 v68, v74, v140
	v_exp_f32_e32 v131, v68
	v_sub_f32_e32 v68, v75, v140
	v_exp_f32_e32 v129, v68
	v_sub_f32_e32 v68, v106, v140
	v_exp_f32_e32 v127, v68
	v_sub_f32_e32 v68, v116, v140
	v_exp_f32_e32 v125, v68
	v_sub_f32_e32 v68, v108, v140
	v_mul_f32_e32 v76, 0x3e38aa3b, v76
	v_exp_f32_e32 v123, v68
	v_sub_f32_e32 v68, v109, v140
	v_exp_f32_e32 v121, v68
	v_sub_f32_e32 v68, v110, v140
	v_mul_f32_e32 v77, 0x3e38aa3b, v77
	v_mul_f32_e32 v78, 0x3e38aa3b, v78
	v_mov_b32_e32 v110, v78
	v_mul_f32_e32 v78, 0x3e38aa3b, v79
	v_max3_f32 v108, v76, s68, v77
	v_mov_b32_e32 v79, v78
	v_mul_f32_e32 v80, 0x3e38aa3b, v80
	v_mul_f32_e32 v81, 0x3e38aa3b, v81
	v_exp_f32_e32 v119, v68
	v_sub_f32_e32 v68, v111, v140
	v_max3_f32 v78, v108, v110, v79
	v_mul_f32_e32 v82, 0x3e38aa3b, v82
	v_mul_f32_e32 v83, 0x3e38aa3b, v83
	v_exp_f32_e32 v115, v68
	v_sub_f32_e32 v68, v112, v140
	v_max3_f32 v78, v78, v80, v81
	v_mul_f32_e32 v84, 0x3e38aa3b, v84
	v_mul_f32_e32 v85, 0x3e38aa3b, v85
	v_exp_f32_e32 v111, v68
	v_sub_f32_e32 v68, v113, v140
	v_max3_f32 v78, v78, v82, v83
	v_mul_f32_e32 v86, 0x3e38aa3b, v86
	v_mul_f32_e32 v87, 0x3e38aa3b, v87
	v_exp_f32_e32 v109, v68
	v_sub_f32_e32 v68, v114, v140
	v_max3_f32 v78, v78, v84, v85
	v_mul_f32_e32 v108, 0x3e38aa3b, v142
	v_mul_f32_e32 v112, 0x3e38aa3b, v143
	v_mul_f32_e32 v114, 0x3e38aa3b, v144
	v_max3_f32 v78, v78, v86, v87
	v_mov_b32_e32 v116, v114
	v_mul_f32_e32 v114, 0x3e38aa3b, v145
	v_max3_f32 v78, v78, v108, v112
	v_mov_b32_e32 v141, v114
	v_max3_f32 v78, v78, v116, v141
	v_mov_b32_e32 v114, v78
	s_nop 1
	v_permlane16_swap_b32_e32 v78, v114
	v_max_f32_e32 v78, v78, v114
	v_mov_b32_e32 v114, v78
	s_nop 1
	v_permlane32_swap_b32_e32 v78, v114
	v_max3_f32 v78, v167, v78, v114
	v_sub_f32_e32 v76, v76, v78
	v_exp_f32_e32 v138, v76
	v_sub_f32_e32 v76, v77, v78
	v_exp_f32_e32 v136, v76
	v_sub_f32_e32 v76, v110, v78
	v_exp_f32_e32 v134, v76
	v_sub_f32_e32 v76, v79, v78
	v_exp_f32_e32 v132, v76
	v_sub_f32_e32 v76, v80, v78
	v_exp_f32_e32 v130, v76
	v_sub_f32_e32 v76, v81, v78
	v_exp_f32_e32 v128, v76
	v_sub_f32_e32 v76, v82, v78
	v_exp_f32_e32 v126, v76
	v_sub_f32_e32 v76, v83, v78
	v_exp_f32_e32 v124, v76
	v_sub_f32_e32 v76, v84, v78
	v_exp_f32_e32 v122, v76
	v_sub_f32_e32 v76, v85, v78
	v_exp_f32_e32 v120, v76
	v_sub_f32_e32 v76, v86, v78
	v_exp_f32_e32 v117, v68
	v_sub_f32_e32 v68, v118, v140
	v_exp_f32_e32 v118, v76
	v_sub_f32_e32 v76, v87, v78
	v_exp_f32_e32 v114, v76
	v_sub_f32_e32 v76, v108, v78
	v_sub_f32_e32 v77, v116, v78
	v_sub_f32_e32 v70, v73, v140
	v_sub_f32_e32 v142, v167, v78
	v_exp_f32_e32 v110, v76
	v_sub_f32_e32 v76, v112, v78
	v_exp_f32_e32 v116, v77
	v_sub_f32_e32 v77, v141, v78
	v_exp_f32_e32 v106, v70
	v_exp_f32_e32 v113, v68
	v_exp_f32_e32 v108, v76
	v_exp_f32_e32 v76, v142
	v_exp_f32_e32 v112, v77
	v_pk_mul_f32 v[58:59], v[58:59], v[106:107] op_sel_hi:[1,0]
	v_pk_mul_f32 v[56:57], v[56:57], v[106:107] op_sel_hi:[1,0]
	v_pk_mul_f32 v[54:55], v[54:55], v[106:107] op_sel_hi:[1,0]
	v_pk_mul_f32 v[52:53], v[52:53], v[106:107] op_sel_hi:[1,0]
	v_pk_mul_f32 v[62:63], v[62:63], v[106:107] op_sel_hi:[1,0]
	v_pk_mul_f32 v[60:61], v[60:61], v[106:107] op_sel_hi:[1,0]
	v_pk_mul_f32 v[70:71], v[66:67], v[106:107] op_sel_hi:[1,0]
	v_pk_mul_f32 v[68:69], v[64:65], v[106:107] op_sel_hi:[1,0]
	v_cvt_pk_bf16_f32 v72, v139, v137
	v_cvt_pk_bf16_f32 v73, v135, v133
	v_cvt_pk_bf16_f32 v74, v131, v129
	v_cvt_pk_bf16_f32 v75, v127, v125
	v_cvt_pk_bf16_f32 v64, v123, v121
	v_cvt_pk_bf16_f32 v65, v119, v115
	v_cvt_pk_bf16_f32 v66, v111, v109
	v_cvt_pk_bf16_f32 v67, v117, v113
	v_pk_mul_f32 v[42:43], v[42:43], v[76:77] op_sel_hi:[1,0]
	v_pk_mul_f32 v[40:41], v[40:41], v[76:77] op_sel_hi:[1,0]
	v_pk_mul_f32 v[38:39], v[38:39], v[76:77] op_sel_hi:[1,0]
	v_pk_mul_f32 v[36:37], v[36:37], v[76:77] op_sel_hi:[1,0]
	v_pk_mul_f32 v[46:47], v[46:47], v[76:77] op_sel_hi:[1,0]
	v_pk_mul_f32 v[44:45], v[44:45], v[76:77] op_sel_hi:[1,0]
	v_pk_mul_f32 v[50:51], v[50:51], v[76:77] op_sel_hi:[1,0]
	v_pk_mul_f32 v[48:49], v[48:49], v[76:77] op_sel_hi:[1,0]
	v_cvt_pk_bf16_f32 v80, v138, v136
	v_cvt_pk_bf16_f32 v81, v134, v132
	v_cvt_pk_bf16_f32 v82, v130, v128
	v_cvt_pk_bf16_f32 v83, v126, v124
	v_cvt_pk_bf16_f32 v84, v122, v120
	v_cvt_pk_bf16_f32 v85, v118, v114
	v_cvt_pk_bf16_f32 v86, v110, v108
	v_cvt_pk_bf16_f32 v87, v116, v112
	s_nop 0
	v_add3_u32 v77, s83, v164, v165
	ds_read_b64_tr_b16 v[206:207], v77 offset:20992
	ds_read_b64_tr_b16 v[204:205], v77 offset:18432
	ds_read_b64_tr_b16 v[208:209], v77 offset:18464
	ds_read_b64_tr_b16 v[210:211], v77 offset:21024
	ds_read_b64_tr_b16 v[212:213], v77 offset:23552
	ds_read_b64_tr_b16 v[214:215], v77 offset:26112
	ds_read_b64_tr_b16 v[216:217], v77 offset:23584
	ds_read_b64_tr_b16 v[218:219], v77 offset:26144
	ds_read_b64_tr_b16 v[220:221], v77 offset:18496
	ds_read_b64_tr_b16 v[222:223], v77 offset:21056
	ds_read_b64_tr_b16 v[224:225], v77 offset:23616
	ds_read_b64_tr_b16 v[226:227], v77 offset:26176
	ds_read_b64_tr_b16 v[228:229], v77 offset:18528
	ds_read_b64_tr_b16 v[230:231], v77 offset:21088
	ds_read_b64_tr_b16 v[232:233], v77 offset:23648
	ds_read_b64_tr_b16 v[234:235], v77 offset:26208
	s_waitcnt lgkmcnt(14)
	v_mfma_f32_16x16x32_bf16 v[56:59], v[204:207], v[72:75], v[56:59]
	v_mfma_f32_16x16x32_bf16 v[40:43], v[204:207], v[80:83], v[40:43]
	s_waitcnt lgkmcnt(10)
	v_mfma_f32_16x16x32_bf16 v[56:59], v[212:215], v[64:67], v[56:59]
	v_mfma_f32_16x16x32_bf16 v[40:43], v[212:215], v[84:87], v[40:43]
	v_mfma_f32_16x16x32_bf16 v[52:55], v[208:211], v[72:75], v[52:55]
	v_mfma_f32_16x16x32_bf16 v[36:39], v[208:211], v[80:83], v[36:39]
	s_waitcnt lgkmcnt(8)
	v_mfma_f32_16x16x32_bf16 v[52:55], v[216:219], v[64:67], v[52:55]
	v_mfma_f32_16x16x32_bf16 v[36:39], v[216:219], v[84:87], v[36:39]
	s_waitcnt lgkmcnt(6)
	v_mfma_f32_16x16x32_bf16 v[60:63], v[220:223], v[72:75], v[60:63]
	v_mfma_f32_16x16x32_bf16 v[44:47], v[220:223], v[80:83], v[44:47]
	s_waitcnt lgkmcnt(4)
	v_mfma_f32_16x16x32_bf16 v[60:63], v[224:227], v[64:67], v[60:63]
	v_mfma_f32_16x16x32_bf16 v[44:47], v[224:227], v[84:87], v[44:47]
	s_waitcnt lgkmcnt(2)
	v_mfma_f32_16x16x32_bf16 v[68:71], v[228:231], v[72:75], v[68:71]
	v_mfma_f32_16x16x32_bf16 v[48:51], v[228:231], v[80:83], v[48:51]
	s_waitcnt lgkmcnt(0)
	v_mfma_f32_16x16x32_bf16 v[64:67], v[232:235], v[64:67], v[68:71]
	v_mfma_f32_16x16x32_bf16 v[48:51], v[232:235], v[84:87], v[48:51]
	s_nop 3
	s_nop 0
	s_nop 0
	ds_read_b128 v[204:207], v88 offset:9216
	ds_read_b128 v[208:211], v88 offset:9280
	ds_read_b128 v[212:215], v88 offset:11520
	ds_read_b128 v[216:219], v88 offset:13824
	ds_read_b128 v[220:223], v88 offset:16128
	ds_read_b128 v[224:227], v88 offset:11584
	ds_read_b128 v[228:231], v88 offset:13888
	ds_read_b128 v[232:235], v88 offset:16192
	s_waitcnt lgkmcnt(7)
	v_mfma_f32_16x16x32_bf16 v[72:75], v[204:207], v[4:7], v[0:3]
	v_mfma_f32_16x16x32_bf16 v[68:71], v[204:207], v[12:15], v[0:3]
	s_waitcnt lgkmcnt(6)
	v_mfma_f32_16x16x32_bf16 v[168:171], v[208:211], v[16:19], v[68:71]
	v_mfma_f32_16x16x32_bf16 v[72:75], v[208:211], v[8:11], v[72:75]
	s_waitcnt lgkmcnt(5)
	v_mfma_f32_16x16x32_bf16 v[84:87], v[212:215], v[4:7], v[0:3]
	v_mfma_f32_16x16x32_bf16 v[80:83], v[212:215], v[12:15], v[0:3]
	s_waitcnt lgkmcnt(2)
	v_mfma_f32_16x16x32_bf16 v[84:87], v[224:227], v[8:11], v[84:87]
	v_mfma_f32_16x16x32_bf16 v[184:187], v[224:227], v[16:19], v[80:83]
	v_mfma_f32_16x16x32_bf16 v[146:149], v[216:219], v[4:7], v[0:3]
	v_mfma_f32_16x16x32_bf16 v[142:145], v[216:219], v[12:15], v[0:3]
	s_waitcnt lgkmcnt(1)
	v_mfma_f32_16x16x32_bf16 v[80:83], v[228:231], v[8:11], v[146:149]
	v_mfma_f32_16x16x32_bf16 v[188:191], v[228:231], v[16:19], v[142:145]
	v_mfma_f32_16x16x32_bf16 v[154:157], v[220:223], v[4:7], v[0:3]
	v_mfma_f32_16x16x32_bf16 v[150:153], v[220:223], v[12:15], v[0:3]
	s_waitcnt lgkmcnt(0)
	v_mfma_f32_16x16x32_bf16 v[142:145], v[232:235], v[8:11], v[154:157]
	v_mfma_f32_16x16x32_bf16 v[192:195], v[232:235], v[16:19], v[150:153]
	s_nop 0
	s_nop 0
	v_mul_f32_e32 v68, 0x3e38aa3b, v72
	v_mul_f32_e32 v71, 0x3e38aa3b, v74
	v_mul_f32_e32 v69, 0x3e38aa3b, v73
	v_mul_f32_e32 v72, 0x3e38aa3b, v75
	v_mul_f32_e32 v73, 0x3e38aa3b, v84
	v_mov_b32_e32 v74, v73
	v_mul_f32_e32 v73, 0x3e38aa3b, v85
	v_mov_b32_e32 v75, v73
	v_mul_f32_e32 v73, 0x3e38aa3b, v86
	v_mov_b32_e32 v79, v73
	v_mul_f32_e32 v73, 0x3e38aa3b, v87
	v_mov_b32_e32 v84, v73
	v_mul_f32_e32 v73, 0x3e38aa3b, v80
	v_mov_b32_e32 v80, v73
	v_mul_f32_e32 v73, 0x3e38aa3b, v81
	v_mov_b32_e32 v81, v73
	v_mul_f32_e32 v73, 0x3e38aa3b, v82
	v_mov_b32_e32 v82, v73
	v_mul_f32_e32 v73, 0x3e38aa3b, v83
	v_mov_b32_e32 v83, v73
	v_mul_f32_e32 v73, 0x3e38aa3b, v142
	v_max3_f32 v70, v68, s68, v69
	v_mov_b32_e32 v85, v73
	v_max3_f32 v70, v70, v71, v72
	v_mul_f32_e32 v73, 0x3e38aa3b, v143
	v_max3_f32 v70, v70, v74, v75
	v_mov_b32_e32 v86, v73
	v_max3_f32 v70, v70, v79, v84
	v_mul_f32_e32 v73, 0x3e38aa3b, v144
	v_max3_f32 v70, v70, v80, v81
	v_mov_b32_e32 v88, v73
	v_max3_f32 v70, v70, v82, v83
	v_mul_f32_e32 v73, 0x3e38aa3b, v145
	v_max3_f32 v70, v70, v85, v86
	v_mov_b32_e32 v142, v73
	v_max3_f32 v70, v70, v88, v142
	v_mov_b32_e32 v73, v70
	s_nop 1
	v_permlane16_swap_b32_e32 v70, v73
	v_max_f32_e32 v70, v70, v73
	v_mov_b32_e32 v73, v70
	s_nop 1
	v_permlane32_swap_b32_e32 v70, v73
	v_max3_f32 v73, v140, v70, v73
	v_sub_f32_e32 v68, v68, v73
	v_exp_f32_e32 v159, v68
	v_sub_f32_e32 v68, v69, v73
	v_exp_f32_e32 v157, v68
	v_sub_f32_e32 v68, v71, v73
	v_exp_f32_e32 v155, v68
	v_sub_f32_e32 v68, v72, v73
	v_exp_f32_e32 v153, v68
	v_sub_f32_e32 v68, v74, v73
	v_exp_f32_e32 v151, v68
	v_sub_f32_e32 v68, v75, v73
	v_exp_f32_e32 v149, v68
	v_sub_f32_e32 v68, v79, v73
	v_exp_f32_e32 v147, v68
	v_sub_f32_e32 v68, v84, v73
	v_exp_f32_e32 v145, v68
	v_sub_f32_e32 v68, v80, v73
	v_exp_f32_e32 v143, v68
	v_sub_f32_e32 v68, v81, v73
	v_exp_f32_e32 v141, v68
	v_sub_f32_e32 v68, v82, v73
	v_sub_f32_e32 v70, v140, v73
	v_exp_f32_e32 v87, v68
	v_sub_f32_e32 v68, v83, v73
	v_exp_f32_e32 v83, v68
	v_sub_f32_e32 v68, v85, v73
	v_exp_f32_e32 v72, v70
	v_exp_f32_e32 v79, v68
	v_sub_f32_e32 v68, v86, v73
	v_exp_f32_e32 v75, v68
	v_sub_f32_e32 v68, v88, v73
	v_exp_f32_e32 v85, v68
	v_sub_f32_e32 v68, v142, v73
	v_exp_f32_e32 v81, v68
	v_pk_mul_f32 v[68:69], v[64:65], v[72:73] op_sel_hi:[1,0]
	v_mul_f32_e32 v64, 0x3e38aa3b, v168
	v_mov_b32_e32 v74, v64
	v_mul_f32_e32 v64, 0x3e38aa3b, v169
	v_mov_b32_e32 v80, v64
	v_mul_f32_e32 v64, 0x3e38aa3b, v170
	v_mov_b32_e32 v82, v64
	v_mul_f32_e32 v64, 0x3e38aa3b, v171
	v_mov_b32_e32 v84, v64
	v_mul_f32_e32 v64, 0x3e38aa3b, v184
	v_mov_b32_e32 v86, v64
	v_mul_f32_e32 v64, 0x3e38aa3b, v185
	v_mov_b32_e32 v88, v64
	v_mul_f32_e32 v64, 0x3e38aa3b, v186
	v_mov_b32_e32 v140, v64
	v_mul_f32_e32 v64, 0x3e38aa3b, v187
	v_mov_b32_e32 v142, v64
	v_mul_f32_e32 v64, 0x3e38aa3b, v188
	v_mov_b32_e32 v160, v64
	v_mul_f32_e32 v64, 0x3e38aa3b, v189
	v_mov_b32_e32 v161, v64
	v_mul_f32_e32 v64, 0x3e38aa3b, v190
	v_mov_b32_e32 v172, v64
	v_mul_f32_e32 v64, 0x3e38aa3b, v191
	v_mov_b32_e32 v173, v64
	v_mul_f32_e32 v64, 0x3e38aa3b, v192
	v_mov_b32_e32 v184, v64
	v_mul_f32_e32 v64, 0x3e38aa3b, v193
	v_mov_b32_e32 v185, v64
	v_mul_f32_e32 v64, 0x3e38aa3b, v194
	v_mov_b32_e32 v186, v64
	v_mul_f32_e32 v64, 0x3e38aa3b, v195
	v_mov_b32_e32 v187, v64
	v_max3_f32 v64, v74, s68, v80
	v_max3_f32 v64, v64, v82, v84
	v_max3_f32 v64, v64, v86, v88
	v_max3_f32 v64, v64, v140, v142
	v_max3_f32 v64, v64, v160, v161
	v_max3_f32 v64, v64, v172, v173
	v_max3_f32 v144, v64, v184, v185
	v_max3_f32 v144, v144, v186, v187
	v_mov_b32_e32 v146, v144
	s_nop 1
	v_permlane16_swap_b32_e32 v144, v146
	v_max_f32_e32 v144, v144, v146
	v_mov_b32_e32 v146, v144
	s_nop 1
	v_permlane32_swap_b32_e32 v144, v146
	v_max3_f32 v167, v78, v144, v146
	v_sub_f32_e32 v74, v74, v167
	v_exp_f32_e32 v158, v74
	v_sub_f32_e32 v74, v80, v167
	v_exp_f32_e32 v156, v74
	v_sub_f32_e32 v74, v82, v167
	v_exp_f32_e32 v154, v74
	v_sub_f32_e32 v74, v84, v167
	v_exp_f32_e32 v152, v74
	v_sub_f32_e32 v74, v86, v167
	v_exp_f32_e32 v150, v74
	v_sub_f32_e32 v74, v88, v167
	v_exp_f32_e32 v148, v74
	v_sub_f32_e32 v74, v140, v167
	v_exp_f32_e32 v146, v74
	v_sub_f32_e32 v74, v142, v167
	v_exp_f32_e32 v144, v74
	v_sub_f32_e32 v74, v160, v167
	v_exp_f32_e32 v142, v74
	v_sub_f32_e32 v74, v161, v167
	v_exp_f32_e32 v140, v74
	v_sub_f32_e32 v74, v172, v167
	v_exp_f32_e32 v86, v74
	v_sub_f32_e32 v74, v173, v167
	v_sub_f32_e32 v188, v78, v167
	v_exp_f32_e32 v82, v74
	v_sub_f32_e32 v74, v184, v167
	v_sub_f32_e32 v80, v186, v167
	v_exp_f32_e32 v78, v74
	v_sub_f32_e32 v74, v185, v167
	v_exp_f32_e32 v160, v188
	v_exp_f32_e32 v84, v80
	v_sub_f32_e32 v80, v187, v167
	v_exp_f32_e32 v74, v74
	v_exp_f32_e32 v80, v80
	v_pk_mul_f32 v[58:59], v[58:59], v[72:73] op_sel_hi:[1,0]
	v_pk_mul_f32 v[56:57], v[56:57], v[72:73] op_sel_hi:[1,0]
	v_pk_mul_f32 v[54:55], v[54:55], v[72:73] op_sel_hi:[1,0]
	v_pk_mul_f32 v[52:53], v[52:53], v[72:73] op_sel_hi:[1,0]
	v_pk_mul_f32 v[62:63], v[62:63], v[72:73] op_sel_hi:[1,0]
	v_pk_mul_f32 v[60:61], v[60:61], v[72:73] op_sel_hi:[1,0]
	v_pk_mul_f32 v[70:71], v[66:67], v[72:73] op_sel_hi:[1,0]
	v_cvt_pk_bf16_f32 v64, v143, v141
	v_cvt_pk_bf16_f32 v65, v87, v83
	v_cvt_pk_bf16_f32 v66, v79, v75
	v_cvt_pk_bf16_f32 v67, v85, v81
	v_pk_mul_f32 v[42:43], v[42:43], v[160:161] op_sel_hi:[1,0]
	v_pk_mul_f32 v[40:41], v[40:41], v[160:161] op_sel_hi:[1,0]
	v_pk_mul_f32 v[38:39], v[38:39], v[160:161] op_sel_hi:[1,0]
	v_pk_mul_f32 v[36:37], v[36:37], v[160:161] op_sel_hi:[1,0]
	v_pk_mul_f32 v[46:47], v[46:47], v[160:161] op_sel_hi:[1,0]
	v_pk_mul_f32 v[44:45], v[44:45], v[160:161] op_sel_hi:[1,0]
	v_pk_mul_f32 v[50:51], v[50:51], v[160:161] op_sel_hi:[1,0]
	v_pk_mul_f32 v[48:49], v[48:49], v[160:161] op_sel_hi:[1,0]
	v_cvt_pk_bf16_f32 v168, v159, v157
	v_cvt_pk_bf16_f32 v169, v155, v153
	v_cvt_pk_bf16_f32 v170, v151, v149
	v_cvt_pk_bf16_f32 v171, v147, v145
	v_cvt_pk_bf16_f32 v184, v158, v156
	v_cvt_pk_bf16_f32 v185, v154, v152
	v_cvt_pk_bf16_f32 v186, v150, v148
	v_cvt_pk_bf16_f32 v187, v146, v144
	v_cvt_pk_bf16_f32 v188, v142, v140
	v_cvt_pk_bf16_f32 v189, v86, v82
	v_cvt_pk_bf16_f32 v190, v78, v74
	v_cvt_pk_bf16_f32 v191, v84, v80
	s_nop 0
	ds_read_b64_tr_b16 v[206:207], v77 offset:31232
	ds_read_b64_tr_b16 v[204:205], v77 offset:28672
	ds_read_b64_tr_b16 v[208:209], v77 offset:28704
	ds_read_b64_tr_b16 v[210:211], v77 offset:31264
	ds_read_b64_tr_b16 v[212:213], v77 offset:33792
	ds_read_b64_tr_b16 v[214:215], v77 offset:36352
	ds_read_b64_tr_b16 v[216:217], v77 offset:33824
	ds_read_b64_tr_b16 v[218:219], v77 offset:36384
	ds_read_b64_tr_b16 v[220:221], v77 offset:28736
	ds_read_b64_tr_b16 v[222:223], v77 offset:31296
	ds_read_b64_tr_b16 v[224:225], v77 offset:33856
	ds_read_b64_tr_b16 v[226:227], v77 offset:36416
	ds_read_b64_tr_b16 v[228:229], v77 offset:28768
	ds_read_b64_tr_b16 v[230:231], v77 offset:31328
	ds_read_b64_tr_b16 v[232:233], v77 offset:33888
	ds_read_b64_tr_b16 v[234:235], v77 offset:36448
	s_waitcnt lgkmcnt(14)
	v_mfma_f32_16x16x32_bf16 v[56:59], v[204:207], v[168:171], v[56:59]
	v_mfma_f32_16x16x32_bf16 v[40:43], v[204:207], v[184:187], v[40:43]
	s_waitcnt lgkmcnt(10)
	v_mfma_f32_16x16x32_bf16 v[56:59], v[212:215], v[64:67], v[56:59]
	v_mfma_f32_16x16x32_bf16 v[40:43], v[212:215], v[188:191], v[40:43]
	v_mfma_f32_16x16x32_bf16 v[52:55], v[208:211], v[168:171], v[52:55]
	v_mfma_f32_16x16x32_bf16 v[36:39], v[208:211], v[184:187], v[36:39]
	s_waitcnt lgkmcnt(8)
	v_mfma_f32_16x16x32_bf16 v[52:55], v[216:219], v[64:67], v[52:55]
	v_mfma_f32_16x16x32_bf16 v[36:39], v[216:219], v[188:191], v[36:39]
	s_waitcnt lgkmcnt(6)
	v_mfma_f32_16x16x32_bf16 v[60:63], v[220:223], v[168:171], v[60:63]
	v_mfma_f32_16x16x32_bf16 v[44:47], v[220:223], v[184:187], v[44:47]
	s_waitcnt lgkmcnt(4)
	v_mfma_f32_16x16x32_bf16 v[60:63], v[224:227], v[64:67], v[60:63]
	v_mfma_f32_16x16x32_bf16 v[44:47], v[224:227], v[188:191], v[44:47]
	s_waitcnt lgkmcnt(2)
	v_mfma_f32_16x16x32_bf16 v[68:71], v[228:231], v[168:171], v[68:71]
	v_mfma_f32_16x16x32_bf16 v[48:51], v[228:231], v[184:187], v[48:51]
	s_waitcnt lgkmcnt(0)
	v_mfma_f32_16x16x32_bf16 v[64:67], v[232:235], v[64:67], v[68:71]
	v_mfma_f32_16x16x32_bf16 v[48:51], v[232:235], v[188:191], v[48:51]
	s_nop 3
	s_nop 0
	s_add_i32 s12, s82, 1
	s_cmp_ge_i32 s12, s44
	s_cbranch_scc1 .Lnm1_b3060
	s_bitcmp1_b32 s12, 0
	s_cselect_b32 s6, 0x9800, 0
	v_add3_u32 v71, s6, v99, v98
	v_add3_u32 v68, s6, v162, v98
	v_add3_u32 v69, s6, v107, v98
	v_add3_u32 v70, s6, v105, v98
	s_waitcnt vmcnt(0)
	ds_write_b128 v71, v[20:23]
	ds_write_b128 v70, v[24:27]
	ds_write_b128 v69, v[28:31] offset:18432
	ds_write_b128 v68, v[32:35] offset:18432

.LBB0_3069:
	s_setprio 0
	v_mov_b32_e32 v4, v97
	s_nop 1
	v_permlane16_swap_b32_e32 v97, v4
	v_add_f32_e32 v4, v97, v4
	v_mov_b32_e32 v5, v4
	s_nop 1
	v_permlane32_swap_b32_e32 v4, v5
	v_add_f32_e32 v4, v4, v5
	v_div_scale_f32 v5, s[6:7], v4, v4, 1.0
	v_rcp_f32_e32 v6, v5
	v_mov_b32_e32 v105, v89
	s_lshl_b32 s44, s78, 1
	s_mov_b64 s[76:77], s[66:67]
	v_fma_f32 v7, -v5, v6, 1.0
	v_fmac_f32_e32 v6, v7, v6
	v_div_scale_f32 v7, vcc, 1.0, v4, 1.0
	v_mul_f32_e32 v8, v7, v6
	v_fma_f32 v9, -v5, v8, v7
	v_fmac_f32_e32 v8, v9, v6
	v_fma_f32 v5, -v5, v8, v7
	v_div_fmas_f32 v5, v5, v6, v8
	v_lshlrev_b64 v[6:7], 11, v[92:93]
	v_lshl_add_u64 v[6:7], s[42:43], 0, v[6:7]
	v_lshl_add_u64 v[6:7], v[6:7], 0, s[44:45]
	v_lshlrev_b64 v[8:9], 1, v[104:105]
	v_div_fixup_f32 v4, v5, v4, 1.0
	v_lshl_add_u64 v[6:7], v[6:7], 0, v[8:9]
	v_lshl_add_u64 v[10:11], v[6:7], 0, s[96:97]
	v_pk_mul_f32 v[12:13], v[56:57], v[4:5] op_sel_hi:[1,0]
	v_pk_mul_f32 v[14:15], v[58:59], v[4:5] op_sel_hi:[1,0]
	v_add_co_u32_e32 v6, vcc, s94, v6
	v_cvt_pk_bf16_f32 v12, v12, v13
	v_cvt_pk_bf16_f32 v13, v14, v15
	v_addc_co_u32_e32 v7, vcc, 0, v7, vcc
	flat_store_dwordx2 v[6:7], v[12:13] offset:512
	v_pk_mul_f32 v[6:7], v[52:53], v[4:5] op_sel_hi:[1,0]
	v_pk_mul_f32 v[12:13], v[54:55], v[4:5] op_sel_hi:[1,0]
	v_cvt_pk_bf16_f32 v6, v6, v7
	v_cvt_pk_bf16_f32 v7, v12, v13
	flat_store_dwordx2 v[10:11], v[6:7] offset:32
	v_pk_mul_f32 v[6:7], v[60:61], v[4:5] op_sel_hi:[1,0]
	v_pk_mul_f32 v[12:13], v[62:63], v[4:5] op_sel_hi:[1,0]
	v_cvt_pk_bf16_f32 v6, v6, v7
	v_cvt_pk_bf16_f32 v7, v12, v13
	flat_store_dwordx2 v[10:11], v[6:7] offset:64
	v_pk_mul_f32 v[6:7], v[64:65], v[4:5] op_sel_hi:[1,0]
	v_mov_b32_e32 v5, v96
	s_nop 1
	v_permlane16_swap_b32_e32 v96, v5
	v_add_f32_e32 v5, v96, v5
	v_cvt_pk_bf16_f32 v6, v6, v7
	v_mov_b32_e32 v7, v5
	s_nop 1
	v_permlane32_swap_b32_e32 v5, v7
	v_add_f32_e32 v12, v5, v7
	v_div_scale_f32 v13, s[6:7], v12, v12, 1.0
	v_rcp_f32_e32 v14, v13
	v_pk_mul_f32 v[4:5], v[66:67], v[4:5] op_sel_hi:[1,0]
	s_nop 0
	v_cvt_pk_bf16_f32 v7, v4, v5
	v_fma_f32 v4, -v13, v14, 1.0
	v_fmac_f32_e32 v14, v4, v14
	v_div_scale_f32 v4, vcc, 1.0, v12, 1.0
	v_mul_f32_e32 v5, v4, v14
	flat_store_dwordx2 v[10:11], v[6:7] offset:96
	v_fma_f32 v6, -v13, v5, v4
	v_fmac_f32_e32 v5, v6, v14
	v_lshlrev_b64 v[6:7], 11, v[90:91]
	v_fma_f32 v4, -v13, v5, v4
	v_lshl_add_u64 v[6:7], s[42:43], 0, v[6:7]
	v_div_fmas_f32 v4, v4, v14, v5
	v_lshl_add_u64 v[6:7], v[6:7], 0, s[44:45]
	v_div_fixup_f32 v4, v4, v12, 1.0
	v_lshl_add_u64 v[6:7], v[6:7], 0, v[8:9]
	v_lshl_add_u64 v[8:9], v[6:7], 0, s[96:97]
	v_pk_mul_f32 v[10:11], v[40:41], v[4:5] op_sel_hi:[1,0]
	v_pk_mul_f32 v[12:13], v[42:43], v[4:5] op_sel_hi:[1,0]
	v_add_co_u32_e32 v6, vcc, s94, v6
	v_cvt_pk_bf16_f32 v10, v10, v11
	v_cvt_pk_bf16_f32 v11, v12, v13
	v_addc_co_u32_e32 v7, vcc, 0, v7, vcc
	flat_store_dwordx2 v[6:7], v[10:11] offset:512
	v_pk_mul_f32 v[6:7], v[36:37], v[4:5] op_sel_hi:[1,0]
	v_pk_mul_f32 v[10:11], v[38:39], v[4:5] op_sel_hi:[1,0]
	v_cvt_pk_bf16_f32 v6, v6, v7
	v_cvt_pk_bf16_f32 v7, v10, v11
	flat_store_dwordx2 v[8:9], v[6:7] offset:32
	v_pk_mul_f32 v[6:7], v[44:45], v[4:5] op_sel_hi:[1,0]
	v_pk_mul_f32 v[10:11], v[46:47], v[4:5] op_sel_hi:[1,0]
	v_cvt_pk_bf16_f32 v6, v6, v7
	v_cvt_pk_bf16_f32 v7, v10, v11
	flat_store_dwordx2 v[8:9], v[6:7] offset:64
	v_pk_mul_f32 v[6:7], v[48:49], v[4:5] op_sel_hi:[1,0]
	v_pk_mul_f32 v[4:5], v[50:51], v[4:5] op_sel_hi:[1,0]
	v_cvt_pk_bf16_f32 v6, v6, v7
	v_cvt_pk_bf16_f32 v7, v4, v5
	flat_store_dwordx2 v[8:9], v[6:7] offset:96
	s_waitcnt lgkmcnt(0)
	s_barrier
	s_and_saveexec_b64 s[6:7], s[4:5]
	s_cbranch_execz .LBB0_3041
	s_cmp_eq_u32 s32, 0
	s_cbranch_scc1 .Lqf8
	s_waitcnt vmcnt(0) lgkmcnt(0)
	ds_write_b32 v177, v253
	s_mov_b32 s32, 0
	s_branch .LBB0_3041
